# Y2: barrier moved inside the QK MFMA stream, loop unrolled x4 with static LDS ring slots, running DMA pointers, per-wave-group code copies, cheaper row-max check
# speedup vs baseline: 1.0121x; 1.0121x over previous
.LBB0_976:
	s_and_b32 s0, s8, 0x3fffffc0
	s_lshl_b32 s0, s0, 2
	s_add_i32 s47, s0, 0
	s_lshl_b32 s90, s75, 6
	v_lshlrev_b32_e32 v21, 1, v19
	v_lshlrev_b32_e32 v19, 4, v19
	s_add_i32 s47, s47, 0x14000
	s_add_i32 s71, s25, -1
	v_and_b32_e32 v19, 0xc0, v19
	s_and_b64 s[0:1], s[88:89], exec
	v_lshl_add_u32 v23, v228, 8, 0
	v_and_b32_e32 v21, 32, v21
	s_cselect_b32 s79, 1, s25
	s_min_i32 s82, s29, s71
	v_add_u32_e32 v19, v23, v19
	v_mov_b32_e32 v48, v3
	v_mov_b32_e32 v49, v3
	s_cmpk_lt_u32 s8, 0x100
	v_add3_u32 v237, v19, v21, v22
	v_mul_u32_u24_e32 v19, 0x300, v228
	s_mov_b64 s[0:1], 0x4000
	v_mov_b32_e32 v34, v3
	v_mov_b32_e32 v35, v3
	v_mov_b32_e32 v36, v3
	v_mov_b32_e32 v37, v3
	v_mov_b32_e32 v38, v3
	v_mov_b32_e32 v39, v3
	v_mov_b32_e32 v40, v3
	v_mov_b32_e32 v41, v3
	v_mov_b32_e32 v42, v3
	v_mov_b32_e32 v43, v3
	v_mov_b32_e32 v44, v3
	v_mov_b32_e32 v45, v3
	v_mov_b32_e32 v46, v3
	v_mov_b32_e32 v47, v3
	v_mov_b32_e32 v142, 0
	v_mov_b64_e32 v[64:65], v[48:49]
	v_mov_b64_e32 v[80:81], v[48:49]
	s_mov_b32 s91, s27
	s_cselect_b64 s[94:95], -1, 0
	s_add_i32 s83, s25, -2
	v_cmp_gt_u32_e64 s[8:9], 32, v233
	v_lshl_add_u32 v235, v229, 2, s47
	v_add3_u32 v238, v23, v19, v20
	v_lshl_add_u64 v[226:227], v[222:223], 0, s[0:1]
	s_mov_b32 s26, 0
	s_mov_b64 s[96:97], -1
	v_mov_b32_e32 v239, 0
	s_movk_i32 s78, 0x6000
	s_mov_b64 s[30:31], 0
	v_mov_b64_e32 v[62:63], v[46:47]
	v_mov_b64_e32 v[60:61], v[44:45]
	v_mov_b64_e32 v[58:59], v[42:43]
	v_mov_b64_e32 v[56:57], v[40:41]
	v_mov_b64_e32 v[54:55], v[38:39]
	v_mov_b64_e32 v[52:53], v[36:37]
	v_mov_b64_e32 v[50:51], v[34:35]
	v_mov_b32_e32 v236, 0
	v_mov_b64_e32 v[78:79], v[46:47]
	v_mov_b64_e32 v[76:77], v[44:45]
	v_mov_b64_e32 v[74:75], v[42:43]
	v_mov_b64_e32 v[72:73], v[40:41]
	v_mov_b64_e32 v[70:71], v[38:39]
	v_mov_b64_e32 v[68:69], v[36:37]
	v_mov_b64_e32 v[66:67], v[34:35]
	v_mov_b32_e32 v143, v142
	v_mov_b32_e32 v144, v142
	v_mov_b32_e32 v145, v142
	v_mov_b32_e32 v146, v142
	v_mov_b32_e32 v147, v142
	v_mov_b32_e32 v148, v142
	v_mov_b32_e32 v149, v142
	v_mov_b32_e32 v150, v142
	v_mov_b32_e32 v151, v142
	v_mov_b32_e32 v152, v142
	v_mov_b32_e32 v153, v142
	v_mov_b32_e32 v154, v142
	v_mov_b32_e32 v155, v142
	v_mov_b32_e32 v156, v142
	v_mov_b32_e32 v157, v142
	v_mov_b32_e32 v158, v142
	v_mov_b32_e32 v159, v142
	v_mov_b32_e32 v160, v142
	v_mov_b32_e32 v161, v142
	v_mov_b32_e32 v162, v142
	v_mov_b32_e32 v163, v142
	v_mov_b32_e32 v164, v142
	v_mov_b32_e32 v165, v142
	v_mov_b32_e32 v166, v142
	v_mov_b32_e32 v167, v142
	v_mov_b32_e32 v168, v142
	v_mov_b32_e32 v169, v142
	v_mov_b32_e32 v170, v142
	v_mov_b32_e32 v171, v142
	v_mov_b32_e32 v172, v142
	v_mov_b32_e32 v173, v142
	s_cmp_eq_u32 s25, 0x41
	s_cbranch_scc1 .LBB0_979
	s_cmp_lt_u32 s24, 4
	s_cbranch_scc1 .Lmy_A_entry
	s_branch .Lmy_B_entry
.Lmy_A_entry:
	s_mov_b32 s30, 0x20000
	s_mov_b32 s31, 0
	s_mov_b32 s12, 0x1000
	s_mov_b32 s13, 0
	s_lshr_b32 s71, s24, 1
	s_lshr_b32 s79, s25, 2
	s_add_i32 s79, s79, -1
	s_barrier
	s_mov_b32 s0, 0x60000
	s_mov_b32 s1, 0
	v_lshl_add_u64 v[24:25], v[16:17], 0, s[0:1]
	s_add_u32 m0, s40, 0x9000
	s_mov_b32 s0, 0x3000
	global_load_lds_dwordx4 v[24:25], off
	v_lshl_add_u64 v[30:31], v[222:223], 0, s[0:1]
	s_add_u32 m0, s43, 0x9000
	s_nop 0
	global_load_lds_dwordx4 v[30:31], off
	s_mov_b32 s0, 0x80000
	s_mov_b32 s1, 0
	v_lshl_add_u64 v[24:25], v[16:17], 0, s[0:1]
	s_mov_b32 s0, 0x60000
	v_lshl_add_u64 v[28:29], v[224:225], 0, s[0:1]
	s_mov_b32 s0, 0x4000
	v_lshl_add_u64 v[30:31], v[222:223], 0, s[0:1]
	s_waitcnt lgkmcnt(0)
	v_mfma_f32_32x32x16_bf16 v[82:97], v[218:221], v[4:7], v[66:81]
	v_mfma_f32_32x32x16_bf16 v[98:113], v[214:217], v[4:7], v[66:81]
	v_mfma_f32_32x32x16_bf16 v[82:97], v[210:213], v[8:11], v[82:97]
	v_mfma_f32_32x32x16_bf16 v[98:113], v[206:209], v[8:11], v[98:113]
	v_mfma_f32_32x32x16_bf16 v[82:97], v[202:205], v[12:15], v[82:97]
	v_mfma_f32_32x32x16_bf16 v[98:113], v[198:201], v[12:15], v[98:113]
	v_mfma_f32_32x32x16_bf16 v[82:97], v[194:197], v[130:133], v[82:97]
	v_mfma_f32_32x32x16_bf16 v[98:113], v[190:193], v[130:133], v[98:113]
	v_mfma_f32_32x32x16_bf16 v[82:97], v[186:189], v[134:137], v[82:97]
	v_mfma_f32_32x32x16_bf16 v[98:113], v[182:185], v[134:137], v[98:113]
	v_mfma_f32_32x32x16_bf16 v[82:97], v[178:181], v[138:141], v[82:97]
	v_mfma_f32_32x32x16_bf16 v[98:113], v[174:177], v[138:141], v[98:113]
	v_add_u32_e32 v2, 0x3000, v238
	ds_read_b128 v[218:221], v2
	ds_read_b128 v[214:217], v2 offset:512
	ds_read_b128 v[210:213], v2 offset:2048
	ds_read_b128 v[206:209], v2 offset:2560
	ds_read_b128 v[202:205], v2 offset:4096
	ds_read_b128 v[198:201], v2 offset:4608
	ds_read_b128 v[194:197], v2 offset:6144
	ds_read_b128 v[190:193], v2 offset:6656
	ds_read_b128 v[186:189], v2 offset:8192
	ds_read_b128 v[182:185], v2 offset:8704
	ds_read_b128 v[178:181], v2 offset:10240
	ds_read_b128 v[174:177], v2 offset:10752
	s_nop 7
	v_max3_f32 v19, v82, v83, v84
	v_max3_f32 v26, v85, v86, v87
	v_max3_f32 v19, v19, v88, v89
	v_max3_f32 v26, v26, v90, v91
	v_max3_f32 v19, v19, v92, v93
	v_max3_f32 v26, v26, v94, v95
	v_max3_f32 v19, v19, v96, v97
	v_max3_f32 v26, v26, v98, v99
	v_max3_f32 v19, v19, v100, v101
	v_max3_f32 v26, v26, v102, v103
	v_max3_f32 v19, v19, v104, v105
	v_max3_f32 v26, v26, v106, v107
	v_max3_f32 v19, v19, v108, v109
	v_max3_f32 v26, v26, v110, v111
	v_max3_f32 v19, v19, v112, v113
	v_max_f32_e32 v19, v19, v26
	v_mov_b32_e32 v26, v19
	s_nop 1
	v_permlane32_swap_b32_e32 v19, v26
	v_max_f32_e32 v19, v19, v26
	v_max_f32_e32 v19, v19, v19
	v_mov_b32_e32 v239, v19
	v_xor_b32_e32 v66, 0x80000000, v19
	v_mov_b32_e32 v67, v66
	v_mov_b32_e32 v68, v66
	v_mov_b32_e32 v69, v66
	v_mov_b32_e32 v70, v66
	v_mov_b32_e32 v71, v66
	v_mov_b32_e32 v72, v66
	v_mov_b32_e32 v73, v66
	v_mov_b32_e32 v74, v66
	v_mov_b32_e32 v75, v66
	v_mov_b32_e32 v76, v66
	v_mov_b32_e32 v77, v66
	v_mov_b32_e32 v78, v66
	v_mov_b32_e32 v79, v66
	v_mov_b32_e32 v80, v66
	v_mov_b32_e32 v81, v66
	v_sub_f32_e32 v82, v82, v19
	v_sub_f32_e32 v83, v83, v19
	v_sub_f32_e32 v84, v84, v19
	v_sub_f32_e32 v85, v85, v19
	v_sub_f32_e32 v86, v86, v19
	v_sub_f32_e32 v87, v87, v19
	v_sub_f32_e32 v88, v88, v19
	v_sub_f32_e32 v89, v89, v19
	v_sub_f32_e32 v90, v90, v19
	v_sub_f32_e32 v91, v91, v19
	v_sub_f32_e32 v92, v92, v19
	v_sub_f32_e32 v93, v93, v19
	v_sub_f32_e32 v94, v94, v19
	v_sub_f32_e32 v95, v95, v19
	v_sub_f32_e32 v96, v96, v19
	v_sub_f32_e32 v97, v97, v19
	v_sub_f32_e32 v98, v98, v19
	v_sub_f32_e32 v99, v99, v19
	v_sub_f32_e32 v100, v100, v19
	v_sub_f32_e32 v101, v101, v19
	v_sub_f32_e32 v102, v102, v19
	v_sub_f32_e32 v103, v103, v19
	v_sub_f32_e32 v104, v104, v19
	v_sub_f32_e32 v105, v105, v19
	v_sub_f32_e32 v106, v106, v19
	v_sub_f32_e32 v107, v107, v19
	v_sub_f32_e32 v108, v108, v19
	v_sub_f32_e32 v109, v109, v19
	v_sub_f32_e32 v110, v110, v19
	v_sub_f32_e32 v111, v111, v19
	v_sub_f32_e32 v112, v112, v19
	v_sub_f32_e32 v113, v113, v19
	s_cmp_lt_i32 s79, 1
	s_cbranch_scc1 .Lmy_A_tail
.Lmy_A_loop:
	s_waitcnt lgkmcnt(0)
	v_mov_b32_e32 v2, v237
	v_mfma_f32_32x32x16_bf16 v[142:157], v[218:221], v[4:7], v[66:81]
	v_exp_f32_e32 v82, v82
	v_exp_f32_e32 v83, v83
	v_exp_f32_e32 v84, v84
	v_add_f32_e32 v27, v82, v83
	v_exp_f32_e32 v85, v85
	ds_read_b64_tr_b16 v[114:115], v2 offset:49152
	ds_read_b64_tr_b16 v[116:117], v2 offset:49664
	ds_read_b64_tr_b16 v[118:119], v2 offset:50176
	ds_read_b64_tr_b16 v[120:121], v2 offset:50688
	v_mfma_f32_32x32x16_bf16 v[158:173], v[214:217], v[4:7], v[66:81]
	v_exp_f32_e32 v86, v86
	v_add_f32_e32 v27, v27, v84
	v_exp_f32_e32 v87, v87
	v_add_f32_e32 v27, v27, v85
	v_exp_f32_e32 v88, v88
	ds_read_b64_tr_b16 v[122:123], v2 offset:51200
	ds_read_b64_tr_b16 v[124:125], v2 offset:51712
	ds_read_b64_tr_b16 v[126:127], v2 offset:52224
	ds_read_b64_tr_b16 v[128:129], v2 offset:52736
	v_mfma_f32_32x32x16_bf16 v[142:157], v[210:213], v[8:11], v[142:157]
	v_add_f32_e32 v27, v27, v86
	v_exp_f32_e32 v89, v89
	v_add_f32_e32 v27, v27, v87
	v_add_f32_e32 v27, v27, v88
	v_add_f32_e32 v27, v27, v89
	ds_read_b64_tr_b16 v[240:241], v2 offset:53248
	ds_read_b64_tr_b16 v[242:243], v2 offset:53760
	ds_read_b64_tr_b16 v[244:245], v2 offset:54272
	ds_read_b64_tr_b16 v[246:247], v2 offset:54784
	v_mfma_f32_32x32x16_bf16 v[158:173], v[206:209], v[8:11], v[158:173]
	v_cvt_pk_bf16_f32 v82, v82, v83
	v_cvt_pk_bf16_f32 v83, v84, v85
	v_cvt_pk_bf16_f32 v84, v86, v87
	v_cvt_pk_bf16_f32 v85, v88, v89
	ds_read_b64_tr_b16 v[248:249], v2 offset:55296
	ds_read_b64_tr_b16 v[250:251], v2 offset:55808
	ds_read_b64_tr_b16 v[20:21], v2 offset:56320
	ds_read_b64_tr_b16 v[22:23], v2 offset:56832
	v_mfma_f32_32x32x16_bf16 v[142:157], v[202:205], v[12:15], v[142:157]
	v_exp_f32_e32 v90, v90
	v_exp_f32_e32 v91, v91
	v_exp_f32_e32 v92, v92
	v_add_f32_e32 v27, v27, v90
	v_exp_f32_e32 v93, v93
	v_mfma_f32_32x32x16_bf16 v[158:173], v[198:201], v[12:15], v[158:173]
	v_add_f32_e32 v27, v27, v91
	v_exp_f32_e32 v94, v94
	v_add_f32_e32 v27, v27, v92
	v_exp_f32_e32 v95, v95
	v_add_f32_e32 v27, v27, v93
	s_waitcnt vmcnt(3)
	s_barrier
	v_mfma_f32_32x32x16_bf16 v[142:157], v[194:197], v[130:133], v[142:157]
	s_add_u32 m0, s57, 0x6000
	v_exp_f32_e32 v96, v96
	v_add_f32_e32 v27, v27, v94
	global_load_lds_dwordx4 v[28:29], off
	v_lshl_add_u64 v[28:29], v[28:29], 0, s[30:31]
	v_exp_f32_e32 v97, v97
	v_add_f32_e32 v27, v27, v95
	v_add_f32_e32 v27, v27, v96
	v_mfma_f32_32x32x16_bf16 v[158:173], v[190:193], v[130:133], v[158:173]
	s_add_u32 m0, s40, 0x0
	v_add_f32_e32 v27, v27, v97
	v_cvt_pk_bf16_f32 v90, v90, v91
	global_load_lds_dwordx4 v[24:25], off
	v_lshl_add_u64 v[24:25], v[24:25], 0, s[30:31]
	v_cvt_pk_bf16_f32 v91, v92, v93
	v_cvt_pk_bf16_f32 v92, v94, v95
	v_cvt_pk_bf16_f32 v93, v96, v97
	v_mfma_f32_32x32x16_bf16 v[142:157], v[186:189], v[134:137], v[142:157]
	s_add_u32 m0, s43, 0x0
	v_exp_f32_e32 v98, v98
	v_exp_f32_e32 v99, v99
	global_load_lds_dwordx4 v[30:31], off
	v_lshl_add_u64 v[30:31], v[30:31], 0, s[12:13]
	v_exp_f32_e32 v100, v100
	v_add_f32_e32 v27, v27, v98
	v_exp_f32_e32 v101, v101
	v_mfma_f32_32x32x16_bf16 v[158:173], v[182:185], v[134:137], v[158:173]
	v_add_f32_e32 v27, v27, v99
	v_exp_f32_e32 v102, v102
	v_add_f32_e32 v27, v27, v100
	v_exp_f32_e32 v103, v103
	v_add_f32_e32 v27, v27, v101
	v_mfma_f32_32x32x16_bf16 v[142:157], v[178:181], v[138:141], v[142:157]
	v_exp_f32_e32 v104, v104
	v_add_f32_e32 v27, v27, v102
	v_exp_f32_e32 v105, v105
	v_add_f32_e32 v27, v27, v103
	v_add_f32_e32 v27, v27, v104
	v_mfma_f32_32x32x16_bf16 v[158:173], v[174:177], v[138:141], v[158:173]
	v_add_f32_e32 v27, v27, v105
	v_cvt_pk_bf16_f32 v98, v98, v99
	v_cvt_pk_bf16_f32 v99, v100, v101
	v_cvt_pk_bf16_f32 v100, v102, v103
	v_cvt_pk_bf16_f32 v101, v104, v105
	s_waitcnt lgkmcnt(0)
	v_add_u32_e32 v2, 0x6000, v238
	v_mfma_f32_32x32x16_bf16 v[34:49], v[82:85], v[114:117], v[34:49]
	v_exp_f32_e32 v106, v106
	v_exp_f32_e32 v107, v107
	v_exp_f32_e32 v108, v108
	v_add_f32_e32 v27, v27, v106
	v_exp_f32_e32 v109, v109
	v_add_f32_e32 v27, v27, v107
	v_exp_f32_e32 v110, v110
	v_add_f32_e32 v27, v27, v108
	v_exp_f32_e32 v111, v111
	v_add_f32_e32 v27, v27, v109
	ds_read_b128 v[218:221], v2
	ds_read_b128 v[214:217], v2 offset:512
	ds_read_b128 v[210:213], v2 offset:2048
	v_mfma_f32_32x32x16_bf16 v[50:65], v[82:85], v[240:243], v[50:65]
	v_exp_f32_e32 v112, v112
	v_add_f32_e32 v27, v27, v110
	v_exp_f32_e32 v113, v113
	v_add_f32_e32 v27, v27, v111
	v_add_f32_e32 v27, v27, v112
	v_add_f32_e32 v27, v27, v113
	v_cvt_pk_bf16_f32 v106, v106, v107
	v_cvt_pk_bf16_f32 v107, v108, v109
	v_cvt_pk_bf16_f32 v108, v110, v111
	v_cvt_pk_bf16_f32 v109, v112, v113
	v_add_f32_e32 v236, v236, v27
	ds_read_b128 v[206:209], v2 offset:2560
	ds_read_b128 v[202:205], v2 offset:4096
	ds_read_b128 v[198:201], v2 offset:4608
	v_mfma_f32_32x32x16_bf16 v[34:49], v[90:93], v[118:121], v[34:49]
	ds_read_b128 v[194:197], v2 offset:6144
	ds_read_b128 v[190:193], v2 offset:6656
	ds_read_b128 v[186:189], v2 offset:8192
	v_max3_f32 v19, v142, v143, v144
	v_max3_f32 v26, v145, v146, v147
	v_max3_f32 v19, v19, v148, v149
	v_max3_f32 v26, v26, v150, v151
	v_max3_f32 v19, v19, v152, v153
	v_mfma_f32_32x32x16_bf16 v[50:65], v[90:93], v[244:247], v[50:65]
	ds_read_b128 v[182:185], v2 offset:8704
	ds_read_b128 v[178:181], v2 offset:10240
	ds_read_b128 v[174:177], v2 offset:10752
	v_max3_f32 v26, v26, v154, v155
	v_max3_f32 v19, v19, v156, v157
	v_max3_f32 v26, v26, v158, v159
	v_max3_f32 v19, v19, v160, v161
	v_max3_f32 v26, v26, v162, v163
	v_mfma_f32_32x32x16_bf16 v[34:49], v[98:101], v[122:125], v[34:49]
	v_max3_f32 v19, v19, v164, v165
	v_max3_f32 v26, v26, v166, v167
	v_max3_f32 v19, v19, v168, v169
	v_max3_f32 v26, v26, v170, v171
	v_mfma_f32_32x32x16_bf16 v[50:65], v[98:101], v[248:251], v[50:65]
	v_max3_f32 v19, v19, v172, v173
	v_max_f32_e32 v19, v19, v26
	v_mfma_f32_32x32x16_bf16 v[34:49], v[106:109], v[126:129], v[34:49]
	v_mfma_f32_32x32x16_bf16 v[50:65], v[106:109], v[20:23], v[50:65]
	v_cmp_lt_f32_e32 vcc, s41, v19
	s_cbranch_vccz .Lmy_nors_1
	s_nop 15
	s_nop 15
	v_mov_b32_e32 v26, v19
	s_nop 1
	v_permlane32_swap_b32_e32 v19, v26
	v_max_f32_e32 v19, v19, v26
	v_max_f32_e32 v19, v19, v19
	v_max_f32_e32 v90, 0, v19
	v_exp_f32_e64 v91, -v90
	v_add_f32_e32 v239, v239, v90
	v_xor_b32_e32 v66, 0x80000000, v239
	v_mov_b32_e32 v67, v66
	v_mov_b32_e32 v68, v66
	v_mov_b32_e32 v69, v66
	v_mov_b32_e32 v70, v66
	v_mov_b32_e32 v71, v66
	v_mov_b32_e32 v72, v66
	v_mov_b32_e32 v73, v66
	v_mov_b32_e32 v74, v66
	v_mov_b32_e32 v75, v66
	v_mov_b32_e32 v76, v66
	v_mov_b32_e32 v77, v66
	v_mov_b32_e32 v78, v66
	v_mov_b32_e32 v79, v66
	v_mov_b32_e32 v80, v66
	v_mov_b32_e32 v81, v66
	v_sub_f32_e32 v142, v142, v90
	v_sub_f32_e32 v143, v143, v90
	v_sub_f32_e32 v144, v144, v90
	v_sub_f32_e32 v145, v145, v90
	v_sub_f32_e32 v146, v146, v90
	v_sub_f32_e32 v147, v147, v90
	v_sub_f32_e32 v148, v148, v90
	v_sub_f32_e32 v149, v149, v90
	v_sub_f32_e32 v150, v150, v90
	v_sub_f32_e32 v151, v151, v90
	v_sub_f32_e32 v152, v152, v90
	v_sub_f32_e32 v153, v153, v90
	v_sub_f32_e32 v154, v154, v90
	v_sub_f32_e32 v155, v155, v90
	v_sub_f32_e32 v156, v156, v90
	v_sub_f32_e32 v157, v157, v90
	v_sub_f32_e32 v158, v158, v90
	v_sub_f32_e32 v159, v159, v90
	v_sub_f32_e32 v160, v160, v90
	v_sub_f32_e32 v161, v161, v90
	v_sub_f32_e32 v162, v162, v90
	v_sub_f32_e32 v163, v163, v90
	v_sub_f32_e32 v164, v164, v90
	v_sub_f32_e32 v165, v165, v90
	v_sub_f32_e32 v166, v166, v90
	v_sub_f32_e32 v167, v167, v90
	v_sub_f32_e32 v168, v168, v90
	v_sub_f32_e32 v169, v169, v90
	v_sub_f32_e32 v170, v170, v90
	v_sub_f32_e32 v171, v171, v90
	v_sub_f32_e32 v172, v172, v90
	v_sub_f32_e32 v173, v173, v90
	v_mul_f32_e32 v236, v236, v91
	s_mov_b64 s[96:97], exec
	s_and_b64 exec, exec, s[8:9]
	ds_write_b32 v235, v91
	s_mov_b64 exec, s[96:97]
	v_lshl_add_u32 v2, v228, 4, s47
	ds_read_b128 v[94:97], v2 offset:0
	s_waitcnt lgkmcnt(0)
	v_mul_f32_e32 v34, v34, v94
	v_mul_f32_e32 v50, v50, v94
	v_mul_f32_e32 v35, v35, v95
	v_mul_f32_e32 v51, v51, v95
	v_mul_f32_e32 v36, v36, v96
	v_mul_f32_e32 v52, v52, v96
	v_mul_f32_e32 v37, v37, v97
	v_mul_f32_e32 v53, v53, v97
	ds_read_b128 v[94:97], v2 offset:32
	s_waitcnt lgkmcnt(0)
	v_mul_f32_e32 v38, v38, v94
	v_mul_f32_e32 v54, v54, v94
	v_mul_f32_e32 v39, v39, v95
	v_mul_f32_e32 v55, v55, v95
	v_mul_f32_e32 v40, v40, v96
	v_mul_f32_e32 v56, v56, v96
	v_mul_f32_e32 v41, v41, v97
	v_mul_f32_e32 v57, v57, v97
	ds_read_b128 v[94:97], v2 offset:64
	s_waitcnt lgkmcnt(0)
	v_mul_f32_e32 v42, v42, v94
	v_mul_f32_e32 v58, v58, v94
	v_mul_f32_e32 v43, v43, v95
	v_mul_f32_e32 v59, v59, v95
	v_mul_f32_e32 v44, v44, v96
	v_mul_f32_e32 v60, v60, v96
	v_mul_f32_e32 v45, v45, v97
	v_mul_f32_e32 v61, v61, v97
	ds_read_b128 v[94:97], v2 offset:96
	s_waitcnt lgkmcnt(0)
	v_mul_f32_e32 v46, v46, v94
	v_mul_f32_e32 v62, v62, v94
	v_mul_f32_e32 v47, v47, v95
	v_mul_f32_e32 v63, v63, v95
	v_mul_f32_e32 v48, v48, v96
	v_mul_f32_e32 v64, v64, v96
	v_mul_f32_e32 v49, v49, v97
	v_mul_f32_e32 v65, v65, v97
.Lmy_nors_1:
	s_waitcnt lgkmcnt(0)
	v_add_u32_e32 v2, 0x2000, v237
	v_mfma_f32_32x32x16_bf16 v[82:97], v[218:221], v[4:7], v[66:81]
	v_exp_f32_e32 v142, v142
	v_exp_f32_e32 v143, v143
	v_exp_f32_e32 v144, v144
	v_add_f32_e32 v27, v142, v143
	v_exp_f32_e32 v145, v145
	ds_read_b64_tr_b16 v[114:115], v2 offset:49152
	ds_read_b64_tr_b16 v[116:117], v2 offset:49664
	ds_read_b64_tr_b16 v[118:119], v2 offset:50176
	ds_read_b64_tr_b16 v[120:121], v2 offset:50688
	v_mfma_f32_32x32x16_bf16 v[98:113], v[214:217], v[4:7], v[66:81]
	v_exp_f32_e32 v146, v146
	v_add_f32_e32 v27, v27, v144
	v_exp_f32_e32 v147, v147
	v_add_f32_e32 v27, v27, v145
	v_exp_f32_e32 v148, v148
	ds_read_b64_tr_b16 v[122:123], v2 offset:51200
	ds_read_b64_tr_b16 v[124:125], v2 offset:51712
	ds_read_b64_tr_b16 v[126:127], v2 offset:52224
	ds_read_b64_tr_b16 v[128:129], v2 offset:52736
	v_mfma_f32_32x32x16_bf16 v[82:97], v[210:213], v[8:11], v[82:97]
	v_add_f32_e32 v27, v27, v146
	v_exp_f32_e32 v149, v149
	v_add_f32_e32 v27, v27, v147
	v_add_f32_e32 v27, v27, v148
	v_add_f32_e32 v27, v27, v149
	ds_read_b64_tr_b16 v[240:241], v2 offset:53248
	ds_read_b64_tr_b16 v[242:243], v2 offset:53760
	ds_read_b64_tr_b16 v[244:245], v2 offset:54272
	ds_read_b64_tr_b16 v[246:247], v2 offset:54784
	v_mfma_f32_32x32x16_bf16 v[98:113], v[206:209], v[8:11], v[98:113]
	v_cvt_pk_bf16_f32 v142, v142, v143
	v_cvt_pk_bf16_f32 v143, v144, v145
	v_cvt_pk_bf16_f32 v144, v146, v147
	v_cvt_pk_bf16_f32 v145, v148, v149
	ds_read_b64_tr_b16 v[248:249], v2 offset:55296
	ds_read_b64_tr_b16 v[250:251], v2 offset:55808
	ds_read_b64_tr_b16 v[20:21], v2 offset:56320
	ds_read_b64_tr_b16 v[22:23], v2 offset:56832
	v_mfma_f32_32x32x16_bf16 v[82:97], v[202:205], v[12:15], v[82:97]
	v_exp_f32_e32 v150, v150
	v_exp_f32_e32 v151, v151
	v_exp_f32_e32 v152, v152
	v_add_f32_e32 v27, v27, v150
	v_exp_f32_e32 v153, v153
	v_mfma_f32_32x32x16_bf16 v[98:113], v[198:201], v[12:15], v[98:113]
	v_add_f32_e32 v27, v27, v151
	v_exp_f32_e32 v154, v154
	v_add_f32_e32 v27, v27, v152
	v_exp_f32_e32 v155, v155
	v_add_f32_e32 v27, v27, v153
	s_waitcnt vmcnt(3)
	s_barrier
	v_mfma_f32_32x32x16_bf16 v[82:97], v[194:197], v[130:133], v[82:97]
	s_add_u32 m0, s57, 0x0
	v_exp_f32_e32 v156, v156
	v_add_f32_e32 v27, v27, v154
	global_load_lds_dwordx4 v[28:29], off
	v_lshl_add_u64 v[28:29], v[28:29], 0, s[30:31]
	v_exp_f32_e32 v157, v157
	v_add_f32_e32 v27, v27, v155
	v_add_f32_e32 v27, v27, v156
	v_mfma_f32_32x32x16_bf16 v[98:113], v[190:193], v[130:133], v[98:113]
	s_add_u32 m0, s40, 0x3000
	v_add_f32_e32 v27, v27, v157
	v_cvt_pk_bf16_f32 v150, v150, v151
	global_load_lds_dwordx4 v[24:25], off
	v_lshl_add_u64 v[24:25], v[24:25], 0, s[30:31]
	v_cvt_pk_bf16_f32 v151, v152, v153
	v_cvt_pk_bf16_f32 v152, v154, v155
	v_cvt_pk_bf16_f32 v153, v156, v157
	v_mfma_f32_32x32x16_bf16 v[82:97], v[186:189], v[134:137], v[82:97]
	s_add_u32 m0, s43, 0x3000
	v_exp_f32_e32 v158, v158
	v_exp_f32_e32 v159, v159
	global_load_lds_dwordx4 v[30:31], off
	v_lshl_add_u64 v[30:31], v[30:31], 0, s[12:13]
	v_exp_f32_e32 v160, v160
	v_add_f32_e32 v27, v27, v158
	v_exp_f32_e32 v161, v161
	v_mfma_f32_32x32x16_bf16 v[98:113], v[182:185], v[134:137], v[98:113]
	v_add_f32_e32 v27, v27, v159
	v_exp_f32_e32 v162, v162
	v_add_f32_e32 v27, v27, v160
	v_exp_f32_e32 v163, v163
	v_add_f32_e32 v27, v27, v161
	v_mfma_f32_32x32x16_bf16 v[82:97], v[178:181], v[138:141], v[82:97]
	v_exp_f32_e32 v164, v164
	v_add_f32_e32 v27, v27, v162
	v_exp_f32_e32 v165, v165
	v_add_f32_e32 v27, v27, v163
	v_add_f32_e32 v27, v27, v164
	v_mfma_f32_32x32x16_bf16 v[98:113], v[174:177], v[138:141], v[98:113]
	v_add_f32_e32 v27, v27, v165
	v_cvt_pk_bf16_f32 v158, v158, v159
	v_cvt_pk_bf16_f32 v159, v160, v161
	v_cvt_pk_bf16_f32 v160, v162, v163
	v_cvt_pk_bf16_f32 v161, v164, v165
	s_waitcnt lgkmcnt(0)
	v_add_u32_e32 v2, 0x9000, v238
	v_mfma_f32_32x32x16_bf16 v[34:49], v[142:145], v[114:117], v[34:49]
	v_exp_f32_e32 v166, v166
	v_exp_f32_e32 v167, v167
	v_exp_f32_e32 v168, v168
	v_add_f32_e32 v27, v27, v166
	v_exp_f32_e32 v169, v169
	v_add_f32_e32 v27, v27, v167
	v_exp_f32_e32 v170, v170
	v_add_f32_e32 v27, v27, v168
	v_exp_f32_e32 v171, v171
	v_add_f32_e32 v27, v27, v169
	ds_read_b128 v[218:221], v2
	ds_read_b128 v[214:217], v2 offset:512
	ds_read_b128 v[210:213], v2 offset:2048
	v_mfma_f32_32x32x16_bf16 v[50:65], v[142:145], v[240:243], v[50:65]
	v_exp_f32_e32 v172, v172
	v_add_f32_e32 v27, v27, v170
	v_exp_f32_e32 v173, v173
	v_add_f32_e32 v27, v27, v171
	v_add_f32_e32 v27, v27, v172
	v_add_f32_e32 v27, v27, v173
	v_cvt_pk_bf16_f32 v166, v166, v167
	v_cvt_pk_bf16_f32 v167, v168, v169
	v_cvt_pk_bf16_f32 v168, v170, v171
	v_cvt_pk_bf16_f32 v169, v172, v173
	v_add_f32_e32 v236, v236, v27
	ds_read_b128 v[206:209], v2 offset:2560
	ds_read_b128 v[202:205], v2 offset:4096
	ds_read_b128 v[198:201], v2 offset:4608
	v_mfma_f32_32x32x16_bf16 v[34:49], v[150:153], v[118:121], v[34:49]
	ds_read_b128 v[194:197], v2 offset:6144
	ds_read_b128 v[190:193], v2 offset:6656
	ds_read_b128 v[186:189], v2 offset:8192
	v_max3_f32 v19, v82, v83, v84
	v_max3_f32 v26, v85, v86, v87
	v_max3_f32 v19, v19, v88, v89
	v_max3_f32 v26, v26, v90, v91
	v_max3_f32 v19, v19, v92, v93
	v_mfma_f32_32x32x16_bf16 v[50:65], v[150:153], v[244:247], v[50:65]
	ds_read_b128 v[182:185], v2 offset:8704
	ds_read_b128 v[178:181], v2 offset:10240
	ds_read_b128 v[174:177], v2 offset:10752
	v_max3_f32 v26, v26, v94, v95
	v_max3_f32 v19, v19, v96, v97
	v_max3_f32 v26, v26, v98, v99
	v_max3_f32 v19, v19, v100, v101
	v_max3_f32 v26, v26, v102, v103
	v_mfma_f32_32x32x16_bf16 v[34:49], v[158:161], v[122:125], v[34:49]
	v_max3_f32 v19, v19, v104, v105
	v_max3_f32 v26, v26, v106, v107
	v_max3_f32 v19, v19, v108, v109
	v_max3_f32 v26, v26, v110, v111
	v_mfma_f32_32x32x16_bf16 v[50:65], v[158:161], v[248:251], v[50:65]
	v_max3_f32 v19, v19, v112, v113
	v_max_f32_e32 v19, v19, v26
	v_mfma_f32_32x32x16_bf16 v[34:49], v[166:169], v[126:129], v[34:49]
	v_mfma_f32_32x32x16_bf16 v[50:65], v[166:169], v[20:23], v[50:65]
	v_cmp_lt_f32_e32 vcc, s41, v19
	s_cbranch_vccz .Lmy_nors_2
	s_nop 15
	s_nop 15
	v_mov_b32_e32 v26, v19
	s_nop 1
	v_permlane32_swap_b32_e32 v19, v26
	v_max_f32_e32 v19, v19, v26
	v_max_f32_e32 v19, v19, v19
	v_max_f32_e32 v150, 0, v19
	v_exp_f32_e64 v151, -v150
	v_add_f32_e32 v239, v239, v150
	v_xor_b32_e32 v66, 0x80000000, v239
	v_mov_b32_e32 v67, v66
	v_mov_b32_e32 v68, v66
	v_mov_b32_e32 v69, v66
	v_mov_b32_e32 v70, v66
	v_mov_b32_e32 v71, v66
	v_mov_b32_e32 v72, v66
	v_mov_b32_e32 v73, v66
	v_mov_b32_e32 v74, v66
	v_mov_b32_e32 v75, v66
	v_mov_b32_e32 v76, v66
	v_mov_b32_e32 v77, v66
	v_mov_b32_e32 v78, v66
	v_mov_b32_e32 v79, v66
	v_mov_b32_e32 v80, v66
	v_mov_b32_e32 v81, v66
	v_sub_f32_e32 v82, v82, v150
	v_sub_f32_e32 v83, v83, v150
	v_sub_f32_e32 v84, v84, v150
	v_sub_f32_e32 v85, v85, v150
	v_sub_f32_e32 v86, v86, v150
	v_sub_f32_e32 v87, v87, v150
	v_sub_f32_e32 v88, v88, v150
	v_sub_f32_e32 v89, v89, v150
	v_sub_f32_e32 v90, v90, v150
	v_sub_f32_e32 v91, v91, v150
	v_sub_f32_e32 v92, v92, v150
	v_sub_f32_e32 v93, v93, v150
	v_sub_f32_e32 v94, v94, v150
	v_sub_f32_e32 v95, v95, v150
	v_sub_f32_e32 v96, v96, v150
	v_sub_f32_e32 v97, v97, v150
	v_sub_f32_e32 v98, v98, v150
	v_sub_f32_e32 v99, v99, v150
	v_sub_f32_e32 v100, v100, v150
	v_sub_f32_e32 v101, v101, v150
	v_sub_f32_e32 v102, v102, v150
	v_sub_f32_e32 v103, v103, v150
	v_sub_f32_e32 v104, v104, v150
	v_sub_f32_e32 v105, v105, v150
	v_sub_f32_e32 v106, v106, v150
	v_sub_f32_e32 v107, v107, v150
	v_sub_f32_e32 v108, v108, v150
	v_sub_f32_e32 v109, v109, v150
	v_sub_f32_e32 v110, v110, v150
	v_sub_f32_e32 v111, v111, v150
	v_sub_f32_e32 v112, v112, v150
	v_sub_f32_e32 v113, v113, v150
	v_mul_f32_e32 v236, v236, v151
	s_mov_b64 s[96:97], exec
	s_and_b64 exec, exec, s[8:9]
	ds_write_b32 v235, v151
	s_mov_b64 exec, s[96:97]
	v_lshl_add_u32 v2, v228, 4, s47
	ds_read_b128 v[154:157], v2 offset:0
	s_waitcnt lgkmcnt(0)
	v_mul_f32_e32 v34, v34, v154
	v_mul_f32_e32 v50, v50, v154
	v_mul_f32_e32 v35, v35, v155
	v_mul_f32_e32 v51, v51, v155
	v_mul_f32_e32 v36, v36, v156
	v_mul_f32_e32 v52, v52, v156
	v_mul_f32_e32 v37, v37, v157
	v_mul_f32_e32 v53, v53, v157
	ds_read_b128 v[154:157], v2 offset:32
	s_waitcnt lgkmcnt(0)
	v_mul_f32_e32 v38, v38, v154
	v_mul_f32_e32 v54, v54, v154
	v_mul_f32_e32 v39, v39, v155
	v_mul_f32_e32 v55, v55, v155
	v_mul_f32_e32 v40, v40, v156
	v_mul_f32_e32 v56, v56, v156
	v_mul_f32_e32 v41, v41, v157
	v_mul_f32_e32 v57, v57, v157
	ds_read_b128 v[154:157], v2 offset:64
	s_waitcnt lgkmcnt(0)
	v_mul_f32_e32 v42, v42, v154
	v_mul_f32_e32 v58, v58, v154
	v_mul_f32_e32 v43, v43, v155
	v_mul_f32_e32 v59, v59, v155
	v_mul_f32_e32 v44, v44, v156
	v_mul_f32_e32 v60, v60, v156
	v_mul_f32_e32 v45, v45, v157
	v_mul_f32_e32 v61, v61, v157
	ds_read_b128 v[154:157], v2 offset:96
	s_waitcnt lgkmcnt(0)
	v_mul_f32_e32 v46, v46, v154
	v_mul_f32_e32 v62, v62, v154
	v_mul_f32_e32 v47, v47, v155
	v_mul_f32_e32 v63, v63, v155
	v_mul_f32_e32 v48, v48, v156
	v_mul_f32_e32 v64, v64, v156
	v_mul_f32_e32 v49, v49, v157
	v_mul_f32_e32 v65, v65, v157
.Lmy_nors_2:
	s_waitcnt lgkmcnt(0)
	v_add_u32_e32 v2, 0x4000, v237
	v_mfma_f32_32x32x16_bf16 v[142:157], v[218:221], v[4:7], v[66:81]
	v_exp_f32_e32 v82, v82
	v_exp_f32_e32 v83, v83
	v_exp_f32_e32 v84, v84
	v_add_f32_e32 v27, v82, v83
	v_exp_f32_e32 v85, v85
	ds_read_b64_tr_b16 v[114:115], v2 offset:49152
	ds_read_b64_tr_b16 v[116:117], v2 offset:49664
	ds_read_b64_tr_b16 v[118:119], v2 offset:50176
	ds_read_b64_tr_b16 v[120:121], v2 offset:50688
	v_mfma_f32_32x32x16_bf16 v[158:173], v[214:217], v[4:7], v[66:81]
	v_exp_f32_e32 v86, v86
	v_add_f32_e32 v27, v27, v84
	v_exp_f32_e32 v87, v87
	v_add_f32_e32 v27, v27, v85
	v_exp_f32_e32 v88, v88
	ds_read_b64_tr_b16 v[122:123], v2 offset:51200
	ds_read_b64_tr_b16 v[124:125], v2 offset:51712
	ds_read_b64_tr_b16 v[126:127], v2 offset:52224
	ds_read_b64_tr_b16 v[128:129], v2 offset:52736
	v_mfma_f32_32x32x16_bf16 v[142:157], v[210:213], v[8:11], v[142:157]
	v_add_f32_e32 v27, v27, v86
	v_exp_f32_e32 v89, v89
	v_add_f32_e32 v27, v27, v87
	v_add_f32_e32 v27, v27, v88
	v_add_f32_e32 v27, v27, v89
	ds_read_b64_tr_b16 v[240:241], v2 offset:53248
	ds_read_b64_tr_b16 v[242:243], v2 offset:53760
	ds_read_b64_tr_b16 v[244:245], v2 offset:54272
	ds_read_b64_tr_b16 v[246:247], v2 offset:54784
	v_mfma_f32_32x32x16_bf16 v[158:173], v[206:209], v[8:11], v[158:173]
	v_cvt_pk_bf16_f32 v82, v82, v83
	v_cvt_pk_bf16_f32 v83, v84, v85
	v_cvt_pk_bf16_f32 v84, v86, v87
	v_cvt_pk_bf16_f32 v85, v88, v89
	ds_read_b64_tr_b16 v[248:249], v2 offset:55296
	ds_read_b64_tr_b16 v[250:251], v2 offset:55808
	ds_read_b64_tr_b16 v[20:21], v2 offset:56320
	ds_read_b64_tr_b16 v[22:23], v2 offset:56832
	v_mfma_f32_32x32x16_bf16 v[142:157], v[202:205], v[12:15], v[142:157]
	v_exp_f32_e32 v90, v90
	v_exp_f32_e32 v91, v91
	v_exp_f32_e32 v92, v92
	v_add_f32_e32 v27, v27, v90
	v_exp_f32_e32 v93, v93
	v_mfma_f32_32x32x16_bf16 v[158:173], v[198:201], v[12:15], v[158:173]
	v_add_f32_e32 v27, v27, v91
	v_exp_f32_e32 v94, v94
	v_add_f32_e32 v27, v27, v92
	v_exp_f32_e32 v95, v95
	v_add_f32_e32 v27, v27, v93
	s_waitcnt vmcnt(3)
	s_barrier
	v_mfma_f32_32x32x16_bf16 v[142:157], v[194:197], v[130:133], v[142:157]
	s_add_u32 m0, s57, 0x2000
	v_exp_f32_e32 v96, v96
	v_add_f32_e32 v27, v27, v94
	global_load_lds_dwordx4 v[28:29], off
	v_lshl_add_u64 v[28:29], v[28:29], 0, s[30:31]
	v_exp_f32_e32 v97, v97
	v_add_f32_e32 v27, v27, v95
	v_add_f32_e32 v27, v27, v96
	v_mfma_f32_32x32x16_bf16 v[158:173], v[190:193], v[130:133], v[158:173]
	s_add_u32 m0, s40, 0x6000
	v_add_f32_e32 v27, v27, v97
	v_cvt_pk_bf16_f32 v90, v90, v91
	global_load_lds_dwordx4 v[24:25], off
	v_lshl_add_u64 v[24:25], v[24:25], 0, s[30:31]
	v_cvt_pk_bf16_f32 v91, v92, v93
	v_cvt_pk_bf16_f32 v92, v94, v95
	v_cvt_pk_bf16_f32 v93, v96, v97
	v_mfma_f32_32x32x16_bf16 v[142:157], v[186:189], v[134:137], v[142:157]
	s_add_u32 m0, s43, 0x6000
	v_exp_f32_e32 v98, v98
	v_exp_f32_e32 v99, v99
	global_load_lds_dwordx4 v[30:31], off
	v_lshl_add_u64 v[30:31], v[30:31], 0, s[12:13]
	v_exp_f32_e32 v100, v100
	v_add_f32_e32 v27, v27, v98
	v_exp_f32_e32 v101, v101
	v_mfma_f32_32x32x16_bf16 v[158:173], v[182:185], v[134:137], v[158:173]
	v_add_f32_e32 v27, v27, v99
	v_exp_f32_e32 v102, v102
	v_add_f32_e32 v27, v27, v100
	v_exp_f32_e32 v103, v103
	v_add_f32_e32 v27, v27, v101
	v_mfma_f32_32x32x16_bf16 v[142:157], v[178:181], v[138:141], v[142:157]
	v_exp_f32_e32 v104, v104
	v_add_f32_e32 v27, v27, v102
	v_exp_f32_e32 v105, v105
	v_add_f32_e32 v27, v27, v103
	v_add_f32_e32 v27, v27, v104
	v_mfma_f32_32x32x16_bf16 v[158:173], v[174:177], v[138:141], v[158:173]
	v_add_f32_e32 v27, v27, v105
	v_cvt_pk_bf16_f32 v98, v98, v99
	v_cvt_pk_bf16_f32 v99, v100, v101
	v_cvt_pk_bf16_f32 v100, v102, v103
	v_cvt_pk_bf16_f32 v101, v104, v105
	s_waitcnt lgkmcnt(0)
	v_mov_b32_e32 v2, v238
	v_mfma_f32_32x32x16_bf16 v[34:49], v[82:85], v[114:117], v[34:49]
	v_exp_f32_e32 v106, v106
	v_exp_f32_e32 v107, v107
	v_exp_f32_e32 v108, v108
	v_add_f32_e32 v27, v27, v106
	v_exp_f32_e32 v109, v109
	v_add_f32_e32 v27, v27, v107
	v_exp_f32_e32 v110, v110
	v_add_f32_e32 v27, v27, v108
	v_exp_f32_e32 v111, v111
	v_add_f32_e32 v27, v27, v109
	ds_read_b128 v[218:221], v2
	ds_read_b128 v[214:217], v2 offset:512
	ds_read_b128 v[210:213], v2 offset:2048
	v_mfma_f32_32x32x16_bf16 v[50:65], v[82:85], v[240:243], v[50:65]
	v_exp_f32_e32 v112, v112
	v_add_f32_e32 v27, v27, v110
	v_exp_f32_e32 v113, v113
	v_add_f32_e32 v27, v27, v111
	v_add_f32_e32 v27, v27, v112
	v_add_f32_e32 v27, v27, v113
	v_cvt_pk_bf16_f32 v106, v106, v107
	v_cvt_pk_bf16_f32 v107, v108, v109
	v_cvt_pk_bf16_f32 v108, v110, v111
	v_cvt_pk_bf16_f32 v109, v112, v113
	v_add_f32_e32 v236, v236, v27
	ds_read_b128 v[206:209], v2 offset:2560
	ds_read_b128 v[202:205], v2 offset:4096
	ds_read_b128 v[198:201], v2 offset:4608
	v_mfma_f32_32x32x16_bf16 v[34:49], v[90:93], v[118:121], v[34:49]
	ds_read_b128 v[194:197], v2 offset:6144
	ds_read_b128 v[190:193], v2 offset:6656
	ds_read_b128 v[186:189], v2 offset:8192
	v_max3_f32 v19, v142, v143, v144
	v_max3_f32 v26, v145, v146, v147
	v_max3_f32 v19, v19, v148, v149
	v_max3_f32 v26, v26, v150, v151
	v_max3_f32 v19, v19, v152, v153
	v_mfma_f32_32x32x16_bf16 v[50:65], v[90:93], v[244:247], v[50:65]
	ds_read_b128 v[182:185], v2 offset:8704
	ds_read_b128 v[178:181], v2 offset:10240
	ds_read_b128 v[174:177], v2 offset:10752
	v_max3_f32 v26, v26, v154, v155
	v_max3_f32 v19, v19, v156, v157
	v_max3_f32 v26, v26, v158, v159
	v_max3_f32 v19, v19, v160, v161
	v_max3_f32 v26, v26, v162, v163
	v_mfma_f32_32x32x16_bf16 v[34:49], v[98:101], v[122:125], v[34:49]
	v_max3_f32 v19, v19, v164, v165
	v_max3_f32 v26, v26, v166, v167
	v_max3_f32 v19, v19, v168, v169
	v_max3_f32 v26, v26, v170, v171
	v_mfma_f32_32x32x16_bf16 v[50:65], v[98:101], v[248:251], v[50:65]
	v_max3_f32 v19, v19, v172, v173
	v_max_f32_e32 v19, v19, v26
	v_mfma_f32_32x32x16_bf16 v[34:49], v[106:109], v[126:129], v[34:49]
	v_mfma_f32_32x32x16_bf16 v[50:65], v[106:109], v[20:23], v[50:65]
	v_cmp_lt_f32_e32 vcc, s41, v19
	s_cbranch_vccz .Lmy_nors_3
	s_nop 15
	s_nop 15
	v_mov_b32_e32 v26, v19
	s_nop 1
	v_permlane32_swap_b32_e32 v19, v26
	v_max_f32_e32 v19, v19, v26
	v_max_f32_e32 v19, v19, v19
	v_max_f32_e32 v90, 0, v19
	v_exp_f32_e64 v91, -v90
	v_add_f32_e32 v239, v239, v90
	v_xor_b32_e32 v66, 0x80000000, v239
	v_mov_b32_e32 v67, v66
	v_mov_b32_e32 v68, v66
	v_mov_b32_e32 v69, v66
	v_mov_b32_e32 v70, v66
	v_mov_b32_e32 v71, v66
	v_mov_b32_e32 v72, v66
	v_mov_b32_e32 v73, v66
	v_mov_b32_e32 v74, v66
	v_mov_b32_e32 v75, v66
	v_mov_b32_e32 v76, v66
	v_mov_b32_e32 v77, v66
	v_mov_b32_e32 v78, v66
	v_mov_b32_e32 v79, v66
	v_mov_b32_e32 v80, v66
	v_mov_b32_e32 v81, v66
	v_sub_f32_e32 v142, v142, v90
	v_sub_f32_e32 v143, v143, v90
	v_sub_f32_e32 v144, v144, v90
	v_sub_f32_e32 v145, v145, v90
	v_sub_f32_e32 v146, v146, v90
	v_sub_f32_e32 v147, v147, v90
	v_sub_f32_e32 v148, v148, v90
	v_sub_f32_e32 v149, v149, v90
	v_sub_f32_e32 v150, v150, v90
	v_sub_f32_e32 v151, v151, v90
	v_sub_f32_e32 v152, v152, v90
	v_sub_f32_e32 v153, v153, v90
	v_sub_f32_e32 v154, v154, v90
	v_sub_f32_e32 v155, v155, v90
	v_sub_f32_e32 v156, v156, v90
	v_sub_f32_e32 v157, v157, v90
	v_sub_f32_e32 v158, v158, v90
	v_sub_f32_e32 v159, v159, v90
	v_sub_f32_e32 v160, v160, v90
	v_sub_f32_e32 v161, v161, v90
	v_sub_f32_e32 v162, v162, v90
	v_sub_f32_e32 v163, v163, v90
	v_sub_f32_e32 v164, v164, v90
	v_sub_f32_e32 v165, v165, v90
	v_sub_f32_e32 v166, v166, v90
	v_sub_f32_e32 v167, v167, v90
	v_sub_f32_e32 v168, v168, v90
	v_sub_f32_e32 v169, v169, v90
	v_sub_f32_e32 v170, v170, v90
	v_sub_f32_e32 v171, v171, v90
	v_sub_f32_e32 v172, v172, v90
	v_sub_f32_e32 v173, v173, v90
	v_mul_f32_e32 v236, v236, v91
	s_mov_b64 s[96:97], exec
	s_and_b64 exec, exec, s[8:9]
	ds_write_b32 v235, v91
	s_mov_b64 exec, s[96:97]
	v_lshl_add_u32 v2, v228, 4, s47
	ds_read_b128 v[94:97], v2 offset:0
	s_waitcnt lgkmcnt(0)
	v_mul_f32_e32 v34, v34, v94
	v_mul_f32_e32 v50, v50, v94
	v_mul_f32_e32 v35, v35, v95
	v_mul_f32_e32 v51, v51, v95
	v_mul_f32_e32 v36, v36, v96
	v_mul_f32_e32 v52, v52, v96
	v_mul_f32_e32 v37, v37, v97
	v_mul_f32_e32 v53, v53, v97
	ds_read_b128 v[94:97], v2 offset:32
	s_waitcnt lgkmcnt(0)
	v_mul_f32_e32 v38, v38, v94
	v_mul_f32_e32 v54, v54, v94
	v_mul_f32_e32 v39, v39, v95
	v_mul_f32_e32 v55, v55, v95
	v_mul_f32_e32 v40, v40, v96
	v_mul_f32_e32 v56, v56, v96
	v_mul_f32_e32 v41, v41, v97
	v_mul_f32_e32 v57, v57, v97
	ds_read_b128 v[94:97], v2 offset:64
	s_waitcnt lgkmcnt(0)
	v_mul_f32_e32 v42, v42, v94
	v_mul_f32_e32 v58, v58, v94
	v_mul_f32_e32 v43, v43, v95
	v_mul_f32_e32 v59, v59, v95
	v_mul_f32_e32 v44, v44, v96
	v_mul_f32_e32 v60, v60, v96
	v_mul_f32_e32 v45, v45, v97
	v_mul_f32_e32 v61, v61, v97
	ds_read_b128 v[94:97], v2 offset:96
	s_waitcnt lgkmcnt(0)
	v_mul_f32_e32 v46, v46, v94
	v_mul_f32_e32 v62, v62, v94
	v_mul_f32_e32 v47, v47, v95
	v_mul_f32_e32 v63, v63, v95
	v_mul_f32_e32 v48, v48, v96
	v_mul_f32_e32 v64, v64, v96
	v_mul_f32_e32 v49, v49, v97
	v_mul_f32_e32 v65, v65, v97
.Lmy_nors_3:
	s_waitcnt lgkmcnt(0)
	v_add_u32_e32 v2, 0x6000, v237
	v_mfma_f32_32x32x16_bf16 v[82:97], v[218:221], v[4:7], v[66:81]
	v_exp_f32_e32 v142, v142
	v_exp_f32_e32 v143, v143
	v_exp_f32_e32 v144, v144
	v_add_f32_e32 v27, v142, v143
	v_exp_f32_e32 v145, v145
	ds_read_b64_tr_b16 v[114:115], v2 offset:49152
	ds_read_b64_tr_b16 v[116:117], v2 offset:49664
	ds_read_b64_tr_b16 v[118:119], v2 offset:50176
	ds_read_b64_tr_b16 v[120:121], v2 offset:50688
	v_mfma_f32_32x32x16_bf16 v[98:113], v[214:217], v[4:7], v[66:81]
	v_exp_f32_e32 v146, v146
	v_add_f32_e32 v27, v27, v144
	v_exp_f32_e32 v147, v147
	v_add_f32_e32 v27, v27, v145
	v_exp_f32_e32 v148, v148
	ds_read_b64_tr_b16 v[122:123], v2 offset:51200
	ds_read_b64_tr_b16 v[124:125], v2 offset:51712
	ds_read_b64_tr_b16 v[126:127], v2 offset:52224
	ds_read_b64_tr_b16 v[128:129], v2 offset:52736
	v_mfma_f32_32x32x16_bf16 v[82:97], v[210:213], v[8:11], v[82:97]
	v_add_f32_e32 v27, v27, v146
	v_exp_f32_e32 v149, v149
	v_add_f32_e32 v27, v27, v147
	v_add_f32_e32 v27, v27, v148
	v_add_f32_e32 v27, v27, v149
	ds_read_b64_tr_b16 v[240:241], v2 offset:53248
	ds_read_b64_tr_b16 v[242:243], v2 offset:53760
	ds_read_b64_tr_b16 v[244:245], v2 offset:54272
	ds_read_b64_tr_b16 v[246:247], v2 offset:54784
	v_mfma_f32_32x32x16_bf16 v[98:113], v[206:209], v[8:11], v[98:113]
	v_cvt_pk_bf16_f32 v142, v142, v143
	v_cvt_pk_bf16_f32 v143, v144, v145
	v_cvt_pk_bf16_f32 v144, v146, v147
	v_cvt_pk_bf16_f32 v145, v148, v149
	ds_read_b64_tr_b16 v[248:249], v2 offset:55296
	ds_read_b64_tr_b16 v[250:251], v2 offset:55808
	ds_read_b64_tr_b16 v[20:21], v2 offset:56320
	ds_read_b64_tr_b16 v[22:23], v2 offset:56832
	v_mfma_f32_32x32x16_bf16 v[82:97], v[202:205], v[12:15], v[82:97]
	v_exp_f32_e32 v150, v150
	v_exp_f32_e32 v151, v151
	v_exp_f32_e32 v152, v152
	v_add_f32_e32 v27, v27, v150
	v_exp_f32_e32 v153, v153
	v_mfma_f32_32x32x16_bf16 v[98:113], v[198:201], v[12:15], v[98:113]
	v_add_f32_e32 v27, v27, v151
	v_exp_f32_e32 v154, v154
	v_add_f32_e32 v27, v27, v152
	v_exp_f32_e32 v155, v155
	v_add_f32_e32 v27, v27, v153
	s_waitcnt vmcnt(3)
	s_barrier
	v_mfma_f32_32x32x16_bf16 v[82:97], v[194:197], v[130:133], v[82:97]
	s_add_u32 m0, s57, 0x4000
	v_exp_f32_e32 v156, v156
	v_add_f32_e32 v27, v27, v154
	global_load_lds_dwordx4 v[28:29], off
	v_lshl_add_u64 v[28:29], v[28:29], 0, s[30:31]
	v_exp_f32_e32 v157, v157
	v_add_f32_e32 v27, v27, v155
	v_add_f32_e32 v27, v27, v156
	v_mfma_f32_32x32x16_bf16 v[98:113], v[190:193], v[130:133], v[98:113]
	s_add_u32 m0, s40, 0x9000
	v_add_f32_e32 v27, v27, v157
	v_cvt_pk_bf16_f32 v150, v150, v151
	global_load_lds_dwordx4 v[24:25], off
	v_lshl_add_u64 v[24:25], v[24:25], 0, s[30:31]
	v_cvt_pk_bf16_f32 v151, v152, v153
	v_cvt_pk_bf16_f32 v152, v154, v155
	v_cvt_pk_bf16_f32 v153, v156, v157
	v_mfma_f32_32x32x16_bf16 v[82:97], v[186:189], v[134:137], v[82:97]
	s_add_u32 m0, s43, 0x9000
	v_exp_f32_e32 v158, v158
	v_exp_f32_e32 v159, v159
	global_load_lds_dwordx4 v[30:31], off
	v_lshl_add_u64 v[30:31], v[30:31], 0, s[12:13]
	v_exp_f32_e32 v160, v160
	v_add_f32_e32 v27, v27, v158
	v_exp_f32_e32 v161, v161
	v_mfma_f32_32x32x16_bf16 v[98:113], v[182:185], v[134:137], v[98:113]
	v_add_f32_e32 v27, v27, v159
	v_exp_f32_e32 v162, v162
	v_add_f32_e32 v27, v27, v160
	v_exp_f32_e32 v163, v163
	v_add_f32_e32 v27, v27, v161
	v_mfma_f32_32x32x16_bf16 v[82:97], v[178:181], v[138:141], v[82:97]
	v_exp_f32_e32 v164, v164
	v_add_f32_e32 v27, v27, v162
	v_exp_f32_e32 v165, v165
	v_add_f32_e32 v27, v27, v163
	v_add_f32_e32 v27, v27, v164
	v_mfma_f32_32x32x16_bf16 v[98:113], v[174:177], v[138:141], v[98:113]
	v_add_f32_e32 v27, v27, v165
	v_cvt_pk_bf16_f32 v158, v158, v159
	v_cvt_pk_bf16_f32 v159, v160, v161
	v_cvt_pk_bf16_f32 v160, v162, v163
	v_cvt_pk_bf16_f32 v161, v164, v165
	s_waitcnt lgkmcnt(0)
	v_add_u32_e32 v2, 0x3000, v238
	v_mfma_f32_32x32x16_bf16 v[34:49], v[142:145], v[114:117], v[34:49]
	v_exp_f32_e32 v166, v166
	v_exp_f32_e32 v167, v167
	v_exp_f32_e32 v168, v168
	v_add_f32_e32 v27, v27, v166
	v_exp_f32_e32 v169, v169
	v_add_f32_e32 v27, v27, v167
	v_exp_f32_e32 v170, v170
	v_add_f32_e32 v27, v27, v168
	v_exp_f32_e32 v171, v171
	v_add_f32_e32 v27, v27, v169
	ds_read_b128 v[218:221], v2
	ds_read_b128 v[214:217], v2 offset:512
	ds_read_b128 v[210:213], v2 offset:2048
	v_mfma_f32_32x32x16_bf16 v[50:65], v[142:145], v[240:243], v[50:65]
	v_exp_f32_e32 v172, v172
	v_add_f32_e32 v27, v27, v170
	v_exp_f32_e32 v173, v173
	v_add_f32_e32 v27, v27, v171
	v_add_f32_e32 v27, v27, v172
	v_add_f32_e32 v27, v27, v173
	v_cvt_pk_bf16_f32 v166, v166, v167
	v_cvt_pk_bf16_f32 v167, v168, v169
	v_cvt_pk_bf16_f32 v168, v170, v171
	v_cvt_pk_bf16_f32 v169, v172, v173
	v_add_f32_e32 v236, v236, v27
	ds_read_b128 v[206:209], v2 offset:2560
	ds_read_b128 v[202:205], v2 offset:4096
	ds_read_b128 v[198:201], v2 offset:4608
	v_mfma_f32_32x32x16_bf16 v[34:49], v[150:153], v[118:121], v[34:49]
	ds_read_b128 v[194:197], v2 offset:6144
	ds_read_b128 v[190:193], v2 offset:6656
	ds_read_b128 v[186:189], v2 offset:8192
	v_max3_f32 v19, v82, v83, v84
	v_max3_f32 v26, v85, v86, v87
	v_max3_f32 v19, v19, v88, v89
	v_max3_f32 v26, v26, v90, v91
	v_max3_f32 v19, v19, v92, v93
	v_mfma_f32_32x32x16_bf16 v[50:65], v[150:153], v[244:247], v[50:65]
	ds_read_b128 v[182:185], v2 offset:8704
	ds_read_b128 v[178:181], v2 offset:10240
	ds_read_b128 v[174:177], v2 offset:10752
	v_max3_f32 v26, v26, v94, v95
	v_max3_f32 v19, v19, v96, v97
	v_max3_f32 v26, v26, v98, v99
	v_max3_f32 v19, v19, v100, v101
	v_max3_f32 v26, v26, v102, v103
	v_mfma_f32_32x32x16_bf16 v[34:49], v[158:161], v[122:125], v[34:49]
	v_max3_f32 v19, v19, v104, v105
	v_max3_f32 v26, v26, v106, v107
	v_max3_f32 v19, v19, v108, v109
	v_max3_f32 v26, v26, v110, v111
	v_mfma_f32_32x32x16_bf16 v[50:65], v[158:161], v[248:251], v[50:65]
	v_max3_f32 v19, v19, v112, v113
	v_max_f32_e32 v19, v19, v26
	v_mfma_f32_32x32x16_bf16 v[34:49], v[166:169], v[126:129], v[34:49]
	v_mfma_f32_32x32x16_bf16 v[50:65], v[166:169], v[20:23], v[50:65]
	v_cmp_lt_f32_e32 vcc, s41, v19
	s_cbranch_vccz .Lmy_nors_4
	s_nop 15
	s_nop 15
	v_mov_b32_e32 v26, v19
	s_nop 1
	v_permlane32_swap_b32_e32 v19, v26
	v_max_f32_e32 v19, v19, v26
	v_max_f32_e32 v19, v19, v19
	v_max_f32_e32 v150, 0, v19
	v_exp_f32_e64 v151, -v150
	v_add_f32_e32 v239, v239, v150
	v_xor_b32_e32 v66, 0x80000000, v239
	v_mov_b32_e32 v67, v66
	v_mov_b32_e32 v68, v66
	v_mov_b32_e32 v69, v66
	v_mov_b32_e32 v70, v66
	v_mov_b32_e32 v71, v66
	v_mov_b32_e32 v72, v66
	v_mov_b32_e32 v73, v66
	v_mov_b32_e32 v74, v66
	v_mov_b32_e32 v75, v66
	v_mov_b32_e32 v76, v66
	v_mov_b32_e32 v77, v66
	v_mov_b32_e32 v78, v66
	v_mov_b32_e32 v79, v66
	v_mov_b32_e32 v80, v66
	v_mov_b32_e32 v81, v66
	v_sub_f32_e32 v82, v82, v150
	v_sub_f32_e32 v83, v83, v150
	v_sub_f32_e32 v84, v84, v150
	v_sub_f32_e32 v85, v85, v150
	v_sub_f32_e32 v86, v86, v150
	v_sub_f32_e32 v87, v87, v150
	v_sub_f32_e32 v88, v88, v150
	v_sub_f32_e32 v89, v89, v150
	v_sub_f32_e32 v90, v90, v150
	v_sub_f32_e32 v91, v91, v150
	v_sub_f32_e32 v92, v92, v150
	v_sub_f32_e32 v93, v93, v150
	v_sub_f32_e32 v94, v94, v150
	v_sub_f32_e32 v95, v95, v150
	v_sub_f32_e32 v96, v96, v150
	v_sub_f32_e32 v97, v97, v150
	v_sub_f32_e32 v98, v98, v150
	v_sub_f32_e32 v99, v99, v150
	v_sub_f32_e32 v100, v100, v150
	v_sub_f32_e32 v101, v101, v150
	v_sub_f32_e32 v102, v102, v150
	v_sub_f32_e32 v103, v103, v150
	v_sub_f32_e32 v104, v104, v150
	v_sub_f32_e32 v105, v105, v150
	v_sub_f32_e32 v106, v106, v150
	v_sub_f32_e32 v107, v107, v150
	v_sub_f32_e32 v108, v108, v150
	v_sub_f32_e32 v109, v109, v150
	v_sub_f32_e32 v110, v110, v150
	v_sub_f32_e32 v111, v111, v150
	v_sub_f32_e32 v112, v112, v150
	v_sub_f32_e32 v113, v113, v150
	v_mul_f32_e32 v236, v236, v151
	s_mov_b64 s[96:97], exec
	s_and_b64 exec, exec, s[8:9]
	ds_write_b32 v235, v151
	s_mov_b64 exec, s[96:97]
	v_lshl_add_u32 v2, v228, 4, s47
	ds_read_b128 v[154:157], v2 offset:0
	s_waitcnt lgkmcnt(0)
	v_mul_f32_e32 v34, v34, v154
	v_mul_f32_e32 v50, v50, v154
	v_mul_f32_e32 v35, v35, v155
	v_mul_f32_e32 v51, v51, v155
	v_mul_f32_e32 v36, v36, v156
	v_mul_f32_e32 v52, v52, v156
	v_mul_f32_e32 v37, v37, v157
	v_mul_f32_e32 v53, v53, v157
	ds_read_b128 v[154:157], v2 offset:32
	s_waitcnt lgkmcnt(0)
	v_mul_f32_e32 v38, v38, v154
	v_mul_f32_e32 v54, v54, v154
	v_mul_f32_e32 v39, v39, v155
	v_mul_f32_e32 v55, v55, v155
	v_mul_f32_e32 v40, v40, v156
	v_mul_f32_e32 v56, v56, v156
	v_mul_f32_e32 v41, v41, v157
	v_mul_f32_e32 v57, v57, v157
	ds_read_b128 v[154:157], v2 offset:64
	s_waitcnt lgkmcnt(0)
	v_mul_f32_e32 v42, v42, v154
	v_mul_f32_e32 v58, v58, v154
	v_mul_f32_e32 v43, v43, v155
	v_mul_f32_e32 v59, v59, v155
	v_mul_f32_e32 v44, v44, v156
	v_mul_f32_e32 v60, v60, v156
	v_mul_f32_e32 v45, v45, v157
	v_mul_f32_e32 v61, v61, v157
	ds_read_b128 v[154:157], v2 offset:96
	s_waitcnt lgkmcnt(0)
	v_mul_f32_e32 v46, v46, v154
	v_mul_f32_e32 v62, v62, v154
	v_mul_f32_e32 v47, v47, v155
	v_mul_f32_e32 v63, v63, v155
	v_mul_f32_e32 v48, v48, v156
	v_mul_f32_e32 v64, v64, v156
	v_mul_f32_e32 v49, v49, v157
	v_mul_f32_e32 v65, v65, v157
.Lmy_nors_4:
	s_add_i32 s79, s79, -1
	s_cmp_gt_i32 s79, 0
	s_cbranch_scc1 .Lmy_A_loop
.Lmy_A_tail:
	s_cmp_gt_u32 s71, 0
	s_cbranch_scc1 .Lmy_tf_5
	s_cmp_eq_u32 s71, 0
	s_cbranch_scc1 .Lmy_ts_6
	s_waitcnt lgkmcnt(0)
	s_waitcnt vmcnt(3)
	s_barrier
	s_add_u32 m0, s57, 0x6000
	s_nop 0
	global_load_lds_dwordx4 v[28:29], off
	v_lshl_add_u64 v[28:29], v[28:29], 0, s[30:31]
	s_branch .Lmy_te_7
.Lmy_ts_6:
	s_waitcnt lgkmcnt(0)
	v_mov_b32_e32 v2, v237
	ds_read_b64_tr_b16 v[114:115], v2 offset:49152
	ds_read_b64_tr_b16 v[116:117], v2 offset:49664
	ds_read_b64_tr_b16 v[118:119], v2 offset:50176
	ds_read_b64_tr_b16 v[120:121], v2 offset:50688
	ds_read_b64_tr_b16 v[122:123], v2 offset:51200
	ds_read_b64_tr_b16 v[124:125], v2 offset:51712
	ds_read_b64_tr_b16 v[126:127], v2 offset:52224
	ds_read_b64_tr_b16 v[128:129], v2 offset:52736
	ds_read_b64_tr_b16 v[240:241], v2 offset:53248
	ds_read_b64_tr_b16 v[242:243], v2 offset:53760
	ds_read_b64_tr_b16 v[244:245], v2 offset:54272
	ds_read_b64_tr_b16 v[246:247], v2 offset:54784
	ds_read_b64_tr_b16 v[248:249], v2 offset:55296
	ds_read_b64_tr_b16 v[250:251], v2 offset:55808
	ds_read_b64_tr_b16 v[20:21], v2 offset:56320
	ds_read_b64_tr_b16 v[22:23], v2 offset:56832
	v_exp_f32_e32 v82, v82
	v_exp_f32_e32 v83, v83
	v_exp_f32_e32 v84, v84
	v_add_f32_e32 v27, v82, v83
	v_exp_f32_e32 v85, v85
	v_exp_f32_e32 v86, v86
	v_add_f32_e32 v27, v27, v84
	v_exp_f32_e32 v87, v87
	v_add_f32_e32 v27, v27, v85
	v_exp_f32_e32 v88, v88
	v_add_f32_e32 v27, v27, v86
	v_exp_f32_e32 v89, v89
	v_add_f32_e32 v27, v27, v87
	v_add_f32_e32 v27, v27, v88
	v_add_f32_e32 v27, v27, v89
	v_cvt_pk_bf16_f32 v82, v82, v83
	v_cvt_pk_bf16_f32 v83, v84, v85
	v_cvt_pk_bf16_f32 v84, v86, v87
	v_cvt_pk_bf16_f32 v85, v88, v89
	v_exp_f32_e32 v90, v90
	v_exp_f32_e32 v91, v91
	v_exp_f32_e32 v92, v92
	v_add_f32_e32 v27, v27, v90
	v_exp_f32_e32 v93, v93
	v_add_f32_e32 v27, v27, v91
	v_exp_f32_e32 v94, v94
	v_add_f32_e32 v27, v27, v92
	v_exp_f32_e32 v95, v95
	v_add_f32_e32 v27, v27, v93
	v_exp_f32_e32 v96, v96
	v_add_f32_e32 v27, v27, v94
	v_exp_f32_e32 v97, v97
	v_add_f32_e32 v27, v27, v95
	v_add_f32_e32 v27, v27, v96
	v_add_f32_e32 v27, v27, v97
	v_cvt_pk_bf16_f32 v90, v90, v91
	v_cvt_pk_bf16_f32 v91, v92, v93
	v_cvt_pk_bf16_f32 v92, v94, v95
	v_cvt_pk_bf16_f32 v93, v96, v97
	s_waitcnt vmcnt(3)
	s_barrier
	s_add_u32 m0, s57, 0x6000
	s_nop 0
	global_load_lds_dwordx4 v[28:29], off
	v_lshl_add_u64 v[28:29], v[28:29], 0, s[30:31]
	s_waitcnt lgkmcnt(0)
	v_mfma_f32_32x32x16_bf16 v[34:49], v[82:85], v[114:117], v[34:49]
	v_mfma_f32_32x32x16_bf16 v[50:65], v[82:85], v[240:243], v[50:65]
	v_exp_f32_e32 v98, v98
	v_exp_f32_e32 v99, v99
	v_exp_f32_e32 v100, v100
	v_add_f32_e32 v27, v27, v98
	v_exp_f32_e32 v101, v101
	v_add_f32_e32 v27, v27, v99
	v_exp_f32_e32 v102, v102
	v_add_f32_e32 v27, v27, v100
	v_exp_f32_e32 v103, v103
	v_add_f32_e32 v27, v27, v101
	v_exp_f32_e32 v104, v104
	v_add_f32_e32 v27, v27, v102
	v_exp_f32_e32 v105, v105
	v_add_f32_e32 v27, v27, v103
	v_add_f32_e32 v27, v27, v104
	v_add_f32_e32 v27, v27, v105
	v_cvt_pk_bf16_f32 v98, v98, v99
	v_cvt_pk_bf16_f32 v99, v100, v101
	v_cvt_pk_bf16_f32 v100, v102, v103
	v_cvt_pk_bf16_f32 v101, v104, v105
	v_mfma_f32_32x32x16_bf16 v[34:49], v[90:93], v[118:121], v[34:49]
	v_mfma_f32_32x32x16_bf16 v[50:65], v[90:93], v[244:247], v[50:65]
	v_exp_f32_e32 v106, v106
	v_exp_f32_e32 v107, v107
	v_exp_f32_e32 v108, v108
	v_add_f32_e32 v27, v27, v106
	v_exp_f32_e32 v109, v109
	v_add_f32_e32 v27, v27, v107
	v_exp_f32_e32 v110, v110
	v_add_f32_e32 v27, v27, v108
	v_exp_f32_e32 v111, v111
	v_add_f32_e32 v27, v27, v109
	v_exp_f32_e32 v112, v112
	v_add_f32_e32 v27, v27, v110
	v_exp_f32_e32 v113, v113
	v_add_f32_e32 v27, v27, v111
	v_add_f32_e32 v27, v27, v112
	v_add_f32_e32 v27, v27, v113
	v_cvt_pk_bf16_f32 v106, v106, v107
	v_cvt_pk_bf16_f32 v107, v108, v109
	v_cvt_pk_bf16_f32 v108, v110, v111
	v_cvt_pk_bf16_f32 v109, v112, v113
	v_add_f32_e32 v236, v236, v27
	s_nop 1
	v_mfma_f32_32x32x16_bf16 v[34:49], v[98:101], v[122:125], v[34:49]
	v_mfma_f32_32x32x16_bf16 v[50:65], v[98:101], v[248:251], v[50:65]
	v_mfma_f32_32x32x16_bf16 v[34:49], v[106:109], v[126:129], v[34:49]
	v_mfma_f32_32x32x16_bf16 v[50:65], v[106:109], v[20:23], v[50:65]
	s_branch .Lmy_te_7
.Lmy_tf_5:
	s_waitcnt lgkmcnt(0)
	v_mov_b32_e32 v2, v237
	v_mfma_f32_32x32x16_bf16 v[142:157], v[218:221], v[4:7], v[66:81]
	v_exp_f32_e32 v82, v82
	v_exp_f32_e32 v83, v83
	v_exp_f32_e32 v84, v84
	v_add_f32_e32 v27, v82, v83
	v_exp_f32_e32 v85, v85
	ds_read_b64_tr_b16 v[114:115], v2 offset:49152
	ds_read_b64_tr_b16 v[116:117], v2 offset:49664
	ds_read_b64_tr_b16 v[118:119], v2 offset:50176
	ds_read_b64_tr_b16 v[120:121], v2 offset:50688
	v_mfma_f32_32x32x16_bf16 v[158:173], v[214:217], v[4:7], v[66:81]
	v_exp_f32_e32 v86, v86
	v_add_f32_e32 v27, v27, v84
	v_exp_f32_e32 v87, v87
	v_add_f32_e32 v27, v27, v85
	v_exp_f32_e32 v88, v88
	ds_read_b64_tr_b16 v[122:123], v2 offset:51200
	ds_read_b64_tr_b16 v[124:125], v2 offset:51712
	ds_read_b64_tr_b16 v[126:127], v2 offset:52224
	ds_read_b64_tr_b16 v[128:129], v2 offset:52736
	v_mfma_f32_32x32x16_bf16 v[142:157], v[210:213], v[8:11], v[142:157]
	v_add_f32_e32 v27, v27, v86
	v_exp_f32_e32 v89, v89
	v_add_f32_e32 v27, v27, v87
	v_add_f32_e32 v27, v27, v88
	v_add_f32_e32 v27, v27, v89
	ds_read_b64_tr_b16 v[240:241], v2 offset:53248
	ds_read_b64_tr_b16 v[242:243], v2 offset:53760
	ds_read_b64_tr_b16 v[244:245], v2 offset:54272
	ds_read_b64_tr_b16 v[246:247], v2 offset:54784
	v_mfma_f32_32x32x16_bf16 v[158:173], v[206:209], v[8:11], v[158:173]
	v_cvt_pk_bf16_f32 v82, v82, v83
	v_cvt_pk_bf16_f32 v83, v84, v85
	v_cvt_pk_bf16_f32 v84, v86, v87
	v_cvt_pk_bf16_f32 v85, v88, v89
	ds_read_b64_tr_b16 v[248:249], v2 offset:55296
	ds_read_b64_tr_b16 v[250:251], v2 offset:55808
	ds_read_b64_tr_b16 v[20:21], v2 offset:56320
	ds_read_b64_tr_b16 v[22:23], v2 offset:56832
	v_mfma_f32_32x32x16_bf16 v[142:157], v[202:205], v[12:15], v[142:157]
	v_exp_f32_e32 v90, v90
	v_exp_f32_e32 v91, v91
	v_exp_f32_e32 v92, v92
	v_add_f32_e32 v27, v27, v90
	v_exp_f32_e32 v93, v93
	v_mfma_f32_32x32x16_bf16 v[158:173], v[198:201], v[12:15], v[158:173]
	v_add_f32_e32 v27, v27, v91
	v_exp_f32_e32 v94, v94
	v_add_f32_e32 v27, v27, v92
	v_exp_f32_e32 v95, v95
	v_add_f32_e32 v27, v27, v93
	s_waitcnt vmcnt(3)
	s_barrier
	v_mfma_f32_32x32x16_bf16 v[142:157], v[194:197], v[130:133], v[142:157]
	s_add_u32 m0, s57, 0x6000
	v_exp_f32_e32 v96, v96
	v_add_f32_e32 v27, v27, v94
	global_load_lds_dwordx4 v[28:29], off
	v_lshl_add_u64 v[28:29], v[28:29], 0, s[30:31]
	v_exp_f32_e32 v97, v97
	v_add_f32_e32 v27, v27, v95
	v_add_f32_e32 v27, v27, v96
	v_mfma_f32_32x32x16_bf16 v[158:173], v[190:193], v[130:133], v[158:173]
	v_add_f32_e32 v27, v27, v97
	v_cvt_pk_bf16_f32 v90, v90, v91
	v_cvt_pk_bf16_f32 v91, v92, v93
	v_cvt_pk_bf16_f32 v92, v94, v95
	v_cvt_pk_bf16_f32 v93, v96, v97
	v_mfma_f32_32x32x16_bf16 v[142:157], v[186:189], v[134:137], v[142:157]
	v_exp_f32_e32 v98, v98
	v_exp_f32_e32 v99, v99
	v_exp_f32_e32 v100, v100
	v_add_f32_e32 v27, v27, v98
	v_exp_f32_e32 v101, v101
	v_mfma_f32_32x32x16_bf16 v[158:173], v[182:185], v[134:137], v[158:173]
	v_add_f32_e32 v27, v27, v99
	v_exp_f32_e32 v102, v102
	v_add_f32_e32 v27, v27, v100
	v_exp_f32_e32 v103, v103
	v_add_f32_e32 v27, v27, v101
	v_mfma_f32_32x32x16_bf16 v[142:157], v[178:181], v[138:141], v[142:157]
	v_exp_f32_e32 v104, v104
	v_add_f32_e32 v27, v27, v102
	v_exp_f32_e32 v105, v105
	v_add_f32_e32 v27, v27, v103
	v_add_f32_e32 v27, v27, v104
	v_mfma_f32_32x32x16_bf16 v[158:173], v[174:177], v[138:141], v[158:173]
	v_add_f32_e32 v27, v27, v105
	v_cvt_pk_bf16_f32 v98, v98, v99
	v_cvt_pk_bf16_f32 v99, v100, v101
	v_cvt_pk_bf16_f32 v100, v102, v103
	v_cvt_pk_bf16_f32 v101, v104, v105
	s_waitcnt lgkmcnt(0)
	v_add_u32_e32 v2, 0x6000, v238
	v_mfma_f32_32x32x16_bf16 v[34:49], v[82:85], v[114:117], v[34:49]
	v_exp_f32_e32 v106, v106
	v_exp_f32_e32 v107, v107
	v_exp_f32_e32 v108, v108
	v_add_f32_e32 v27, v27, v106
	v_exp_f32_e32 v109, v109
	v_add_f32_e32 v27, v27, v107
	v_exp_f32_e32 v110, v110
	v_add_f32_e32 v27, v27, v108
	v_exp_f32_e32 v111, v111
	v_add_f32_e32 v27, v27, v109
	s_cmp_gt_u32 s71, 1
	s_cbranch_scc0 .Lmy_nok_8
	ds_read_b128 v[218:221], v2
	ds_read_b128 v[214:217], v2 offset:512
	ds_read_b128 v[210:213], v2 offset:2048
	ds_read_b128 v[206:209], v2 offset:2560
	ds_read_b128 v[202:205], v2 offset:4096
	ds_read_b128 v[198:201], v2 offset:4608
	ds_read_b128 v[194:197], v2 offset:6144
	ds_read_b128 v[190:193], v2 offset:6656
	ds_read_b128 v[186:189], v2 offset:8192
	ds_read_b128 v[182:185], v2 offset:8704
	ds_read_b128 v[178:181], v2 offset:10240
	ds_read_b128 v[174:177], v2 offset:10752
.Lmy_nok_8:
	v_mfma_f32_32x32x16_bf16 v[50:65], v[82:85], v[240:243], v[50:65]
	v_exp_f32_e32 v112, v112
	v_add_f32_e32 v27, v27, v110
	v_exp_f32_e32 v113, v113
	v_add_f32_e32 v27, v27, v111
	v_add_f32_e32 v27, v27, v112
	v_add_f32_e32 v27, v27, v113
	v_cvt_pk_bf16_f32 v106, v106, v107
	v_cvt_pk_bf16_f32 v107, v108, v109
	v_cvt_pk_bf16_f32 v108, v110, v111
	v_cvt_pk_bf16_f32 v109, v112, v113
	v_add_f32_e32 v236, v236, v27
	v_mfma_f32_32x32x16_bf16 v[34:49], v[90:93], v[118:121], v[34:49]
	v_max3_f32 v19, v142, v143, v144
	v_max3_f32 v26, v145, v146, v147
	v_max3_f32 v19, v19, v148, v149
	v_max3_f32 v26, v26, v150, v151
	v_max3_f32 v19, v19, v152, v153
	v_mfma_f32_32x32x16_bf16 v[50:65], v[90:93], v[244:247], v[50:65]
	v_max3_f32 v26, v26, v154, v155
	v_max3_f32 v19, v19, v156, v157
	v_max3_f32 v26, v26, v158, v159
	v_max3_f32 v19, v19, v160, v161
	v_max3_f32 v26, v26, v162, v163
	v_mfma_f32_32x32x16_bf16 v[34:49], v[98:101], v[122:125], v[34:49]
	v_max3_f32 v19, v19, v164, v165
	v_max3_f32 v26, v26, v166, v167
	v_max3_f32 v19, v19, v168, v169
	v_max3_f32 v26, v26, v170, v171
	v_mfma_f32_32x32x16_bf16 v[50:65], v[98:101], v[248:251], v[50:65]
	v_max3_f32 v19, v19, v172, v173
	v_max_f32_e32 v19, v19, v26
	v_mfma_f32_32x32x16_bf16 v[34:49], v[106:109], v[126:129], v[34:49]
	v_mfma_f32_32x32x16_bf16 v[50:65], v[106:109], v[20:23], v[50:65]
	v_cmp_lt_f32_e32 vcc, s41, v19
	s_cbranch_vccz .Lmy_nors_9
	s_nop 15
	s_nop 15
	v_mov_b32_e32 v26, v19
	s_nop 1
	v_permlane32_swap_b32_e32 v19, v26
	v_max_f32_e32 v19, v19, v26
	v_max_f32_e32 v19, v19, v19
	v_max_f32_e32 v90, 0, v19
	v_exp_f32_e64 v91, -v90
	v_add_f32_e32 v239, v239, v90
	v_xor_b32_e32 v66, 0x80000000, v239
	v_mov_b32_e32 v67, v66
	v_mov_b32_e32 v68, v66
	v_mov_b32_e32 v69, v66
	v_mov_b32_e32 v70, v66
	v_mov_b32_e32 v71, v66
	v_mov_b32_e32 v72, v66
	v_mov_b32_e32 v73, v66
	v_mov_b32_e32 v74, v66
	v_mov_b32_e32 v75, v66
	v_mov_b32_e32 v76, v66
	v_mov_b32_e32 v77, v66
	v_mov_b32_e32 v78, v66
	v_mov_b32_e32 v79, v66
	v_mov_b32_e32 v80, v66
	v_mov_b32_e32 v81, v66
	v_sub_f32_e32 v142, v142, v90
	v_sub_f32_e32 v143, v143, v90
	v_sub_f32_e32 v144, v144, v90
	v_sub_f32_e32 v145, v145, v90
	v_sub_f32_e32 v146, v146, v90
	v_sub_f32_e32 v147, v147, v90
	v_sub_f32_e32 v148, v148, v90
	v_sub_f32_e32 v149, v149, v90
	v_sub_f32_e32 v150, v150, v90
	v_sub_f32_e32 v151, v151, v90
	v_sub_f32_e32 v152, v152, v90
	v_sub_f32_e32 v153, v153, v90
	v_sub_f32_e32 v154, v154, v90
	v_sub_f32_e32 v155, v155, v90
	v_sub_f32_e32 v156, v156, v90
	v_sub_f32_e32 v157, v157, v90
	v_sub_f32_e32 v158, v158, v90
	v_sub_f32_e32 v159, v159, v90
	v_sub_f32_e32 v160, v160, v90
	v_sub_f32_e32 v161, v161, v90
	v_sub_f32_e32 v162, v162, v90
	v_sub_f32_e32 v163, v163, v90
	v_sub_f32_e32 v164, v164, v90
	v_sub_f32_e32 v165, v165, v90
	v_sub_f32_e32 v166, v166, v90
	v_sub_f32_e32 v167, v167, v90
	v_sub_f32_e32 v168, v168, v90
	v_sub_f32_e32 v169, v169, v90
	v_sub_f32_e32 v170, v170, v90
	v_sub_f32_e32 v171, v171, v90
	v_sub_f32_e32 v172, v172, v90
	v_sub_f32_e32 v173, v173, v90
	v_mul_f32_e32 v236, v236, v91
	s_mov_b64 s[96:97], exec
	s_and_b64 exec, exec, s[8:9]
	ds_write_b32 v235, v91
	s_mov_b64 exec, s[96:97]
	v_lshl_add_u32 v2, v228, 4, s47
	ds_read_b128 v[94:97], v2 offset:0
	s_waitcnt lgkmcnt(0)
	v_mul_f32_e32 v34, v34, v94
	v_mul_f32_e32 v50, v50, v94
	v_mul_f32_e32 v35, v35, v95
	v_mul_f32_e32 v51, v51, v95
	v_mul_f32_e32 v36, v36, v96
	v_mul_f32_e32 v52, v52, v96
	v_mul_f32_e32 v37, v37, v97
	v_mul_f32_e32 v53, v53, v97
	ds_read_b128 v[94:97], v2 offset:32
	s_waitcnt lgkmcnt(0)
	v_mul_f32_e32 v38, v38, v94
	v_mul_f32_e32 v54, v54, v94
	v_mul_f32_e32 v39, v39, v95
	v_mul_f32_e32 v55, v55, v95
	v_mul_f32_e32 v40, v40, v96
	v_mul_f32_e32 v56, v56, v96
	v_mul_f32_e32 v41, v41, v97
	v_mul_f32_e32 v57, v57, v97
	ds_read_b128 v[94:97], v2 offset:64
	s_waitcnt lgkmcnt(0)
	v_mul_f32_e32 v42, v42, v94
	v_mul_f32_e32 v58, v58, v94
	v_mul_f32_e32 v43, v43, v95
	v_mul_f32_e32 v59, v59, v95
	v_mul_f32_e32 v44, v44, v96
	v_mul_f32_e32 v60, v60, v96
	v_mul_f32_e32 v45, v45, v97
	v_mul_f32_e32 v61, v61, v97
	ds_read_b128 v[94:97], v2 offset:96
	s_waitcnt lgkmcnt(0)
	v_mul_f32_e32 v46, v46, v94
	v_mul_f32_e32 v62, v62, v94
	v_mul_f32_e32 v47, v47, v95
	v_mul_f32_e32 v63, v63, v95
	v_mul_f32_e32 v48, v48, v96
	v_mul_f32_e32 v64, v64, v96
	v_mul_f32_e32 v49, v49, v97
	v_mul_f32_e32 v65, v65, v97
.Lmy_nors_9:
.Lmy_te_7:
	s_cmp_gt_u32 s71, 1
	s_cbranch_scc1 .Lmy_tf_10
	s_cmp_eq_u32 s71, 1
	s_cbranch_scc1 .Lmy_ts_11
	s_waitcnt lgkmcnt(0)
	s_waitcnt vmcnt(1)
	s_barrier
	s_branch .Lmy_te_12
.Lmy_ts_11:
	s_waitcnt lgkmcnt(0)
	v_add_u32_e32 v2, 0x2000, v237
	ds_read_b64_tr_b16 v[114:115], v2 offset:49152
	ds_read_b64_tr_b16 v[116:117], v2 offset:49664
	ds_read_b64_tr_b16 v[118:119], v2 offset:50176
	ds_read_b64_tr_b16 v[120:121], v2 offset:50688
	ds_read_b64_tr_b16 v[122:123], v2 offset:51200
	ds_read_b64_tr_b16 v[124:125], v2 offset:51712
	ds_read_b64_tr_b16 v[126:127], v2 offset:52224
	ds_read_b64_tr_b16 v[128:129], v2 offset:52736
	ds_read_b64_tr_b16 v[240:241], v2 offset:53248
	ds_read_b64_tr_b16 v[242:243], v2 offset:53760
	ds_read_b64_tr_b16 v[244:245], v2 offset:54272
	ds_read_b64_tr_b16 v[246:247], v2 offset:54784
	ds_read_b64_tr_b16 v[248:249], v2 offset:55296
	ds_read_b64_tr_b16 v[250:251], v2 offset:55808
	ds_read_b64_tr_b16 v[20:21], v2 offset:56320
	ds_read_b64_tr_b16 v[22:23], v2 offset:56832
	v_exp_f32_e32 v142, v142
	v_exp_f32_e32 v143, v143
	v_exp_f32_e32 v144, v144
	v_add_f32_e32 v27, v142, v143
	v_exp_f32_e32 v145, v145
	v_exp_f32_e32 v146, v146
	v_add_f32_e32 v27, v27, v144
	v_exp_f32_e32 v147, v147
	v_add_f32_e32 v27, v27, v145
	v_exp_f32_e32 v148, v148
	v_add_f32_e32 v27, v27, v146
	v_exp_f32_e32 v149, v149
	v_add_f32_e32 v27, v27, v147
	v_add_f32_e32 v27, v27, v148
	v_add_f32_e32 v27, v27, v149
	v_cvt_pk_bf16_f32 v142, v142, v143
	v_cvt_pk_bf16_f32 v143, v144, v145
	v_cvt_pk_bf16_f32 v144, v146, v147
	v_cvt_pk_bf16_f32 v145, v148, v149
	v_exp_f32_e32 v150, v150
	v_exp_f32_e32 v151, v151
	v_exp_f32_e32 v152, v152
	v_add_f32_e32 v27, v27, v150
	v_exp_f32_e32 v153, v153
	v_add_f32_e32 v27, v27, v151
	v_exp_f32_e32 v154, v154
	v_add_f32_e32 v27, v27, v152
	v_exp_f32_e32 v155, v155
	v_add_f32_e32 v27, v27, v153
	v_exp_f32_e32 v156, v156
	v_add_f32_e32 v27, v27, v154
	v_exp_f32_e32 v157, v157
	v_add_f32_e32 v27, v27, v155
	v_add_f32_e32 v27, v27, v156
	v_add_f32_e32 v27, v27, v157
	v_cvt_pk_bf16_f32 v150, v150, v151
	v_cvt_pk_bf16_f32 v151, v152, v153
	v_cvt_pk_bf16_f32 v152, v154, v155
	v_cvt_pk_bf16_f32 v153, v156, v157
	s_waitcnt vmcnt(1)
	s_barrier
	s_waitcnt lgkmcnt(0)
	v_mfma_f32_32x32x16_bf16 v[34:49], v[142:145], v[114:117], v[34:49]
	v_mfma_f32_32x32x16_bf16 v[50:65], v[142:145], v[240:243], v[50:65]
	v_exp_f32_e32 v158, v158
	v_exp_f32_e32 v159, v159
	v_exp_f32_e32 v160, v160
	v_add_f32_e32 v27, v27, v158
	v_exp_f32_e32 v161, v161
	v_add_f32_e32 v27, v27, v159
	v_exp_f32_e32 v162, v162
	v_add_f32_e32 v27, v27, v160
	v_exp_f32_e32 v163, v163
	v_add_f32_e32 v27, v27, v161
	v_exp_f32_e32 v164, v164
	v_add_f32_e32 v27, v27, v162
	v_exp_f32_e32 v165, v165
	v_add_f32_e32 v27, v27, v163
	v_add_f32_e32 v27, v27, v164
	v_add_f32_e32 v27, v27, v165
	v_cvt_pk_bf16_f32 v158, v158, v159
	v_cvt_pk_bf16_f32 v159, v160, v161
	v_cvt_pk_bf16_f32 v160, v162, v163
	v_cvt_pk_bf16_f32 v161, v164, v165
	v_mfma_f32_32x32x16_bf16 v[34:49], v[150:153], v[118:121], v[34:49]
	v_mfma_f32_32x32x16_bf16 v[50:65], v[150:153], v[244:247], v[50:65]
	v_exp_f32_e32 v166, v166
	v_exp_f32_e32 v167, v167
	v_exp_f32_e32 v168, v168
	v_add_f32_e32 v27, v27, v166
	v_exp_f32_e32 v169, v169
	v_add_f32_e32 v27, v27, v167
	v_exp_f32_e32 v170, v170
	v_add_f32_e32 v27, v27, v168
	v_exp_f32_e32 v171, v171
	v_add_f32_e32 v27, v27, v169
	v_exp_f32_e32 v172, v172
	v_add_f32_e32 v27, v27, v170
	v_exp_f32_e32 v173, v173
	v_add_f32_e32 v27, v27, v171
	v_add_f32_e32 v27, v27, v172
	v_add_f32_e32 v27, v27, v173
	v_cvt_pk_bf16_f32 v166, v166, v167
	v_cvt_pk_bf16_f32 v167, v168, v169
	v_cvt_pk_bf16_f32 v168, v170, v171
	v_cvt_pk_bf16_f32 v169, v172, v173
	v_add_f32_e32 v236, v236, v27
	s_nop 1
	v_mfma_f32_32x32x16_bf16 v[34:49], v[158:161], v[122:125], v[34:49]
	v_mfma_f32_32x32x16_bf16 v[50:65], v[158:161], v[248:251], v[50:65]
	v_mfma_f32_32x32x16_bf16 v[34:49], v[166:169], v[126:129], v[34:49]
	v_mfma_f32_32x32x16_bf16 v[50:65], v[166:169], v[20:23], v[50:65]
	s_branch .Lmy_te_12
.Lmy_tf_10:
	s_waitcnt lgkmcnt(0)
	v_add_u32_e32 v2, 0x2000, v237
	v_mfma_f32_32x32x16_bf16 v[82:97], v[218:221], v[4:7], v[66:81]
	v_exp_f32_e32 v142, v142
	v_exp_f32_e32 v143, v143
	v_exp_f32_e32 v144, v144
	v_add_f32_e32 v27, v142, v143
	v_exp_f32_e32 v145, v145
	ds_read_b64_tr_b16 v[114:115], v2 offset:49152
	ds_read_b64_tr_b16 v[116:117], v2 offset:49664
	ds_read_b64_tr_b16 v[118:119], v2 offset:50176
	ds_read_b64_tr_b16 v[120:121], v2 offset:50688
	v_mfma_f32_32x32x16_bf16 v[98:113], v[214:217], v[4:7], v[66:81]
	v_exp_f32_e32 v146, v146
	v_add_f32_e32 v27, v27, v144
	v_exp_f32_e32 v147, v147
	v_add_f32_e32 v27, v27, v145
	v_exp_f32_e32 v148, v148
	ds_read_b64_tr_b16 v[122:123], v2 offset:51200
	ds_read_b64_tr_b16 v[124:125], v2 offset:51712
	ds_read_b64_tr_b16 v[126:127], v2 offset:52224
	ds_read_b64_tr_b16 v[128:129], v2 offset:52736
	v_mfma_f32_32x32x16_bf16 v[82:97], v[210:213], v[8:11], v[82:97]
	v_add_f32_e32 v27, v27, v146
	v_exp_f32_e32 v149, v149
	v_add_f32_e32 v27, v27, v147
	v_add_f32_e32 v27, v27, v148
	v_add_f32_e32 v27, v27, v149
	ds_read_b64_tr_b16 v[240:241], v2 offset:53248
	ds_read_b64_tr_b16 v[242:243], v2 offset:53760
	ds_read_b64_tr_b16 v[244:245], v2 offset:54272
	ds_read_b64_tr_b16 v[246:247], v2 offset:54784
	v_mfma_f32_32x32x16_bf16 v[98:113], v[206:209], v[8:11], v[98:113]
	v_cvt_pk_bf16_f32 v142, v142, v143
	v_cvt_pk_bf16_f32 v143, v144, v145
	v_cvt_pk_bf16_f32 v144, v146, v147
	v_cvt_pk_bf16_f32 v145, v148, v149
	ds_read_b64_tr_b16 v[248:249], v2 offset:55296
	ds_read_b64_tr_b16 v[250:251], v2 offset:55808
	ds_read_b64_tr_b16 v[20:21], v2 offset:56320
	ds_read_b64_tr_b16 v[22:23], v2 offset:56832
	v_mfma_f32_32x32x16_bf16 v[82:97], v[202:205], v[12:15], v[82:97]
	v_exp_f32_e32 v150, v150
	v_exp_f32_e32 v151, v151
	v_exp_f32_e32 v152, v152
	v_add_f32_e32 v27, v27, v150
	v_exp_f32_e32 v153, v153
	v_mfma_f32_32x32x16_bf16 v[98:113], v[198:201], v[12:15], v[98:113]
	v_add_f32_e32 v27, v27, v151
	v_exp_f32_e32 v154, v154
	v_add_f32_e32 v27, v27, v152
	v_exp_f32_e32 v155, v155
	v_add_f32_e32 v27, v27, v153
	s_waitcnt vmcnt(1)
	s_barrier
	v_mfma_f32_32x32x16_bf16 v[82:97], v[194:197], v[130:133], v[82:97]
	v_exp_f32_e32 v156, v156
	v_add_f32_e32 v27, v27, v154
	v_exp_f32_e32 v157, v157
	v_add_f32_e32 v27, v27, v155
	v_add_f32_e32 v27, v27, v156
	v_mfma_f32_32x32x16_bf16 v[98:113], v[190:193], v[130:133], v[98:113]
	v_add_f32_e32 v27, v27, v157
	v_cvt_pk_bf16_f32 v150, v150, v151
	v_cvt_pk_bf16_f32 v151, v152, v153
	v_cvt_pk_bf16_f32 v152, v154, v155
	v_cvt_pk_bf16_f32 v153, v156, v157
	v_mfma_f32_32x32x16_bf16 v[82:97], v[186:189], v[134:137], v[82:97]
	v_exp_f32_e32 v158, v158
	v_exp_f32_e32 v159, v159
	v_exp_f32_e32 v160, v160
	v_add_f32_e32 v27, v27, v158
	v_exp_f32_e32 v161, v161
	v_mfma_f32_32x32x16_bf16 v[98:113], v[182:185], v[134:137], v[98:113]
	v_add_f32_e32 v27, v27, v159
	v_exp_f32_e32 v162, v162
	v_add_f32_e32 v27, v27, v160
	v_exp_f32_e32 v163, v163
	v_add_f32_e32 v27, v27, v161
	v_mfma_f32_32x32x16_bf16 v[82:97], v[178:181], v[138:141], v[82:97]
	v_exp_f32_e32 v164, v164
	v_add_f32_e32 v27, v27, v162
	v_exp_f32_e32 v165, v165
	v_add_f32_e32 v27, v27, v163
	v_add_f32_e32 v27, v27, v164
	v_mfma_f32_32x32x16_bf16 v[98:113], v[174:177], v[138:141], v[98:113]
	v_add_f32_e32 v27, v27, v165
	v_cvt_pk_bf16_f32 v158, v158, v159
	v_cvt_pk_bf16_f32 v159, v160, v161
	v_cvt_pk_bf16_f32 v160, v162, v163
	v_cvt_pk_bf16_f32 v161, v164, v165
	s_waitcnt lgkmcnt(0)
	v_add_u32_e32 v2, 0x9000, v238
	v_mfma_f32_32x32x16_bf16 v[34:49], v[142:145], v[114:117], v[34:49]
	v_exp_f32_e32 v166, v166
	v_exp_f32_e32 v167, v167
	v_exp_f32_e32 v168, v168
	v_add_f32_e32 v27, v27, v166
	v_exp_f32_e32 v169, v169
	v_add_f32_e32 v27, v27, v167
	v_exp_f32_e32 v170, v170
	v_add_f32_e32 v27, v27, v168
	v_exp_f32_e32 v171, v171
	v_add_f32_e32 v27, v27, v169
	s_cmp_gt_u32 s71, 2
	s_cbranch_scc0 .Lmy_nok_13
	ds_read_b128 v[218:221], v2
	ds_read_b128 v[214:217], v2 offset:512
	ds_read_b128 v[210:213], v2 offset:2048
	ds_read_b128 v[206:209], v2 offset:2560
	ds_read_b128 v[202:205], v2 offset:4096
	ds_read_b128 v[198:201], v2 offset:4608
	ds_read_b128 v[194:197], v2 offset:6144
	ds_read_b128 v[190:193], v2 offset:6656
	ds_read_b128 v[186:189], v2 offset:8192
	ds_read_b128 v[182:185], v2 offset:8704
	ds_read_b128 v[178:181], v2 offset:10240
	ds_read_b128 v[174:177], v2 offset:10752
.Lmy_nok_13:
	v_mfma_f32_32x32x16_bf16 v[50:65], v[142:145], v[240:243], v[50:65]
	v_exp_f32_e32 v172, v172
	v_add_f32_e32 v27, v27, v170
	v_exp_f32_e32 v173, v173
	v_add_f32_e32 v27, v27, v171
	v_add_f32_e32 v27, v27, v172
	v_add_f32_e32 v27, v27, v173
	v_cvt_pk_bf16_f32 v166, v166, v167
	v_cvt_pk_bf16_f32 v167, v168, v169
	v_cvt_pk_bf16_f32 v168, v170, v171
	v_cvt_pk_bf16_f32 v169, v172, v173
	v_add_f32_e32 v236, v236, v27
	v_mfma_f32_32x32x16_bf16 v[34:49], v[150:153], v[118:121], v[34:49]
	v_max3_f32 v19, v82, v83, v84
	v_max3_f32 v26, v85, v86, v87
	v_max3_f32 v19, v19, v88, v89
	v_max3_f32 v26, v26, v90, v91
	v_max3_f32 v19, v19, v92, v93
	v_mfma_f32_32x32x16_bf16 v[50:65], v[150:153], v[244:247], v[50:65]
	v_max3_f32 v26, v26, v94, v95
	v_max3_f32 v19, v19, v96, v97
	v_max3_f32 v26, v26, v98, v99
	v_max3_f32 v19, v19, v100, v101
	v_max3_f32 v26, v26, v102, v103
	v_mfma_f32_32x32x16_bf16 v[34:49], v[158:161], v[122:125], v[34:49]
	v_max3_f32 v19, v19, v104, v105
	v_max3_f32 v26, v26, v106, v107
	v_max3_f32 v19, v19, v108, v109
	v_max3_f32 v26, v26, v110, v111
	v_mfma_f32_32x32x16_bf16 v[50:65], v[158:161], v[248:251], v[50:65]
	v_max3_f32 v19, v19, v112, v113
	v_max_f32_e32 v19, v19, v26
	v_mfma_f32_32x32x16_bf16 v[34:49], v[166:169], v[126:129], v[34:49]
	v_mfma_f32_32x32x16_bf16 v[50:65], v[166:169], v[20:23], v[50:65]
	v_cmp_lt_f32_e32 vcc, s41, v19
	s_cbranch_vccz .Lmy_nors_14
	s_nop 15
	s_nop 15
	v_mov_b32_e32 v26, v19
	s_nop 1
	v_permlane32_swap_b32_e32 v19, v26
	v_max_f32_e32 v19, v19, v26
	v_max_f32_e32 v19, v19, v19
	v_max_f32_e32 v150, 0, v19
	v_exp_f32_e64 v151, -v150
	v_add_f32_e32 v239, v239, v150
	v_xor_b32_e32 v66, 0x80000000, v239
	v_mov_b32_e32 v67, v66
	v_mov_b32_e32 v68, v66
	v_mov_b32_e32 v69, v66
	v_mov_b32_e32 v70, v66
	v_mov_b32_e32 v71, v66
	v_mov_b32_e32 v72, v66
	v_mov_b32_e32 v73, v66
	v_mov_b32_e32 v74, v66
	v_mov_b32_e32 v75, v66
	v_mov_b32_e32 v76, v66
	v_mov_b32_e32 v77, v66
	v_mov_b32_e32 v78, v66
	v_mov_b32_e32 v79, v66
	v_mov_b32_e32 v80, v66
	v_mov_b32_e32 v81, v66
	v_sub_f32_e32 v82, v82, v150
	v_sub_f32_e32 v83, v83, v150
	v_sub_f32_e32 v84, v84, v150
	v_sub_f32_e32 v85, v85, v150
	v_sub_f32_e32 v86, v86, v150
	v_sub_f32_e32 v87, v87, v150
	v_sub_f32_e32 v88, v88, v150
	v_sub_f32_e32 v89, v89, v150
	v_sub_f32_e32 v90, v90, v150
	v_sub_f32_e32 v91, v91, v150
	v_sub_f32_e32 v92, v92, v150
	v_sub_f32_e32 v93, v93, v150
	v_sub_f32_e32 v94, v94, v150
	v_sub_f32_e32 v95, v95, v150
	v_sub_f32_e32 v96, v96, v150
	v_sub_f32_e32 v97, v97, v150
	v_sub_f32_e32 v98, v98, v150
	v_sub_f32_e32 v99, v99, v150
	v_sub_f32_e32 v100, v100, v150
	v_sub_f32_e32 v101, v101, v150
	v_sub_f32_e32 v102, v102, v150
	v_sub_f32_e32 v103, v103, v150
	v_sub_f32_e32 v104, v104, v150
	v_sub_f32_e32 v105, v105, v150
	v_sub_f32_e32 v106, v106, v150
	v_sub_f32_e32 v107, v107, v150
	v_sub_f32_e32 v108, v108, v150
	v_sub_f32_e32 v109, v109, v150
	v_sub_f32_e32 v110, v110, v150
	v_sub_f32_e32 v111, v111, v150
	v_sub_f32_e32 v112, v112, v150
	v_sub_f32_e32 v113, v113, v150
	v_mul_f32_e32 v236, v236, v151
	s_mov_b64 s[96:97], exec
	s_and_b64 exec, exec, s[8:9]
	ds_write_b32 v235, v151
	s_mov_b64 exec, s[96:97]
	v_lshl_add_u32 v2, v228, 4, s47
	ds_read_b128 v[154:157], v2 offset:0
	s_waitcnt lgkmcnt(0)
	v_mul_f32_e32 v34, v34, v154
	v_mul_f32_e32 v50, v50, v154
	v_mul_f32_e32 v35, v35, v155
	v_mul_f32_e32 v51, v51, v155
	v_mul_f32_e32 v36, v36, v156
	v_mul_f32_e32 v52, v52, v156
	v_mul_f32_e32 v37, v37, v157
	v_mul_f32_e32 v53, v53, v157
	ds_read_b128 v[154:157], v2 offset:32
	s_waitcnt lgkmcnt(0)
	v_mul_f32_e32 v38, v38, v154
	v_mul_f32_e32 v54, v54, v154
	v_mul_f32_e32 v39, v39, v155
	v_mul_f32_e32 v55, v55, v155
	v_mul_f32_e32 v40, v40, v156
	v_mul_f32_e32 v56, v56, v156
	v_mul_f32_e32 v41, v41, v157
	v_mul_f32_e32 v57, v57, v157
	ds_read_b128 v[154:157], v2 offset:64
	s_waitcnt lgkmcnt(0)
	v_mul_f32_e32 v42, v42, v154
	v_mul_f32_e32 v58, v58, v154
	v_mul_f32_e32 v43, v43, v155
	v_mul_f32_e32 v59, v59, v155
	v_mul_f32_e32 v44, v44, v156
	v_mul_f32_e32 v60, v60, v156
	v_mul_f32_e32 v45, v45, v157
	v_mul_f32_e32 v61, v61, v157
	ds_read_b128 v[154:157], v2 offset:96
	s_waitcnt lgkmcnt(0)
	v_mul_f32_e32 v46, v46, v154
	v_mul_f32_e32 v62, v62, v154
	v_mul_f32_e32 v47, v47, v155
	v_mul_f32_e32 v63, v63, v155
	v_mul_f32_e32 v48, v48, v156
	v_mul_f32_e32 v64, v64, v156
	v_mul_f32_e32 v49, v49, v157
	v_mul_f32_e32 v65, v65, v157
.Lmy_nors_14:
.Lmy_te_12:
	s_cmp_gt_u32 s71, 2
	s_cbranch_scc1 .Lmy_tf_15
	s_cmp_eq_u32 s71, 2
	s_cbranch_scc1 .Lmy_ts_16
	s_waitcnt lgkmcnt(0)
	s_waitcnt vmcnt(0)
	s_barrier
	s_branch .Lmy_te_17
.Lmy_ts_16:
	s_waitcnt lgkmcnt(0)
	v_add_u32_e32 v2, 0x4000, v237
	ds_read_b64_tr_b16 v[114:115], v2 offset:49152
	ds_read_b64_tr_b16 v[116:117], v2 offset:49664
	ds_read_b64_tr_b16 v[118:119], v2 offset:50176
	ds_read_b64_tr_b16 v[120:121], v2 offset:50688
	ds_read_b64_tr_b16 v[122:123], v2 offset:51200
	ds_read_b64_tr_b16 v[124:125], v2 offset:51712
	ds_read_b64_tr_b16 v[126:127], v2 offset:52224
	ds_read_b64_tr_b16 v[128:129], v2 offset:52736
	ds_read_b64_tr_b16 v[240:241], v2 offset:53248
	ds_read_b64_tr_b16 v[242:243], v2 offset:53760
	ds_read_b64_tr_b16 v[244:245], v2 offset:54272
	ds_read_b64_tr_b16 v[246:247], v2 offset:54784
	ds_read_b64_tr_b16 v[248:249], v2 offset:55296
	ds_read_b64_tr_b16 v[250:251], v2 offset:55808
	ds_read_b64_tr_b16 v[20:21], v2 offset:56320
	ds_read_b64_tr_b16 v[22:23], v2 offset:56832
	v_exp_f32_e32 v82, v82
	v_exp_f32_e32 v83, v83
	v_exp_f32_e32 v84, v84
	v_add_f32_e32 v27, v82, v83
	v_exp_f32_e32 v85, v85
	v_exp_f32_e32 v86, v86
	v_add_f32_e32 v27, v27, v84
	v_exp_f32_e32 v87, v87
	v_add_f32_e32 v27, v27, v85
	v_exp_f32_e32 v88, v88
	v_add_f32_e32 v27, v27, v86
	v_exp_f32_e32 v89, v89
	v_add_f32_e32 v27, v27, v87
	v_add_f32_e32 v27, v27, v88
	v_add_f32_e32 v27, v27, v89
	v_cvt_pk_bf16_f32 v82, v82, v83
	v_cvt_pk_bf16_f32 v83, v84, v85
	v_cvt_pk_bf16_f32 v84, v86, v87
	v_cvt_pk_bf16_f32 v85, v88, v89
	v_exp_f32_e32 v90, v90
	v_exp_f32_e32 v91, v91
	v_exp_f32_e32 v92, v92
	v_add_f32_e32 v27, v27, v90
	v_exp_f32_e32 v93, v93
	v_add_f32_e32 v27, v27, v91
	v_exp_f32_e32 v94, v94
	v_add_f32_e32 v27, v27, v92
	v_exp_f32_e32 v95, v95
	v_add_f32_e32 v27, v27, v93
	v_exp_f32_e32 v96, v96
	v_add_f32_e32 v27, v27, v94
	v_exp_f32_e32 v97, v97
	v_add_f32_e32 v27, v27, v95
	v_add_f32_e32 v27, v27, v96
	v_add_f32_e32 v27, v27, v97
	v_cvt_pk_bf16_f32 v90, v90, v91
	v_cvt_pk_bf16_f32 v91, v92, v93
	v_cvt_pk_bf16_f32 v92, v94, v95
	v_cvt_pk_bf16_f32 v93, v96, v97
	s_waitcnt vmcnt(0)
	s_barrier
	s_waitcnt lgkmcnt(0)
	v_mfma_f32_32x32x16_bf16 v[34:49], v[82:85], v[114:117], v[34:49]
	v_mfma_f32_32x32x16_bf16 v[50:65], v[82:85], v[240:243], v[50:65]
	v_exp_f32_e32 v98, v98
	v_exp_f32_e32 v99, v99
	v_exp_f32_e32 v100, v100
	v_add_f32_e32 v27, v27, v98
	v_exp_f32_e32 v101, v101
	v_add_f32_e32 v27, v27, v99
	v_exp_f32_e32 v102, v102
	v_add_f32_e32 v27, v27, v100
	v_exp_f32_e32 v103, v103
	v_add_f32_e32 v27, v27, v101
	v_exp_f32_e32 v104, v104
	v_add_f32_e32 v27, v27, v102
	v_exp_f32_e32 v105, v105
	v_add_f32_e32 v27, v27, v103
	v_add_f32_e32 v27, v27, v104
	v_add_f32_e32 v27, v27, v105
	v_cvt_pk_bf16_f32 v98, v98, v99
	v_cvt_pk_bf16_f32 v99, v100, v101
	v_cvt_pk_bf16_f32 v100, v102, v103
	v_cvt_pk_bf16_f32 v101, v104, v105
	v_mfma_f32_32x32x16_bf16 v[34:49], v[90:93], v[118:121], v[34:49]
	v_mfma_f32_32x32x16_bf16 v[50:65], v[90:93], v[244:247], v[50:65]
	v_exp_f32_e32 v106, v106
	v_exp_f32_e32 v107, v107
	v_exp_f32_e32 v108, v108
	v_add_f32_e32 v27, v27, v106
	v_exp_f32_e32 v109, v109
	v_add_f32_e32 v27, v27, v107
	v_exp_f32_e32 v110, v110
	v_add_f32_e32 v27, v27, v108
	v_exp_f32_e32 v111, v111
	v_add_f32_e32 v27, v27, v109
	v_exp_f32_e32 v112, v112
	v_add_f32_e32 v27, v27, v110
	v_exp_f32_e32 v113, v113
	v_add_f32_e32 v27, v27, v111
	v_add_f32_e32 v27, v27, v112
	v_add_f32_e32 v27, v27, v113
	v_cvt_pk_bf16_f32 v106, v106, v107
	v_cvt_pk_bf16_f32 v107, v108, v109
	v_cvt_pk_bf16_f32 v108, v110, v111
	v_cvt_pk_bf16_f32 v109, v112, v113
	v_add_f32_e32 v236, v236, v27
	s_nop 1
	v_mfma_f32_32x32x16_bf16 v[34:49], v[98:101], v[122:125], v[34:49]
	v_mfma_f32_32x32x16_bf16 v[50:65], v[98:101], v[248:251], v[50:65]
	v_mfma_f32_32x32x16_bf16 v[34:49], v[106:109], v[126:129], v[34:49]
	v_mfma_f32_32x32x16_bf16 v[50:65], v[106:109], v[20:23], v[50:65]
	s_branch .Lmy_te_17
.Lmy_tf_15:
	s_waitcnt lgkmcnt(0)
	v_add_u32_e32 v2, 0x4000, v237
	v_mfma_f32_32x32x16_bf16 v[142:157], v[218:221], v[4:7], v[66:81]
	v_exp_f32_e32 v82, v82
	v_exp_f32_e32 v83, v83
	v_exp_f32_e32 v84, v84
	v_add_f32_e32 v27, v82, v83
	v_exp_f32_e32 v85, v85
	ds_read_b64_tr_b16 v[114:115], v2 offset:49152
	ds_read_b64_tr_b16 v[116:117], v2 offset:49664
	ds_read_b64_tr_b16 v[118:119], v2 offset:50176
	ds_read_b64_tr_b16 v[120:121], v2 offset:50688
	v_mfma_f32_32x32x16_bf16 v[158:173], v[214:217], v[4:7], v[66:81]
	v_exp_f32_e32 v86, v86
	v_add_f32_e32 v27, v27, v84
	v_exp_f32_e32 v87, v87
	v_add_f32_e32 v27, v27, v85
	v_exp_f32_e32 v88, v88
	ds_read_b64_tr_b16 v[122:123], v2 offset:51200
	ds_read_b64_tr_b16 v[124:125], v2 offset:51712
	ds_read_b64_tr_b16 v[126:127], v2 offset:52224
	ds_read_b64_tr_b16 v[128:129], v2 offset:52736
	v_mfma_f32_32x32x16_bf16 v[142:157], v[210:213], v[8:11], v[142:157]
	v_add_f32_e32 v27, v27, v86
	v_exp_f32_e32 v89, v89
	v_add_f32_e32 v27, v27, v87
	v_add_f32_e32 v27, v27, v88
	v_add_f32_e32 v27, v27, v89
	ds_read_b64_tr_b16 v[240:241], v2 offset:53248
	ds_read_b64_tr_b16 v[242:243], v2 offset:53760
	ds_read_b64_tr_b16 v[244:245], v2 offset:54272
	ds_read_b64_tr_b16 v[246:247], v2 offset:54784
	v_mfma_f32_32x32x16_bf16 v[158:173], v[206:209], v[8:11], v[158:173]
	v_cvt_pk_bf16_f32 v82, v82, v83
	v_cvt_pk_bf16_f32 v83, v84, v85
	v_cvt_pk_bf16_f32 v84, v86, v87
	v_cvt_pk_bf16_f32 v85, v88, v89
	ds_read_b64_tr_b16 v[248:249], v2 offset:55296
	ds_read_b64_tr_b16 v[250:251], v2 offset:55808
	ds_read_b64_tr_b16 v[20:21], v2 offset:56320
	ds_read_b64_tr_b16 v[22:23], v2 offset:56832
	v_mfma_f32_32x32x16_bf16 v[142:157], v[202:205], v[12:15], v[142:157]
	v_exp_f32_e32 v90, v90
	v_exp_f32_e32 v91, v91
	v_exp_f32_e32 v92, v92
	v_add_f32_e32 v27, v27, v90
	v_exp_f32_e32 v93, v93
	v_mfma_f32_32x32x16_bf16 v[158:173], v[198:201], v[12:15], v[158:173]
	v_add_f32_e32 v27, v27, v91
	v_exp_f32_e32 v94, v94
	v_add_f32_e32 v27, v27, v92
	v_exp_f32_e32 v95, v95
	v_add_f32_e32 v27, v27, v93
	s_waitcnt vmcnt(0)
	s_barrier
	v_mfma_f32_32x32x16_bf16 v[142:157], v[194:197], v[130:133], v[142:157]
	v_exp_f32_e32 v96, v96
	v_add_f32_e32 v27, v27, v94
	v_exp_f32_e32 v97, v97
	v_add_f32_e32 v27, v27, v95
	v_add_f32_e32 v27, v27, v96
	v_mfma_f32_32x32x16_bf16 v[158:173], v[190:193], v[130:133], v[158:173]
	v_add_f32_e32 v27, v27, v97
	v_cvt_pk_bf16_f32 v90, v90, v91
	v_cvt_pk_bf16_f32 v91, v92, v93
	v_cvt_pk_bf16_f32 v92, v94, v95
	v_cvt_pk_bf16_f32 v93, v96, v97
	v_mfma_f32_32x32x16_bf16 v[142:157], v[186:189], v[134:137], v[142:157]
	v_exp_f32_e32 v98, v98
	v_exp_f32_e32 v99, v99
	v_exp_f32_e32 v100, v100
	v_add_f32_e32 v27, v27, v98
	v_exp_f32_e32 v101, v101
	v_mfma_f32_32x32x16_bf16 v[158:173], v[182:185], v[134:137], v[158:173]
	v_add_f32_e32 v27, v27, v99
	v_exp_f32_e32 v102, v102
	v_add_f32_e32 v27, v27, v100
	v_exp_f32_e32 v103, v103
	v_add_f32_e32 v27, v27, v101
	v_mfma_f32_32x32x16_bf16 v[142:157], v[178:181], v[138:141], v[142:157]
	v_exp_f32_e32 v104, v104
	v_add_f32_e32 v27, v27, v102
	v_exp_f32_e32 v105, v105
	v_add_f32_e32 v27, v27, v103
	v_add_f32_e32 v27, v27, v104
	v_mfma_f32_32x32x16_bf16 v[158:173], v[174:177], v[138:141], v[158:173]
	v_add_f32_e32 v27, v27, v105
	v_cvt_pk_bf16_f32 v98, v98, v99
	v_cvt_pk_bf16_f32 v99, v100, v101
	v_cvt_pk_bf16_f32 v100, v102, v103
	v_cvt_pk_bf16_f32 v101, v104, v105
	s_waitcnt lgkmcnt(0)
	v_mov_b32_e32 v2, v238
	v_mfma_f32_32x32x16_bf16 v[34:49], v[82:85], v[114:117], v[34:49]
	v_exp_f32_e32 v106, v106
	v_exp_f32_e32 v107, v107
	v_exp_f32_e32 v108, v108
	v_add_f32_e32 v27, v27, v106
	v_exp_f32_e32 v109, v109
	v_add_f32_e32 v27, v27, v107
	v_exp_f32_e32 v110, v110
	v_add_f32_e32 v27, v27, v108
	v_exp_f32_e32 v111, v111
	v_add_f32_e32 v27, v27, v109
	s_cmp_gt_u32 s71, 3
	s_cbranch_scc0 .Lmy_nok_18
	ds_read_b128 v[218:221], v2
	ds_read_b128 v[214:217], v2 offset:512
	ds_read_b128 v[210:213], v2 offset:2048
	ds_read_b128 v[206:209], v2 offset:2560
	ds_read_b128 v[202:205], v2 offset:4096
	ds_read_b128 v[198:201], v2 offset:4608
	ds_read_b128 v[194:197], v2 offset:6144
	ds_read_b128 v[190:193], v2 offset:6656
	ds_read_b128 v[186:189], v2 offset:8192
	ds_read_b128 v[182:185], v2 offset:8704
	ds_read_b128 v[178:181], v2 offset:10240
	ds_read_b128 v[174:177], v2 offset:10752

.Lmy_nors_19:
.Lmy_te_17:
	s_cmp_gt_u32 s71, 3
	s_cbranch_scc1 .Lmy_tf_20
	s_cmp_eq_u32 s71, 3
	s_cbranch_scc1 .Lmy_ts_21
	s_waitcnt lgkmcnt(0)
	s_waitcnt vmcnt(0)
	s_barrier
	s_branch .Lmy_te_22
.Lmy_ts_21:
	s_waitcnt lgkmcnt(0)
	v_add_u32_e32 v2, 0x6000, v237
	ds_read_b64_tr_b16 v[114:115], v2 offset:49152
	ds_read_b64_tr_b16 v[116:117], v2 offset:49664
	ds_read_b64_tr_b16 v[118:119], v2 offset:50176
	ds_read_b64_tr_b16 v[120:121], v2 offset:50688
	ds_read_b64_tr_b16 v[122:123], v2 offset:51200
	ds_read_b64_tr_b16 v[124:125], v2 offset:51712
	ds_read_b64_tr_b16 v[126:127], v2 offset:52224
	ds_read_b64_tr_b16 v[128:129], v2 offset:52736
	ds_read_b64_tr_b16 v[240:241], v2 offset:53248
	ds_read_b64_tr_b16 v[242:243], v2 offset:53760
	ds_read_b64_tr_b16 v[244:245], v2 offset:54272
	ds_read_b64_tr_b16 v[246:247], v2 offset:54784
	ds_read_b64_tr_b16 v[248:249], v2 offset:55296
	ds_read_b64_tr_b16 v[250:251], v2 offset:55808
	ds_read_b64_tr_b16 v[20:21], v2 offset:56320
	ds_read_b64_tr_b16 v[22:23], v2 offset:56832
	v_exp_f32_e32 v142, v142
	v_exp_f32_e32 v143, v143
	v_exp_f32_e32 v144, v144
	v_add_f32_e32 v27, v142, v143
	v_exp_f32_e32 v145, v145
	v_exp_f32_e32 v146, v146
	v_add_f32_e32 v27, v27, v144
	v_exp_f32_e32 v147, v147
	v_add_f32_e32 v27, v27, v145
	v_exp_f32_e32 v148, v148
	v_add_f32_e32 v27, v27, v146
	v_exp_f32_e32 v149, v149
	v_add_f32_e32 v27, v27, v147
	v_add_f32_e32 v27, v27, v148
	v_add_f32_e32 v27, v27, v149
	v_cvt_pk_bf16_f32 v142, v142, v143
	v_cvt_pk_bf16_f32 v143, v144, v145
	v_cvt_pk_bf16_f32 v144, v146, v147
	v_cvt_pk_bf16_f32 v145, v148, v149
	v_exp_f32_e32 v150, v150
	v_exp_f32_e32 v151, v151
	v_exp_f32_e32 v152, v152
	v_add_f32_e32 v27, v27, v150
	v_exp_f32_e32 v153, v153
	v_add_f32_e32 v27, v27, v151
	v_exp_f32_e32 v154, v154
	v_add_f32_e32 v27, v27, v152
	v_exp_f32_e32 v155, v155
	v_add_f32_e32 v27, v27, v153
	v_exp_f32_e32 v156, v156
	v_add_f32_e32 v27, v27, v154
	v_exp_f32_e32 v157, v157
	v_add_f32_e32 v27, v27, v155
	v_add_f32_e32 v27, v27, v156
	v_add_f32_e32 v27, v27, v157
	v_cvt_pk_bf16_f32 v150, v150, v151
	v_cvt_pk_bf16_f32 v151, v152, v153
	v_cvt_pk_bf16_f32 v152, v154, v155
	v_cvt_pk_bf16_f32 v153, v156, v157
	s_waitcnt vmcnt(0)
	s_barrier
	s_waitcnt lgkmcnt(0)
	v_mfma_f32_32x32x16_bf16 v[34:49], v[142:145], v[114:117], v[34:49]
	v_mfma_f32_32x32x16_bf16 v[50:65], v[142:145], v[240:243], v[50:65]
	v_exp_f32_e32 v158, v158
	v_exp_f32_e32 v159, v159
	v_exp_f32_e32 v160, v160
	v_add_f32_e32 v27, v27, v158
	v_exp_f32_e32 v161, v161
	v_add_f32_e32 v27, v27, v159
	v_exp_f32_e32 v162, v162
	v_add_f32_e32 v27, v27, v160
	v_exp_f32_e32 v163, v163
	v_add_f32_e32 v27, v27, v161
	v_exp_f32_e32 v164, v164
	v_add_f32_e32 v27, v27, v162
	v_exp_f32_e32 v165, v165
	v_add_f32_e32 v27, v27, v163
	v_add_f32_e32 v27, v27, v164
	v_add_f32_e32 v27, v27, v165
	v_cvt_pk_bf16_f32 v158, v158, v159
	v_cvt_pk_bf16_f32 v159, v160, v161
	v_cvt_pk_bf16_f32 v160, v162, v163
	v_cvt_pk_bf16_f32 v161, v164, v165
	v_mfma_f32_32x32x16_bf16 v[34:49], v[150:153], v[118:121], v[34:49]
	v_mfma_f32_32x32x16_bf16 v[50:65], v[150:153], v[244:247], v[50:65]
	v_exp_f32_e32 v166, v166
	v_exp_f32_e32 v167, v167
	v_exp_f32_e32 v168, v168
	v_add_f32_e32 v27, v27, v166
	v_exp_f32_e32 v169, v169
	v_add_f32_e32 v27, v27, v167
	v_exp_f32_e32 v170, v170
	v_add_f32_e32 v27, v27, v168
	v_exp_f32_e32 v171, v171
	v_add_f32_e32 v27, v27, v169
	v_exp_f32_e32 v172, v172
	v_add_f32_e32 v27, v27, v170
	v_exp_f32_e32 v173, v173
	v_add_f32_e32 v27, v27, v171
	v_add_f32_e32 v27, v27, v172
	v_add_f32_e32 v27, v27, v173
	v_cvt_pk_bf16_f32 v166, v166, v167
	v_cvt_pk_bf16_f32 v167, v168, v169
	v_cvt_pk_bf16_f32 v168, v170, v171
	v_cvt_pk_bf16_f32 v169, v172, v173
	v_add_f32_e32 v236, v236, v27
	s_nop 1
	v_mfma_f32_32x32x16_bf16 v[34:49], v[158:161], v[122:125], v[34:49]
	v_mfma_f32_32x32x16_bf16 v[50:65], v[158:161], v[248:251], v[50:65]
	v_mfma_f32_32x32x16_bf16 v[34:49], v[166:169], v[126:129], v[34:49]
	v_mfma_f32_32x32x16_bf16 v[50:65], v[166:169], v[20:23], v[50:65]
	s_branch .Lmy_te_22

.Lmy_B_entry:
	s_mov_b32 s30, 0x20000
	s_mov_b32 s31, 0
	s_mov_b32 s12, 0x1000
	s_mov_b32 s13, 0
	s_lshr_b32 s71, s24, 1
	s_lshr_b32 s79, s25, 2
	s_add_i32 s79, s79, -1
	s_mov_b32 s0, 0x80000
	s_mov_b32 s1, 0
	v_lshl_add_u64 v[24:25], v[16:17], 0, s[0:1]
	s_mov_b32 s0, 0x60000
	v_lshl_add_u64 v[28:29], v[224:225], 0, s[0:1]
	s_mov_b32 s0, 0x4000
	v_lshl_add_u64 v[30:31], v[222:223], 0, s[0:1]
	s_waitcnt lgkmcnt(0)
	v_mfma_f32_32x32x16_bf16 v[82:97], v[218:221], v[4:7], v[66:81]
	v_mfma_f32_32x32x16_bf16 v[98:113], v[214:217], v[4:7], v[66:81]
	v_mfma_f32_32x32x16_bf16 v[82:97], v[210:213], v[8:11], v[82:97]
	v_mfma_f32_32x32x16_bf16 v[98:113], v[206:209], v[8:11], v[98:113]
	v_mfma_f32_32x32x16_bf16 v[82:97], v[202:205], v[12:15], v[82:97]
	v_mfma_f32_32x32x16_bf16 v[98:113], v[198:201], v[12:15], v[98:113]
	v_mfma_f32_32x32x16_bf16 v[82:97], v[194:197], v[130:133], v[82:97]
	v_mfma_f32_32x32x16_bf16 v[98:113], v[190:193], v[130:133], v[98:113]
	v_mfma_f32_32x32x16_bf16 v[82:97], v[186:189], v[134:137], v[82:97]
	v_mfma_f32_32x32x16_bf16 v[98:113], v[182:185], v[134:137], v[98:113]
	v_mfma_f32_32x32x16_bf16 v[82:97], v[178:181], v[138:141], v[82:97]
	v_mfma_f32_32x32x16_bf16 v[98:113], v[174:177], v[138:141], v[98:113]
	v_add_u32_e32 v2, 0x3000, v238
	ds_read_b128 v[218:221], v2
	ds_read_b128 v[214:217], v2 offset:512
	ds_read_b128 v[210:213], v2 offset:2048
	ds_read_b128 v[206:209], v2 offset:2560
	ds_read_b128 v[202:205], v2 offset:4096
	ds_read_b128 v[198:201], v2 offset:4608
	ds_read_b128 v[194:197], v2 offset:6144
	ds_read_b128 v[190:193], v2 offset:6656
	ds_read_b128 v[186:189], v2 offset:8192
	ds_read_b128 v[182:185], v2 offset:8704
	ds_read_b128 v[178:181], v2 offset:10240
	ds_read_b128 v[174:177], v2 offset:10752
	s_nop 7
	v_max3_f32 v19, v82, v83, v84
	v_max3_f32 v26, v85, v86, v87
	v_max3_f32 v19, v19, v88, v89
	v_max3_f32 v26, v26, v90, v91
	v_max3_f32 v19, v19, v92, v93
	v_max3_f32 v26, v26, v94, v95
	v_max3_f32 v19, v19, v96, v97
	v_max3_f32 v26, v26, v98, v99
	v_max3_f32 v19, v19, v100, v101
	v_max3_f32 v26, v26, v102, v103
	v_max3_f32 v19, v19, v104, v105
	v_max3_f32 v26, v26, v106, v107
	v_max3_f32 v19, v19, v108, v109
	v_max3_f32 v26, v26, v110, v111
	v_max3_f32 v19, v19, v112, v113
	v_max_f32_e32 v19, v19, v26
	v_mov_b32_e32 v26, v19
	s_nop 1
	v_permlane32_swap_b32_e32 v19, v26
	v_max_f32_e32 v19, v19, v26
	v_max_f32_e32 v19, v19, v19
	v_mov_b32_e32 v239, v19
	v_xor_b32_e32 v66, 0x80000000, v19
	v_mov_b32_e32 v67, v66
	v_mov_b32_e32 v68, v66
	v_mov_b32_e32 v69, v66
	v_mov_b32_e32 v70, v66
	v_mov_b32_e32 v71, v66
	v_mov_b32_e32 v72, v66
	v_mov_b32_e32 v73, v66
	v_mov_b32_e32 v74, v66
	v_mov_b32_e32 v75, v66
	v_mov_b32_e32 v76, v66
	v_mov_b32_e32 v77, v66
	v_mov_b32_e32 v78, v66
	v_mov_b32_e32 v79, v66
	v_mov_b32_e32 v80, v66
	v_mov_b32_e32 v81, v66
	v_sub_f32_e32 v82, v82, v19
	v_sub_f32_e32 v83, v83, v19
	v_sub_f32_e32 v84, v84, v19
	v_sub_f32_e32 v85, v85, v19
	v_sub_f32_e32 v86, v86, v19
	v_sub_f32_e32 v87, v87, v19
	v_sub_f32_e32 v88, v88, v19
	v_sub_f32_e32 v89, v89, v19
	v_sub_f32_e32 v90, v90, v19
	v_sub_f32_e32 v91, v91, v19
	v_sub_f32_e32 v92, v92, v19
	v_sub_f32_e32 v93, v93, v19
	v_sub_f32_e32 v94, v94, v19
	v_sub_f32_e32 v95, v95, v19
	v_sub_f32_e32 v96, v96, v19
	v_sub_f32_e32 v97, v97, v19
	v_sub_f32_e32 v98, v98, v19
	v_sub_f32_e32 v99, v99, v19
	v_sub_f32_e32 v100, v100, v19
	v_sub_f32_e32 v101, v101, v19
	v_sub_f32_e32 v102, v102, v19
	v_sub_f32_e32 v103, v103, v19
	v_sub_f32_e32 v104, v104, v19
	v_sub_f32_e32 v105, v105, v19
	v_sub_f32_e32 v106, v106, v19
	v_sub_f32_e32 v107, v107, v19
	v_sub_f32_e32 v108, v108, v19
	v_sub_f32_e32 v109, v109, v19
	v_sub_f32_e32 v110, v110, v19
	v_sub_f32_e32 v111, v111, v19
	v_sub_f32_e32 v112, v112, v19
	v_sub_f32_e32 v113, v113, v19
	s_cmp_lt_i32 s79, 1
	s_cbranch_scc1 .Lmy_B_tail
.Lmy_B_loop:
	s_waitcnt lgkmcnt(0)
	v_mov_b32_e32 v2, v237
	v_mfma_f32_32x32x16_bf16 v[142:157], v[218:221], v[4:7], v[66:81]
	v_exp_f32_e32 v82, v82
	v_exp_f32_e32 v83, v83
	v_exp_f32_e32 v84, v84
	v_add_f32_e32 v27, v82, v83
	v_exp_f32_e32 v85, v85
	ds_read_b64_tr_b16 v[114:115], v2 offset:49152
	ds_read_b64_tr_b16 v[116:117], v2 offset:49664
	ds_read_b64_tr_b16 v[118:119], v2 offset:50176
	ds_read_b64_tr_b16 v[120:121], v2 offset:50688
	v_mfma_f32_32x32x16_bf16 v[158:173], v[214:217], v[4:7], v[66:81]
	v_exp_f32_e32 v86, v86
	v_add_f32_e32 v27, v27, v84
	v_exp_f32_e32 v87, v87
	v_add_f32_e32 v27, v27, v85
	v_exp_f32_e32 v88, v88
	ds_read_b64_tr_b16 v[122:123], v2 offset:51200
	ds_read_b64_tr_b16 v[124:125], v2 offset:51712
	ds_read_b64_tr_b16 v[126:127], v2 offset:52224
	ds_read_b64_tr_b16 v[128:129], v2 offset:52736
	v_mfma_f32_32x32x16_bf16 v[142:157], v[210:213], v[8:11], v[142:157]
	v_add_f32_e32 v27, v27, v86
	v_exp_f32_e32 v89, v89
	v_add_f32_e32 v27, v27, v87
	v_add_f32_e32 v27, v27, v88
	v_add_f32_e32 v27, v27, v89
	ds_read_b64_tr_b16 v[240:241], v2 offset:53248
	ds_read_b64_tr_b16 v[242:243], v2 offset:53760
	ds_read_b64_tr_b16 v[244:245], v2 offset:54272
	ds_read_b64_tr_b16 v[246:247], v2 offset:54784
	v_mfma_f32_32x32x16_bf16 v[158:173], v[206:209], v[8:11], v[158:173]
	v_cvt_pk_bf16_f32 v82, v82, v83
	v_cvt_pk_bf16_f32 v83, v84, v85
	v_cvt_pk_bf16_f32 v84, v86, v87
	v_cvt_pk_bf16_f32 v85, v88, v89
	ds_read_b64_tr_b16 v[248:249], v2 offset:55296
	ds_read_b64_tr_b16 v[250:251], v2 offset:55808
	ds_read_b64_tr_b16 v[20:21], v2 offset:56320
	ds_read_b64_tr_b16 v[22:23], v2 offset:56832
	v_mfma_f32_32x32x16_bf16 v[142:157], v[202:205], v[12:15], v[142:157]
	v_exp_f32_e32 v90, v90
	v_exp_f32_e32 v91, v91
	v_exp_f32_e32 v92, v92
	v_add_f32_e32 v27, v27, v90
	v_exp_f32_e32 v93, v93
	v_mfma_f32_32x32x16_bf16 v[158:173], v[198:201], v[12:15], v[158:173]
	v_add_f32_e32 v27, v27, v91
	v_exp_f32_e32 v94, v94
	v_add_f32_e32 v27, v27, v92
	v_exp_f32_e32 v95, v95
	v_add_f32_e32 v27, v27, v93
	s_waitcnt vmcnt(2)
	s_barrier
	v_mfma_f32_32x32x16_bf16 v[142:157], v[194:197], v[130:133], v[142:157]
	s_add_u32 m0, s57, 0x6000
	v_exp_f32_e32 v96, v96
	v_add_f32_e32 v27, v27, v94
	global_load_lds_dwordx4 v[28:29], off
	v_lshl_add_u64 v[28:29], v[28:29], 0, s[30:31]
	v_exp_f32_e32 v97, v97
	v_add_f32_e32 v27, v27, v95
	v_add_f32_e32 v27, v27, v96
	v_mfma_f32_32x32x16_bf16 v[158:173], v[190:193], v[130:133], v[158:173]
	s_add_u32 m0, s40, 0x0
	v_add_f32_e32 v27, v27, v97
	v_cvt_pk_bf16_f32 v90, v90, v91
	global_load_lds_dwordx4 v[24:25], off
	v_lshl_add_u64 v[24:25], v[24:25], 0, s[30:31]
	v_cvt_pk_bf16_f32 v91, v92, v93
	v_cvt_pk_bf16_f32 v92, v94, v95
	v_cvt_pk_bf16_f32 v93, v96, v97
	v_mfma_f32_32x32x16_bf16 v[142:157], v[186:189], v[134:137], v[142:157]
	v_exp_f32_e32 v98, v98
	v_exp_f32_e32 v99, v99
	v_exp_f32_e32 v100, v100
	v_add_f32_e32 v27, v27, v98
	v_exp_f32_e32 v101, v101
	v_mfma_f32_32x32x16_bf16 v[158:173], v[182:185], v[134:137], v[158:173]
	v_add_f32_e32 v27, v27, v99
	v_exp_f32_e32 v102, v102
	v_add_f32_e32 v27, v27, v100
	v_exp_f32_e32 v103, v103
	v_add_f32_e32 v27, v27, v101
	v_mfma_f32_32x32x16_bf16 v[142:157], v[178:181], v[138:141], v[142:157]
	v_exp_f32_e32 v104, v104
	v_add_f32_e32 v27, v27, v102
	v_exp_f32_e32 v105, v105
	v_add_f32_e32 v27, v27, v103
	v_add_f32_e32 v27, v27, v104
	v_mfma_f32_32x32x16_bf16 v[158:173], v[174:177], v[138:141], v[158:173]
	v_add_f32_e32 v27, v27, v105
	v_cvt_pk_bf16_f32 v98, v98, v99
	v_cvt_pk_bf16_f32 v99, v100, v101
	v_cvt_pk_bf16_f32 v100, v102, v103
	v_cvt_pk_bf16_f32 v101, v104, v105
	s_waitcnt lgkmcnt(0)
	v_add_u32_e32 v2, 0x6000, v238
	v_mfma_f32_32x32x16_bf16 v[34:49], v[82:85], v[114:117], v[34:49]
	v_exp_f32_e32 v106, v106
	v_exp_f32_e32 v107, v107
	v_exp_f32_e32 v108, v108
	v_add_f32_e32 v27, v27, v106
	v_exp_f32_e32 v109, v109
	v_add_f32_e32 v27, v27, v107
	v_exp_f32_e32 v110, v110
	v_add_f32_e32 v27, v27, v108
	v_exp_f32_e32 v111, v111
	v_add_f32_e32 v27, v27, v109
	ds_read_b128 v[218:221], v2
	ds_read_b128 v[214:217], v2 offset:512
	ds_read_b128 v[210:213], v2 offset:2048
	v_mfma_f32_32x32x16_bf16 v[50:65], v[82:85], v[240:243], v[50:65]
	v_exp_f32_e32 v112, v112
	v_add_f32_e32 v27, v27, v110
	v_exp_f32_e32 v113, v113
	v_add_f32_e32 v27, v27, v111
	v_add_f32_e32 v27, v27, v112
	v_add_f32_e32 v27, v27, v113
	v_cvt_pk_bf16_f32 v106, v106, v107
	v_cvt_pk_bf16_f32 v107, v108, v109
	v_cvt_pk_bf16_f32 v108, v110, v111
	v_cvt_pk_bf16_f32 v109, v112, v113
	v_add_f32_e32 v236, v236, v27
	ds_read_b128 v[206:209], v2 offset:2560
	ds_read_b128 v[202:205], v2 offset:4096
	ds_read_b128 v[198:201], v2 offset:4608
	v_mfma_f32_32x32x16_bf16 v[34:49], v[90:93], v[118:121], v[34:49]
	ds_read_b128 v[194:197], v2 offset:6144
	ds_read_b128 v[190:193], v2 offset:6656
	ds_read_b128 v[186:189], v2 offset:8192
	v_max3_f32 v19, v142, v143, v144
	v_max3_f32 v26, v145, v146, v147
	v_max3_f32 v19, v19, v148, v149
	v_max3_f32 v26, v26, v150, v151
	v_max3_f32 v19, v19, v152, v153
	v_mfma_f32_32x32x16_bf16 v[50:65], v[90:93], v[244:247], v[50:65]
	ds_read_b128 v[182:185], v2 offset:8704
	ds_read_b128 v[178:181], v2 offset:10240
	ds_read_b128 v[174:177], v2 offset:10752
	v_max3_f32 v26, v26, v154, v155
	v_max3_f32 v19, v19, v156, v157
	v_max3_f32 v26, v26, v158, v159
	v_max3_f32 v19, v19, v160, v161
	v_max3_f32 v26, v26, v162, v163
	v_mfma_f32_32x32x16_bf16 v[34:49], v[98:101], v[122:125], v[34:49]
	v_max3_f32 v19, v19, v164, v165
	v_max3_f32 v26, v26, v166, v167
	v_max3_f32 v19, v19, v168, v169
	v_max3_f32 v26, v26, v170, v171
	v_mfma_f32_32x32x16_bf16 v[50:65], v[98:101], v[248:251], v[50:65]
	v_max3_f32 v19, v19, v172, v173
	v_max_f32_e32 v19, v19, v26
	v_mfma_f32_32x32x16_bf16 v[34:49], v[106:109], v[126:129], v[34:49]
	v_mfma_f32_32x32x16_bf16 v[50:65], v[106:109], v[20:23], v[50:65]
	v_cmp_lt_f32_e32 vcc, s41, v19
	s_cbranch_vccz .Lmy_nors_23
	s_nop 15
	s_nop 15
	v_mov_b32_e32 v26, v19
	s_nop 1
	v_permlane32_swap_b32_e32 v19, v26
	v_max_f32_e32 v19, v19, v26
	v_max_f32_e32 v19, v19, v19
	v_max_f32_e32 v90, 0, v19
	v_exp_f32_e64 v91, -v90
	v_add_f32_e32 v239, v239, v90
	v_xor_b32_e32 v66, 0x80000000, v239
	v_mov_b32_e32 v67, v66
	v_mov_b32_e32 v68, v66
	v_mov_b32_e32 v69, v66
	v_mov_b32_e32 v70, v66
	v_mov_b32_e32 v71, v66
	v_mov_b32_e32 v72, v66
	v_mov_b32_e32 v73, v66
	v_mov_b32_e32 v74, v66
	v_mov_b32_e32 v75, v66
	v_mov_b32_e32 v76, v66
	v_mov_b32_e32 v77, v66
	v_mov_b32_e32 v78, v66
	v_mov_b32_e32 v79, v66
	v_mov_b32_e32 v80, v66
	v_mov_b32_e32 v81, v66
	v_sub_f32_e32 v142, v142, v90
	v_sub_f32_e32 v143, v143, v90
	v_sub_f32_e32 v144, v144, v90
	v_sub_f32_e32 v145, v145, v90
	v_sub_f32_e32 v146, v146, v90
	v_sub_f32_e32 v147, v147, v90
	v_sub_f32_e32 v148, v148, v90
	v_sub_f32_e32 v149, v149, v90
	v_sub_f32_e32 v150, v150, v90
	v_sub_f32_e32 v151, v151, v90
	v_sub_f32_e32 v152, v152, v90
	v_sub_f32_e32 v153, v153, v90
	v_sub_f32_e32 v154, v154, v90
	v_sub_f32_e32 v155, v155, v90
	v_sub_f32_e32 v156, v156, v90
	v_sub_f32_e32 v157, v157, v90
	v_sub_f32_e32 v158, v158, v90
	v_sub_f32_e32 v159, v159, v90
	v_sub_f32_e32 v160, v160, v90
	v_sub_f32_e32 v161, v161, v90
	v_sub_f32_e32 v162, v162, v90
	v_sub_f32_e32 v163, v163, v90
	v_sub_f32_e32 v164, v164, v90
	v_sub_f32_e32 v165, v165, v90
	v_sub_f32_e32 v166, v166, v90
	v_sub_f32_e32 v167, v167, v90
	v_sub_f32_e32 v168, v168, v90
	v_sub_f32_e32 v169, v169, v90
	v_sub_f32_e32 v170, v170, v90
	v_sub_f32_e32 v171, v171, v90
	v_sub_f32_e32 v172, v172, v90
	v_sub_f32_e32 v173, v173, v90
	v_mul_f32_e32 v236, v236, v91
	s_mov_b64 s[96:97], exec
	s_and_b64 exec, exec, s[8:9]
	ds_write_b32 v235, v91
	s_mov_b64 exec, s[96:97]
	v_lshl_add_u32 v2, v228, 4, s47
	ds_read_b128 v[94:97], v2 offset:0
	s_waitcnt lgkmcnt(0)
	v_mul_f32_e32 v34, v34, v94
	v_mul_f32_e32 v50, v50, v94
	v_mul_f32_e32 v35, v35, v95
	v_mul_f32_e32 v51, v51, v95
	v_mul_f32_e32 v36, v36, v96
	v_mul_f32_e32 v52, v52, v96
	v_mul_f32_e32 v37, v37, v97
	v_mul_f32_e32 v53, v53, v97
	ds_read_b128 v[94:97], v2 offset:32
	s_waitcnt lgkmcnt(0)
	v_mul_f32_e32 v38, v38, v94
	v_mul_f32_e32 v54, v54, v94
	v_mul_f32_e32 v39, v39, v95
	v_mul_f32_e32 v55, v55, v95
	v_mul_f32_e32 v40, v40, v96
	v_mul_f32_e32 v56, v56, v96
	v_mul_f32_e32 v41, v41, v97
	v_mul_f32_e32 v57, v57, v97
	ds_read_b128 v[94:97], v2 offset:64
	s_waitcnt lgkmcnt(0)
	v_mul_f32_e32 v42, v42, v94
	v_mul_f32_e32 v58, v58, v94
	v_mul_f32_e32 v43, v43, v95
	v_mul_f32_e32 v59, v59, v95
	v_mul_f32_e32 v44, v44, v96
	v_mul_f32_e32 v60, v60, v96
	v_mul_f32_e32 v45, v45, v97
	v_mul_f32_e32 v61, v61, v97
	ds_read_b128 v[94:97], v2 offset:96
	s_waitcnt lgkmcnt(0)
	v_mul_f32_e32 v46, v46, v94
	v_mul_f32_e32 v62, v62, v94
	v_mul_f32_e32 v47, v47, v95
	v_mul_f32_e32 v63, v63, v95
	v_mul_f32_e32 v48, v48, v96
	v_mul_f32_e32 v64, v64, v96
	v_mul_f32_e32 v49, v49, v97
	v_mul_f32_e32 v65, v65, v97
.Lmy_nors_23:
	s_waitcnt lgkmcnt(0)
	v_add_u32_e32 v2, 0x2000, v237
	v_mfma_f32_32x32x16_bf16 v[82:97], v[218:221], v[4:7], v[66:81]
	v_exp_f32_e32 v142, v142
	v_exp_f32_e32 v143, v143
	v_exp_f32_e32 v144, v144
	v_add_f32_e32 v27, v142, v143
	v_exp_f32_e32 v145, v145
	ds_read_b64_tr_b16 v[114:115], v2 offset:49152
	ds_read_b64_tr_b16 v[116:117], v2 offset:49664
	ds_read_b64_tr_b16 v[118:119], v2 offset:50176
	ds_read_b64_tr_b16 v[120:121], v2 offset:50688
	v_mfma_f32_32x32x16_bf16 v[98:113], v[214:217], v[4:7], v[66:81]
	v_exp_f32_e32 v146, v146
	v_add_f32_e32 v27, v27, v144
	v_exp_f32_e32 v147, v147
	v_add_f32_e32 v27, v27, v145
	v_exp_f32_e32 v148, v148
	ds_read_b64_tr_b16 v[122:123], v2 offset:51200
	ds_read_b64_tr_b16 v[124:125], v2 offset:51712
	ds_read_b64_tr_b16 v[126:127], v2 offset:52224
	ds_read_b64_tr_b16 v[128:129], v2 offset:52736
	v_mfma_f32_32x32x16_bf16 v[82:97], v[210:213], v[8:11], v[82:97]
	v_add_f32_e32 v27, v27, v146
	v_exp_f32_e32 v149, v149
	v_add_f32_e32 v27, v27, v147
	v_add_f32_e32 v27, v27, v148
	v_add_f32_e32 v27, v27, v149
	ds_read_b64_tr_b16 v[240:241], v2 offset:53248
	ds_read_b64_tr_b16 v[242:243], v2 offset:53760
	ds_read_b64_tr_b16 v[244:245], v2 offset:54272
	ds_read_b64_tr_b16 v[246:247], v2 offset:54784
	v_mfma_f32_32x32x16_bf16 v[98:113], v[206:209], v[8:11], v[98:113]
	v_cvt_pk_bf16_f32 v142, v142, v143
	v_cvt_pk_bf16_f32 v143, v144, v145
	v_cvt_pk_bf16_f32 v144, v146, v147
	v_cvt_pk_bf16_f32 v145, v148, v149
	ds_read_b64_tr_b16 v[248:249], v2 offset:55296
	ds_read_b64_tr_b16 v[250:251], v2 offset:55808
	ds_read_b64_tr_b16 v[20:21], v2 offset:56320
	ds_read_b64_tr_b16 v[22:23], v2 offset:56832
	v_mfma_f32_32x32x16_bf16 v[82:97], v[202:205], v[12:15], v[82:97]
	v_exp_f32_e32 v150, v150
	v_exp_f32_e32 v151, v151
	v_exp_f32_e32 v152, v152
	v_add_f32_e32 v27, v27, v150
	v_exp_f32_e32 v153, v153
	v_mfma_f32_32x32x16_bf16 v[98:113], v[198:201], v[12:15], v[98:113]
	v_add_f32_e32 v27, v27, v151
	v_exp_f32_e32 v154, v154
	v_add_f32_e32 v27, v27, v152
	v_exp_f32_e32 v155, v155
	v_add_f32_e32 v27, v27, v153
	s_waitcnt vmcnt(2)
	s_barrier
	v_mfma_f32_32x32x16_bf16 v[82:97], v[194:197], v[130:133], v[82:97]
	s_add_u32 m0, s57, 0x0
	v_exp_f32_e32 v156, v156
	v_add_f32_e32 v27, v27, v154
	global_load_lds_dwordx4 v[28:29], off
	v_lshl_add_u64 v[28:29], v[28:29], 0, s[30:31]
	v_exp_f32_e32 v157, v157
	v_add_f32_e32 v27, v27, v155
	v_add_f32_e32 v27, v27, v156
	v_mfma_f32_32x32x16_bf16 v[98:113], v[190:193], v[130:133], v[98:113]
	s_add_u32 m0, s40, 0x3000
	v_add_f32_e32 v27, v27, v157
	v_cvt_pk_bf16_f32 v150, v150, v151
	global_load_lds_dwordx4 v[24:25], off
	v_lshl_add_u64 v[24:25], v[24:25], 0, s[30:31]
	v_cvt_pk_bf16_f32 v151, v152, v153
	v_cvt_pk_bf16_f32 v152, v154, v155
	v_cvt_pk_bf16_f32 v153, v156, v157
	v_mfma_f32_32x32x16_bf16 v[82:97], v[186:189], v[134:137], v[82:97]
	v_exp_f32_e32 v158, v158
	v_exp_f32_e32 v159, v159
	v_exp_f32_e32 v160, v160
	v_add_f32_e32 v27, v27, v158
	v_exp_f32_e32 v161, v161
	v_mfma_f32_32x32x16_bf16 v[98:113], v[182:185], v[134:137], v[98:113]
	v_add_f32_e32 v27, v27, v159
	v_exp_f32_e32 v162, v162
	v_add_f32_e32 v27, v27, v160
	v_exp_f32_e32 v163, v163
	v_add_f32_e32 v27, v27, v161
	v_mfma_f32_32x32x16_bf16 v[82:97], v[178:181], v[138:141], v[82:97]
	v_exp_f32_e32 v164, v164
	v_add_f32_e32 v27, v27, v162
	v_exp_f32_e32 v165, v165
	v_add_f32_e32 v27, v27, v163
	v_add_f32_e32 v27, v27, v164
	v_mfma_f32_32x32x16_bf16 v[98:113], v[174:177], v[138:141], v[98:113]
	v_add_f32_e32 v27, v27, v165
	v_cvt_pk_bf16_f32 v158, v158, v159
	v_cvt_pk_bf16_f32 v159, v160, v161
	v_cvt_pk_bf16_f32 v160, v162, v163
	v_cvt_pk_bf16_f32 v161, v164, v165
	s_waitcnt lgkmcnt(0)
	v_add_u32_e32 v2, 0x9000, v238
	v_mfma_f32_32x32x16_bf16 v[34:49], v[142:145], v[114:117], v[34:49]
	v_exp_f32_e32 v166, v166
	v_exp_f32_e32 v167, v167
	v_exp_f32_e32 v168, v168
	v_add_f32_e32 v27, v27, v166
	v_exp_f32_e32 v169, v169
	v_add_f32_e32 v27, v27, v167
	v_exp_f32_e32 v170, v170
	v_add_f32_e32 v27, v27, v168
	v_exp_f32_e32 v171, v171
	v_add_f32_e32 v27, v27, v169
	ds_read_b128 v[218:221], v2
	ds_read_b128 v[214:217], v2 offset:512
	ds_read_b128 v[210:213], v2 offset:2048
	v_mfma_f32_32x32x16_bf16 v[50:65], v[142:145], v[240:243], v[50:65]
	v_exp_f32_e32 v172, v172
	v_add_f32_e32 v27, v27, v170
	v_exp_f32_e32 v173, v173
	v_add_f32_e32 v27, v27, v171
	v_add_f32_e32 v27, v27, v172
	v_add_f32_e32 v27, v27, v173
	v_cvt_pk_bf16_f32 v166, v166, v167
	v_cvt_pk_bf16_f32 v167, v168, v169
	v_cvt_pk_bf16_f32 v168, v170, v171
	v_cvt_pk_bf16_f32 v169, v172, v173
	v_add_f32_e32 v236, v236, v27
	ds_read_b128 v[206:209], v2 offset:2560
	ds_read_b128 v[202:205], v2 offset:4096
	ds_read_b128 v[198:201], v2 offset:4608
	v_mfma_f32_32x32x16_bf16 v[34:49], v[150:153], v[118:121], v[34:49]
	ds_read_b128 v[194:197], v2 offset:6144
	ds_read_b128 v[190:193], v2 offset:6656
	ds_read_b128 v[186:189], v2 offset:8192
	v_max3_f32 v19, v82, v83, v84
	v_max3_f32 v26, v85, v86, v87
	v_max3_f32 v19, v19, v88, v89
	v_max3_f32 v26, v26, v90, v91
	v_max3_f32 v19, v19, v92, v93
	v_mfma_f32_32x32x16_bf16 v[50:65], v[150:153], v[244:247], v[50:65]
	ds_read_b128 v[182:185], v2 offset:8704
	ds_read_b128 v[178:181], v2 offset:10240
	ds_read_b128 v[174:177], v2 offset:10752
	v_max3_f32 v26, v26, v94, v95
	v_max3_f32 v19, v19, v96, v97
	v_max3_f32 v26, v26, v98, v99
	v_max3_f32 v19, v19, v100, v101
	v_max3_f32 v26, v26, v102, v103
	v_mfma_f32_32x32x16_bf16 v[34:49], v[158:161], v[122:125], v[34:49]
	v_max3_f32 v19, v19, v104, v105
	v_max3_f32 v26, v26, v106, v107
	v_max3_f32 v19, v19, v108, v109
	v_max3_f32 v26, v26, v110, v111
	v_mfma_f32_32x32x16_bf16 v[50:65], v[158:161], v[248:251], v[50:65]
	v_max3_f32 v19, v19, v112, v113
	v_max_f32_e32 v19, v19, v26
	v_mfma_f32_32x32x16_bf16 v[34:49], v[166:169], v[126:129], v[34:49]
	v_mfma_f32_32x32x16_bf16 v[50:65], v[166:169], v[20:23], v[50:65]
	v_cmp_lt_f32_e32 vcc, s41, v19
	s_cbranch_vccz .Lmy_nors_24
	s_nop 15
	s_nop 15
	v_mov_b32_e32 v26, v19
	s_nop 1
	v_permlane32_swap_b32_e32 v19, v26
	v_max_f32_e32 v19, v19, v26
	v_max_f32_e32 v19, v19, v19
	v_max_f32_e32 v150, 0, v19
	v_exp_f32_e64 v151, -v150
	v_add_f32_e32 v239, v239, v150
	v_xor_b32_e32 v66, 0x80000000, v239
	v_mov_b32_e32 v67, v66
	v_mov_b32_e32 v68, v66
	v_mov_b32_e32 v69, v66
	v_mov_b32_e32 v70, v66
	v_mov_b32_e32 v71, v66
	v_mov_b32_e32 v72, v66
	v_mov_b32_e32 v73, v66
	v_mov_b32_e32 v74, v66
	v_mov_b32_e32 v75, v66
	v_mov_b32_e32 v76, v66
	v_mov_b32_e32 v77, v66
	v_mov_b32_e32 v78, v66
	v_mov_b32_e32 v79, v66
	v_mov_b32_e32 v80, v66
	v_mov_b32_e32 v81, v66
	v_sub_f32_e32 v82, v82, v150
	v_sub_f32_e32 v83, v83, v150
	v_sub_f32_e32 v84, v84, v150
	v_sub_f32_e32 v85, v85, v150
	v_sub_f32_e32 v86, v86, v150
	v_sub_f32_e32 v87, v87, v150
	v_sub_f32_e32 v88, v88, v150
	v_sub_f32_e32 v89, v89, v150
	v_sub_f32_e32 v90, v90, v150
	v_sub_f32_e32 v91, v91, v150
	v_sub_f32_e32 v92, v92, v150
	v_sub_f32_e32 v93, v93, v150
	v_sub_f32_e32 v94, v94, v150
	v_sub_f32_e32 v95, v95, v150
	v_sub_f32_e32 v96, v96, v150
	v_sub_f32_e32 v97, v97, v150
	v_sub_f32_e32 v98, v98, v150
	v_sub_f32_e32 v99, v99, v150
	v_sub_f32_e32 v100, v100, v150
	v_sub_f32_e32 v101, v101, v150
	v_sub_f32_e32 v102, v102, v150
	v_sub_f32_e32 v103, v103, v150
	v_sub_f32_e32 v104, v104, v150
	v_sub_f32_e32 v105, v105, v150
	v_sub_f32_e32 v106, v106, v150
	v_sub_f32_e32 v107, v107, v150
	v_sub_f32_e32 v108, v108, v150
	v_sub_f32_e32 v109, v109, v150
	v_sub_f32_e32 v110, v110, v150
	v_sub_f32_e32 v111, v111, v150
	v_sub_f32_e32 v112, v112, v150
	v_sub_f32_e32 v113, v113, v150
	v_mul_f32_e32 v236, v236, v151
	s_mov_b64 s[96:97], exec
	s_and_b64 exec, exec, s[8:9]
	ds_write_b32 v235, v151
	s_mov_b64 exec, s[96:97]
	v_lshl_add_u32 v2, v228, 4, s47
	ds_read_b128 v[154:157], v2 offset:0
	s_waitcnt lgkmcnt(0)
	v_mul_f32_e32 v34, v34, v154
	v_mul_f32_e32 v50, v50, v154
	v_mul_f32_e32 v35, v35, v155
	v_mul_f32_e32 v51, v51, v155
	v_mul_f32_e32 v36, v36, v156
	v_mul_f32_e32 v52, v52, v156
	v_mul_f32_e32 v37, v37, v157
	v_mul_f32_e32 v53, v53, v157
	ds_read_b128 v[154:157], v2 offset:32
	s_waitcnt lgkmcnt(0)
	v_mul_f32_e32 v38, v38, v154
	v_mul_f32_e32 v54, v54, v154
	v_mul_f32_e32 v39, v39, v155
	v_mul_f32_e32 v55, v55, v155
	v_mul_f32_e32 v40, v40, v156
	v_mul_f32_e32 v56, v56, v156
	v_mul_f32_e32 v41, v41, v157
	v_mul_f32_e32 v57, v57, v157
	ds_read_b128 v[154:157], v2 offset:64
	s_waitcnt lgkmcnt(0)
	v_mul_f32_e32 v42, v42, v154
	v_mul_f32_e32 v58, v58, v154
	v_mul_f32_e32 v43, v43, v155
	v_mul_f32_e32 v59, v59, v155
	v_mul_f32_e32 v44, v44, v156
	v_mul_f32_e32 v60, v60, v156
	v_mul_f32_e32 v45, v45, v157
	v_mul_f32_e32 v61, v61, v157
	ds_read_b128 v[154:157], v2 offset:96
	s_waitcnt lgkmcnt(0)
	v_mul_f32_e32 v46, v46, v154
	v_mul_f32_e32 v62, v62, v154
	v_mul_f32_e32 v47, v47, v155
	v_mul_f32_e32 v63, v63, v155
	v_mul_f32_e32 v48, v48, v156
	v_mul_f32_e32 v64, v64, v156
	v_mul_f32_e32 v49, v49, v157
	v_mul_f32_e32 v65, v65, v157
.Lmy_nors_24:
	s_waitcnt lgkmcnt(0)
	v_add_u32_e32 v2, 0x4000, v237
	v_mfma_f32_32x32x16_bf16 v[142:157], v[218:221], v[4:7], v[66:81]
	v_exp_f32_e32 v82, v82
	v_exp_f32_e32 v83, v83
	v_exp_f32_e32 v84, v84
	v_add_f32_e32 v27, v82, v83
	v_exp_f32_e32 v85, v85
	ds_read_b64_tr_b16 v[114:115], v2 offset:49152
	ds_read_b64_tr_b16 v[116:117], v2 offset:49664
	ds_read_b64_tr_b16 v[118:119], v2 offset:50176
	ds_read_b64_tr_b16 v[120:121], v2 offset:50688
	v_mfma_f32_32x32x16_bf16 v[158:173], v[214:217], v[4:7], v[66:81]
	v_exp_f32_e32 v86, v86
	v_add_f32_e32 v27, v27, v84
	v_exp_f32_e32 v87, v87
	v_add_f32_e32 v27, v27, v85
	v_exp_f32_e32 v88, v88
	ds_read_b64_tr_b16 v[122:123], v2 offset:51200
	ds_read_b64_tr_b16 v[124:125], v2 offset:51712
	ds_read_b64_tr_b16 v[126:127], v2 offset:52224
	ds_read_b64_tr_b16 v[128:129], v2 offset:52736
	v_mfma_f32_32x32x16_bf16 v[142:157], v[210:213], v[8:11], v[142:157]
	v_add_f32_e32 v27, v27, v86
	v_exp_f32_e32 v89, v89
	v_add_f32_e32 v27, v27, v87
	v_add_f32_e32 v27, v27, v88
	v_add_f32_e32 v27, v27, v89
	ds_read_b64_tr_b16 v[240:241], v2 offset:53248
	ds_read_b64_tr_b16 v[242:243], v2 offset:53760
	ds_read_b64_tr_b16 v[244:245], v2 offset:54272
	ds_read_b64_tr_b16 v[246:247], v2 offset:54784
	v_mfma_f32_32x32x16_bf16 v[158:173], v[206:209], v[8:11], v[158:173]
	v_cvt_pk_bf16_f32 v82, v82, v83
	v_cvt_pk_bf16_f32 v83, v84, v85
	v_cvt_pk_bf16_f32 v84, v86, v87
	v_cvt_pk_bf16_f32 v85, v88, v89
	ds_read_b64_tr_b16 v[248:249], v2 offset:55296
	ds_read_b64_tr_b16 v[250:251], v2 offset:55808
	ds_read_b64_tr_b16 v[20:21], v2 offset:56320
	ds_read_b64_tr_b16 v[22:23], v2 offset:56832
	v_mfma_f32_32x32x16_bf16 v[142:157], v[202:205], v[12:15], v[142:157]
	v_exp_f32_e32 v90, v90
	v_exp_f32_e32 v91, v91
	v_exp_f32_e32 v92, v92
	v_add_f32_e32 v27, v27, v90
	v_exp_f32_e32 v93, v93
	v_mfma_f32_32x32x16_bf16 v[158:173], v[198:201], v[12:15], v[158:173]
	v_add_f32_e32 v27, v27, v91
	v_exp_f32_e32 v94, v94
	v_add_f32_e32 v27, v27, v92
	v_exp_f32_e32 v95, v95
	v_add_f32_e32 v27, v27, v93
	s_waitcnt vmcnt(2)
	s_barrier
	v_mfma_f32_32x32x16_bf16 v[142:157], v[194:197], v[130:133], v[142:157]
	s_add_u32 m0, s57, 0x2000
	v_exp_f32_e32 v96, v96
	v_add_f32_e32 v27, v27, v94
	global_load_lds_dwordx4 v[28:29], off
	v_lshl_add_u64 v[28:29], v[28:29], 0, s[30:31]
	v_exp_f32_e32 v97, v97
	v_add_f32_e32 v27, v27, v95
	v_add_f32_e32 v27, v27, v96
	v_mfma_f32_32x32x16_bf16 v[158:173], v[190:193], v[130:133], v[158:173]
	s_add_u32 m0, s40, 0x6000
	v_add_f32_e32 v27, v27, v97
	v_cvt_pk_bf16_f32 v90, v90, v91
	global_load_lds_dwordx4 v[24:25], off
	v_lshl_add_u64 v[24:25], v[24:25], 0, s[30:31]
	v_cvt_pk_bf16_f32 v91, v92, v93
	v_cvt_pk_bf16_f32 v92, v94, v95
	v_cvt_pk_bf16_f32 v93, v96, v97
	v_mfma_f32_32x32x16_bf16 v[142:157], v[186:189], v[134:137], v[142:157]
	v_exp_f32_e32 v98, v98
	v_exp_f32_e32 v99, v99
	v_exp_f32_e32 v100, v100
	v_add_f32_e32 v27, v27, v98
	v_exp_f32_e32 v101, v101
	v_mfma_f32_32x32x16_bf16 v[158:173], v[182:185], v[134:137], v[158:173]
	v_add_f32_e32 v27, v27, v99
	v_exp_f32_e32 v102, v102
	v_add_f32_e32 v27, v27, v100
	v_exp_f32_e32 v103, v103
	v_add_f32_e32 v27, v27, v101
	v_mfma_f32_32x32x16_bf16 v[142:157], v[178:181], v[138:141], v[142:157]
	v_exp_f32_e32 v104, v104
	v_add_f32_e32 v27, v27, v102
	v_exp_f32_e32 v105, v105
	v_add_f32_e32 v27, v27, v103
	v_add_f32_e32 v27, v27, v104
	v_mfma_f32_32x32x16_bf16 v[158:173], v[174:177], v[138:141], v[158:173]
	v_add_f32_e32 v27, v27, v105
	v_cvt_pk_bf16_f32 v98, v98, v99
	v_cvt_pk_bf16_f32 v99, v100, v101
	v_cvt_pk_bf16_f32 v100, v102, v103
	v_cvt_pk_bf16_f32 v101, v104, v105
	s_waitcnt lgkmcnt(0)
	v_mov_b32_e32 v2, v238
	v_mfma_f32_32x32x16_bf16 v[34:49], v[82:85], v[114:117], v[34:49]
	v_exp_f32_e32 v106, v106
	v_exp_f32_e32 v107, v107
	v_exp_f32_e32 v108, v108
	v_add_f32_e32 v27, v27, v106
	v_exp_f32_e32 v109, v109
	v_add_f32_e32 v27, v27, v107
	v_exp_f32_e32 v110, v110
	v_add_f32_e32 v27, v27, v108
	v_exp_f32_e32 v111, v111
	v_add_f32_e32 v27, v27, v109
	ds_read_b128 v[218:221], v2
	ds_read_b128 v[214:217], v2 offset:512
	ds_read_b128 v[210:213], v2 offset:2048
	v_mfma_f32_32x32x16_bf16 v[50:65], v[82:85], v[240:243], v[50:65]
	v_exp_f32_e32 v112, v112
	v_add_f32_e32 v27, v27, v110
	v_exp_f32_e32 v113, v113
	v_add_f32_e32 v27, v27, v111
	v_add_f32_e32 v27, v27, v112
	v_add_f32_e32 v27, v27, v113
	v_cvt_pk_bf16_f32 v106, v106, v107
	v_cvt_pk_bf16_f32 v107, v108, v109
	v_cvt_pk_bf16_f32 v108, v110, v111
	v_cvt_pk_bf16_f32 v109, v112, v113
	v_add_f32_e32 v236, v236, v27
	ds_read_b128 v[206:209], v2 offset:2560
	ds_read_b128 v[202:205], v2 offset:4096
	ds_read_b128 v[198:201], v2 offset:4608
	v_mfma_f32_32x32x16_bf16 v[34:49], v[90:93], v[118:121], v[34:49]
	ds_read_b128 v[194:197], v2 offset:6144
	ds_read_b128 v[190:193], v2 offset:6656
	ds_read_b128 v[186:189], v2 offset:8192
	v_max3_f32 v19, v142, v143, v144
	v_max3_f32 v26, v145, v146, v147
	v_max3_f32 v19, v19, v148, v149
	v_max3_f32 v26, v26, v150, v151
	v_max3_f32 v19, v19, v152, v153
	v_mfma_f32_32x32x16_bf16 v[50:65], v[90:93], v[244:247], v[50:65]
	ds_read_b128 v[182:185], v2 offset:8704
	ds_read_b128 v[178:181], v2 offset:10240
	ds_read_b128 v[174:177], v2 offset:10752
	v_max3_f32 v26, v26, v154, v155
	v_max3_f32 v19, v19, v156, v157
	v_max3_f32 v26, v26, v158, v159
	v_max3_f32 v19, v19, v160, v161
	v_max3_f32 v26, v26, v162, v163
	v_mfma_f32_32x32x16_bf16 v[34:49], v[98:101], v[122:125], v[34:49]
	v_max3_f32 v19, v19, v164, v165
	v_max3_f32 v26, v26, v166, v167
	v_max3_f32 v19, v19, v168, v169
	v_max3_f32 v26, v26, v170, v171
	v_mfma_f32_32x32x16_bf16 v[50:65], v[98:101], v[248:251], v[50:65]
	v_max3_f32 v19, v19, v172, v173
	v_max_f32_e32 v19, v19, v26
	v_mfma_f32_32x32x16_bf16 v[34:49], v[106:109], v[126:129], v[34:49]
	v_mfma_f32_32x32x16_bf16 v[50:65], v[106:109], v[20:23], v[50:65]
	v_cmp_lt_f32_e32 vcc, s41, v19
	s_cbranch_vccz .Lmy_nors_25
	s_nop 15
	s_nop 15
	v_mov_b32_e32 v26, v19
	s_nop 1
	v_permlane32_swap_b32_e32 v19, v26
	v_max_f32_e32 v19, v19, v26
	v_max_f32_e32 v19, v19, v19
	v_max_f32_e32 v90, 0, v19
	v_exp_f32_e64 v91, -v90
	v_add_f32_e32 v239, v239, v90
	v_xor_b32_e32 v66, 0x80000000, v239
	v_mov_b32_e32 v67, v66
	v_mov_b32_e32 v68, v66
	v_mov_b32_e32 v69, v66
	v_mov_b32_e32 v70, v66
	v_mov_b32_e32 v71, v66
	v_mov_b32_e32 v72, v66
	v_mov_b32_e32 v73, v66
	v_mov_b32_e32 v74, v66
	v_mov_b32_e32 v75, v66
	v_mov_b32_e32 v76, v66
	v_mov_b32_e32 v77, v66
	v_mov_b32_e32 v78, v66
	v_mov_b32_e32 v79, v66
	v_mov_b32_e32 v80, v66
	v_mov_b32_e32 v81, v66
	v_sub_f32_e32 v142, v142, v90
	v_sub_f32_e32 v143, v143, v90
	v_sub_f32_e32 v144, v144, v90
	v_sub_f32_e32 v145, v145, v90
	v_sub_f32_e32 v146, v146, v90
	v_sub_f32_e32 v147, v147, v90
	v_sub_f32_e32 v148, v148, v90
	v_sub_f32_e32 v149, v149, v90
	v_sub_f32_e32 v150, v150, v90
	v_sub_f32_e32 v151, v151, v90
	v_sub_f32_e32 v152, v152, v90
	v_sub_f32_e32 v153, v153, v90
	v_sub_f32_e32 v154, v154, v90
	v_sub_f32_e32 v155, v155, v90
	v_sub_f32_e32 v156, v156, v90
	v_sub_f32_e32 v157, v157, v90
	v_sub_f32_e32 v158, v158, v90
	v_sub_f32_e32 v159, v159, v90
	v_sub_f32_e32 v160, v160, v90
	v_sub_f32_e32 v161, v161, v90
	v_sub_f32_e32 v162, v162, v90
	v_sub_f32_e32 v163, v163, v90
	v_sub_f32_e32 v164, v164, v90
	v_sub_f32_e32 v165, v165, v90
	v_sub_f32_e32 v166, v166, v90
	v_sub_f32_e32 v167, v167, v90
	v_sub_f32_e32 v168, v168, v90
	v_sub_f32_e32 v169, v169, v90
	v_sub_f32_e32 v170, v170, v90
	v_sub_f32_e32 v171, v171, v90
	v_sub_f32_e32 v172, v172, v90
	v_sub_f32_e32 v173, v173, v90
	v_mul_f32_e32 v236, v236, v91
	s_mov_b64 s[96:97], exec
	s_and_b64 exec, exec, s[8:9]
	ds_write_b32 v235, v91
	s_mov_b64 exec, s[96:97]
	v_lshl_add_u32 v2, v228, 4, s47
	ds_read_b128 v[94:97], v2 offset:0
	s_waitcnt lgkmcnt(0)
	v_mul_f32_e32 v34, v34, v94
	v_mul_f32_e32 v50, v50, v94
	v_mul_f32_e32 v35, v35, v95
	v_mul_f32_e32 v51, v51, v95
	v_mul_f32_e32 v36, v36, v96
	v_mul_f32_e32 v52, v52, v96
	v_mul_f32_e32 v37, v37, v97
	v_mul_f32_e32 v53, v53, v97
	ds_read_b128 v[94:97], v2 offset:32
	s_waitcnt lgkmcnt(0)
	v_mul_f32_e32 v38, v38, v94
	v_mul_f32_e32 v54, v54, v94
	v_mul_f32_e32 v39, v39, v95
	v_mul_f32_e32 v55, v55, v95
	v_mul_f32_e32 v40, v40, v96
	v_mul_f32_e32 v56, v56, v96
	v_mul_f32_e32 v41, v41, v97
	v_mul_f32_e32 v57, v57, v97
	ds_read_b128 v[94:97], v2 offset:64
	s_waitcnt lgkmcnt(0)
	v_mul_f32_e32 v42, v42, v94
	v_mul_f32_e32 v58, v58, v94
	v_mul_f32_e32 v43, v43, v95
	v_mul_f32_e32 v59, v59, v95
	v_mul_f32_e32 v44, v44, v96
	v_mul_f32_e32 v60, v60, v96
	v_mul_f32_e32 v45, v45, v97
	v_mul_f32_e32 v61, v61, v97
	ds_read_b128 v[94:97], v2 offset:96
	s_waitcnt lgkmcnt(0)
	v_mul_f32_e32 v46, v46, v94
	v_mul_f32_e32 v62, v62, v94
	v_mul_f32_e32 v47, v47, v95
	v_mul_f32_e32 v63, v63, v95
	v_mul_f32_e32 v48, v48, v96
	v_mul_f32_e32 v64, v64, v96
	v_mul_f32_e32 v49, v49, v97
	v_mul_f32_e32 v65, v65, v97
.Lmy_nors_25:
	s_waitcnt lgkmcnt(0)
	v_add_u32_e32 v2, 0x6000, v237
	v_mfma_f32_32x32x16_bf16 v[82:97], v[218:221], v[4:7], v[66:81]
	v_exp_f32_e32 v142, v142
	v_exp_f32_e32 v143, v143
	v_exp_f32_e32 v144, v144
	v_add_f32_e32 v27, v142, v143
	v_exp_f32_e32 v145, v145
	ds_read_b64_tr_b16 v[114:115], v2 offset:49152
	ds_read_b64_tr_b16 v[116:117], v2 offset:49664
	ds_read_b64_tr_b16 v[118:119], v2 offset:50176
	ds_read_b64_tr_b16 v[120:121], v2 offset:50688
	v_mfma_f32_32x32x16_bf16 v[98:113], v[214:217], v[4:7], v[66:81]
	v_exp_f32_e32 v146, v146
	v_add_f32_e32 v27, v27, v144
	v_exp_f32_e32 v147, v147
	v_add_f32_e32 v27, v27, v145
	v_exp_f32_e32 v148, v148
	ds_read_b64_tr_b16 v[122:123], v2 offset:51200
	ds_read_b64_tr_b16 v[124:125], v2 offset:51712
	ds_read_b64_tr_b16 v[126:127], v2 offset:52224
	ds_read_b64_tr_b16 v[128:129], v2 offset:52736
	v_mfma_f32_32x32x16_bf16 v[82:97], v[210:213], v[8:11], v[82:97]
	v_add_f32_e32 v27, v27, v146
	v_exp_f32_e32 v149, v149
	v_add_f32_e32 v27, v27, v147
	v_add_f32_e32 v27, v27, v148
	v_add_f32_e32 v27, v27, v149
	ds_read_b64_tr_b16 v[240:241], v2 offset:53248
	ds_read_b64_tr_b16 v[242:243], v2 offset:53760
	ds_read_b64_tr_b16 v[244:245], v2 offset:54272
	ds_read_b64_tr_b16 v[246:247], v2 offset:54784
	v_mfma_f32_32x32x16_bf16 v[98:113], v[206:209], v[8:11], v[98:113]
	v_cvt_pk_bf16_f32 v142, v142, v143
	v_cvt_pk_bf16_f32 v143, v144, v145
	v_cvt_pk_bf16_f32 v144, v146, v147
	v_cvt_pk_bf16_f32 v145, v148, v149
	ds_read_b64_tr_b16 v[248:249], v2 offset:55296
	ds_read_b64_tr_b16 v[250:251], v2 offset:55808
	ds_read_b64_tr_b16 v[20:21], v2 offset:56320
	ds_read_b64_tr_b16 v[22:23], v2 offset:56832
	v_mfma_f32_32x32x16_bf16 v[82:97], v[202:205], v[12:15], v[82:97]
	v_exp_f32_e32 v150, v150
	v_exp_f32_e32 v151, v151
	v_exp_f32_e32 v152, v152
	v_add_f32_e32 v27, v27, v150
	v_exp_f32_e32 v153, v153
	v_mfma_f32_32x32x16_bf16 v[98:113], v[198:201], v[12:15], v[98:113]
	v_add_f32_e32 v27, v27, v151
	v_exp_f32_e32 v154, v154
	v_add_f32_e32 v27, v27, v152
	v_exp_f32_e32 v155, v155
	v_add_f32_e32 v27, v27, v153
	s_waitcnt vmcnt(2)
	s_barrier
	v_mfma_f32_32x32x16_bf16 v[82:97], v[194:197], v[130:133], v[82:97]
	s_add_u32 m0, s57, 0x4000
	v_exp_f32_e32 v156, v156
	v_add_f32_e32 v27, v27, v154
	global_load_lds_dwordx4 v[28:29], off
	v_lshl_add_u64 v[28:29], v[28:29], 0, s[30:31]
	v_exp_f32_e32 v157, v157
	v_add_f32_e32 v27, v27, v155
	v_add_f32_e32 v27, v27, v156
	v_mfma_f32_32x32x16_bf16 v[98:113], v[190:193], v[130:133], v[98:113]
	s_add_u32 m0, s40, 0x9000
	v_add_f32_e32 v27, v27, v157
	v_cvt_pk_bf16_f32 v150, v150, v151
	global_load_lds_dwordx4 v[24:25], off
	v_lshl_add_u64 v[24:25], v[24:25], 0, s[30:31]
	v_cvt_pk_bf16_f32 v151, v152, v153
	v_cvt_pk_bf16_f32 v152, v154, v155
	v_cvt_pk_bf16_f32 v153, v156, v157
	v_mfma_f32_32x32x16_bf16 v[82:97], v[186:189], v[134:137], v[82:97]
	v_exp_f32_e32 v158, v158
	v_exp_f32_e32 v159, v159
	v_exp_f32_e32 v160, v160
	v_add_f32_e32 v27, v27, v158
	v_exp_f32_e32 v161, v161
	v_mfma_f32_32x32x16_bf16 v[98:113], v[182:185], v[134:137], v[98:113]
	v_add_f32_e32 v27, v27, v159
	v_exp_f32_e32 v162, v162
	v_add_f32_e32 v27, v27, v160
	v_exp_f32_e32 v163, v163
	v_add_f32_e32 v27, v27, v161
	v_mfma_f32_32x32x16_bf16 v[82:97], v[178:181], v[138:141], v[82:97]
	v_exp_f32_e32 v164, v164
	v_add_f32_e32 v27, v27, v162
	v_exp_f32_e32 v165, v165
	v_add_f32_e32 v27, v27, v163
	v_add_f32_e32 v27, v27, v164
	v_mfma_f32_32x32x16_bf16 v[98:113], v[174:177], v[138:141], v[98:113]
	v_add_f32_e32 v27, v27, v165
	v_cvt_pk_bf16_f32 v158, v158, v159
	v_cvt_pk_bf16_f32 v159, v160, v161
	v_cvt_pk_bf16_f32 v160, v162, v163
	v_cvt_pk_bf16_f32 v161, v164, v165
	s_waitcnt lgkmcnt(0)
	v_add_u32_e32 v2, 0x3000, v238
	v_mfma_f32_32x32x16_bf16 v[34:49], v[142:145], v[114:117], v[34:49]
	v_exp_f32_e32 v166, v166
	v_exp_f32_e32 v167, v167
	v_exp_f32_e32 v168, v168
	v_add_f32_e32 v27, v27, v166
	v_exp_f32_e32 v169, v169
	v_add_f32_e32 v27, v27, v167
	v_exp_f32_e32 v170, v170
	v_add_f32_e32 v27, v27, v168
	v_exp_f32_e32 v171, v171
	v_add_f32_e32 v27, v27, v169
	ds_read_b128 v[218:221], v2
	ds_read_b128 v[214:217], v2 offset:512
	ds_read_b128 v[210:213], v2 offset:2048
	v_mfma_f32_32x32x16_bf16 v[50:65], v[142:145], v[240:243], v[50:65]
	v_exp_f32_e32 v172, v172
	v_add_f32_e32 v27, v27, v170
	v_exp_f32_e32 v173, v173
	v_add_f32_e32 v27, v27, v171
	v_add_f32_e32 v27, v27, v172
	v_add_f32_e32 v27, v27, v173
	v_cvt_pk_bf16_f32 v166, v166, v167
	v_cvt_pk_bf16_f32 v167, v168, v169
	v_cvt_pk_bf16_f32 v168, v170, v171
	v_cvt_pk_bf16_f32 v169, v172, v173
	v_add_f32_e32 v236, v236, v27
	ds_read_b128 v[206:209], v2 offset:2560
	ds_read_b128 v[202:205], v2 offset:4096
	ds_read_b128 v[198:201], v2 offset:4608
	v_mfma_f32_32x32x16_bf16 v[34:49], v[150:153], v[118:121], v[34:49]
	ds_read_b128 v[194:197], v2 offset:6144
	ds_read_b128 v[190:193], v2 offset:6656
	ds_read_b128 v[186:189], v2 offset:8192
	v_max3_f32 v19, v82, v83, v84
	v_max3_f32 v26, v85, v86, v87
	v_max3_f32 v19, v19, v88, v89
	v_max3_f32 v26, v26, v90, v91
	v_max3_f32 v19, v19, v92, v93
	v_mfma_f32_32x32x16_bf16 v[50:65], v[150:153], v[244:247], v[50:65]
	ds_read_b128 v[182:185], v2 offset:8704
	ds_read_b128 v[178:181], v2 offset:10240
	ds_read_b128 v[174:177], v2 offset:10752
	v_max3_f32 v26, v26, v94, v95
	v_max3_f32 v19, v19, v96, v97
	v_max3_f32 v26, v26, v98, v99
	v_max3_f32 v19, v19, v100, v101
	v_max3_f32 v26, v26, v102, v103
	v_mfma_f32_32x32x16_bf16 v[34:49], v[158:161], v[122:125], v[34:49]
	v_max3_f32 v19, v19, v104, v105
	v_max3_f32 v26, v26, v106, v107
	v_max3_f32 v19, v19, v108, v109
	v_max3_f32 v26, v26, v110, v111
	v_mfma_f32_32x32x16_bf16 v[50:65], v[158:161], v[248:251], v[50:65]
	v_max3_f32 v19, v19, v112, v113
	v_max_f32_e32 v19, v19, v26
	v_mfma_f32_32x32x16_bf16 v[34:49], v[166:169], v[126:129], v[34:49]
	v_mfma_f32_32x32x16_bf16 v[50:65], v[166:169], v[20:23], v[50:65]
	v_cmp_lt_f32_e32 vcc, s41, v19
	s_cbranch_vccz .Lmy_nors_26
	s_nop 15
	s_nop 15
	v_mov_b32_e32 v26, v19
	s_nop 1
	v_permlane32_swap_b32_e32 v19, v26
	v_max_f32_e32 v19, v19, v26
	v_max_f32_e32 v19, v19, v19
	v_max_f32_e32 v150, 0, v19
	v_exp_f32_e64 v151, -v150
	v_add_f32_e32 v239, v239, v150
	v_xor_b32_e32 v66, 0x80000000, v239
	v_mov_b32_e32 v67, v66
	v_mov_b32_e32 v68, v66
	v_mov_b32_e32 v69, v66
	v_mov_b32_e32 v70, v66
	v_mov_b32_e32 v71, v66
	v_mov_b32_e32 v72, v66
	v_mov_b32_e32 v73, v66
	v_mov_b32_e32 v74, v66
	v_mov_b32_e32 v75, v66
	v_mov_b32_e32 v76, v66
	v_mov_b32_e32 v77, v66
	v_mov_b32_e32 v78, v66
	v_mov_b32_e32 v79, v66
	v_mov_b32_e32 v80, v66
	v_mov_b32_e32 v81, v66
	v_sub_f32_e32 v82, v82, v150
	v_sub_f32_e32 v83, v83, v150
	v_sub_f32_e32 v84, v84, v150
	v_sub_f32_e32 v85, v85, v150
	v_sub_f32_e32 v86, v86, v150
	v_sub_f32_e32 v87, v87, v150
	v_sub_f32_e32 v88, v88, v150
	v_sub_f32_e32 v89, v89, v150
	v_sub_f32_e32 v90, v90, v150
	v_sub_f32_e32 v91, v91, v150
	v_sub_f32_e32 v92, v92, v150
	v_sub_f32_e32 v93, v93, v150
	v_sub_f32_e32 v94, v94, v150
	v_sub_f32_e32 v95, v95, v150
	v_sub_f32_e32 v96, v96, v150
	v_sub_f32_e32 v97, v97, v150
	v_sub_f32_e32 v98, v98, v150
	v_sub_f32_e32 v99, v99, v150
	v_sub_f32_e32 v100, v100, v150
	v_sub_f32_e32 v101, v101, v150
	v_sub_f32_e32 v102, v102, v150
	v_sub_f32_e32 v103, v103, v150
	v_sub_f32_e32 v104, v104, v150
	v_sub_f32_e32 v105, v105, v150
	v_sub_f32_e32 v106, v106, v150
	v_sub_f32_e32 v107, v107, v150
	v_sub_f32_e32 v108, v108, v150
	v_sub_f32_e32 v109, v109, v150
	v_sub_f32_e32 v110, v110, v150
	v_sub_f32_e32 v111, v111, v150
	v_sub_f32_e32 v112, v112, v150
	v_sub_f32_e32 v113, v113, v150
	v_mul_f32_e32 v236, v236, v151
	s_mov_b64 s[96:97], exec
	s_and_b64 exec, exec, s[8:9]
	ds_write_b32 v235, v151
	s_mov_b64 exec, s[96:97]
	v_lshl_add_u32 v2, v228, 4, s47
	ds_read_b128 v[154:157], v2 offset:0
	s_waitcnt lgkmcnt(0)
	v_mul_f32_e32 v34, v34, v154
	v_mul_f32_e32 v50, v50, v154
	v_mul_f32_e32 v35, v35, v155
	v_mul_f32_e32 v51, v51, v155
	v_mul_f32_e32 v36, v36, v156
	v_mul_f32_e32 v52, v52, v156
	v_mul_f32_e32 v37, v37, v157
	v_mul_f32_e32 v53, v53, v157
	ds_read_b128 v[154:157], v2 offset:32
	s_waitcnt lgkmcnt(0)
	v_mul_f32_e32 v38, v38, v154
	v_mul_f32_e32 v54, v54, v154
	v_mul_f32_e32 v39, v39, v155
	v_mul_f32_e32 v55, v55, v155
	v_mul_f32_e32 v40, v40, v156
	v_mul_f32_e32 v56, v56, v156
	v_mul_f32_e32 v41, v41, v157
	v_mul_f32_e32 v57, v57, v157
	ds_read_b128 v[154:157], v2 offset:64
	s_waitcnt lgkmcnt(0)
	v_mul_f32_e32 v42, v42, v154
	v_mul_f32_e32 v58, v58, v154
	v_mul_f32_e32 v43, v43, v155
	v_mul_f32_e32 v59, v59, v155
	v_mul_f32_e32 v44, v44, v156
	v_mul_f32_e32 v60, v60, v156
	v_mul_f32_e32 v45, v45, v157
	v_mul_f32_e32 v61, v61, v157
	ds_read_b128 v[154:157], v2 offset:96
	s_waitcnt lgkmcnt(0)
	v_mul_f32_e32 v46, v46, v154
	v_mul_f32_e32 v62, v62, v154
	v_mul_f32_e32 v47, v47, v155
	v_mul_f32_e32 v63, v63, v155
	v_mul_f32_e32 v48, v48, v156
	v_mul_f32_e32 v64, v64, v156
	v_mul_f32_e32 v49, v49, v157
	v_mul_f32_e32 v65, v65, v157

.Lmy_B_tail:
	s_cmp_gt_u32 s71, 0
	s_cbranch_scc1 .Lmy_tf_27
	s_cmp_eq_u32 s71, 0
	s_cbranch_scc1 .Lmy_ts_28
	s_waitcnt lgkmcnt(0)
	s_waitcnt vmcnt(2)
	s_barrier
	s_add_u32 m0, s57, 0x6000
	s_nop 0
	global_load_lds_dwordx4 v[28:29], off
	v_lshl_add_u64 v[28:29], v[28:29], 0, s[30:31]
	s_branch .Lmy_te_29
.Lmy_ts_28:
	s_waitcnt lgkmcnt(0)
	v_mov_b32_e32 v2, v237
	ds_read_b64_tr_b16 v[114:115], v2 offset:49152
	ds_read_b64_tr_b16 v[116:117], v2 offset:49664
	ds_read_b64_tr_b16 v[118:119], v2 offset:50176
	ds_read_b64_tr_b16 v[120:121], v2 offset:50688
	ds_read_b64_tr_b16 v[122:123], v2 offset:51200
	ds_read_b64_tr_b16 v[124:125], v2 offset:51712
	ds_read_b64_tr_b16 v[126:127], v2 offset:52224
	ds_read_b64_tr_b16 v[128:129], v2 offset:52736
	ds_read_b64_tr_b16 v[240:241], v2 offset:53248
	ds_read_b64_tr_b16 v[242:243], v2 offset:53760
	ds_read_b64_tr_b16 v[244:245], v2 offset:54272
	ds_read_b64_tr_b16 v[246:247], v2 offset:54784
	ds_read_b64_tr_b16 v[248:249], v2 offset:55296
	ds_read_b64_tr_b16 v[250:251], v2 offset:55808
	ds_read_b64_tr_b16 v[20:21], v2 offset:56320
	ds_read_b64_tr_b16 v[22:23], v2 offset:56832
	v_exp_f32_e32 v82, v82
	v_exp_f32_e32 v83, v83
	v_exp_f32_e32 v84, v84
	v_add_f32_e32 v27, v82, v83
	v_exp_f32_e32 v85, v85
	v_exp_f32_e32 v86, v86
	v_add_f32_e32 v27, v27, v84
	v_exp_f32_e32 v87, v87
	v_add_f32_e32 v27, v27, v85
	v_exp_f32_e32 v88, v88
	v_add_f32_e32 v27, v27, v86
	v_exp_f32_e32 v89, v89
	v_add_f32_e32 v27, v27, v87
	v_add_f32_e32 v27, v27, v88
	v_add_f32_e32 v27, v27, v89
	v_cvt_pk_bf16_f32 v82, v82, v83
	v_cvt_pk_bf16_f32 v83, v84, v85
	v_cvt_pk_bf16_f32 v84, v86, v87
	v_cvt_pk_bf16_f32 v85, v88, v89
	v_exp_f32_e32 v90, v90
	v_exp_f32_e32 v91, v91
	v_exp_f32_e32 v92, v92
	v_add_f32_e32 v27, v27, v90
	v_exp_f32_e32 v93, v93
	v_add_f32_e32 v27, v27, v91
	v_exp_f32_e32 v94, v94
	v_add_f32_e32 v27, v27, v92
	v_exp_f32_e32 v95, v95
	v_add_f32_e32 v27, v27, v93
	v_exp_f32_e32 v96, v96
	v_add_f32_e32 v27, v27, v94
	v_exp_f32_e32 v97, v97
	v_add_f32_e32 v27, v27, v95
	v_add_f32_e32 v27, v27, v96
	v_add_f32_e32 v27, v27, v97
	v_cvt_pk_bf16_f32 v90, v90, v91
	v_cvt_pk_bf16_f32 v91, v92, v93
	v_cvt_pk_bf16_f32 v92, v94, v95
	v_cvt_pk_bf16_f32 v93, v96, v97
	s_waitcnt vmcnt(2)
	s_barrier
	s_add_u32 m0, s57, 0x6000
	s_nop 0
	global_load_lds_dwordx4 v[28:29], off
	v_lshl_add_u64 v[28:29], v[28:29], 0, s[30:31]
	s_waitcnt lgkmcnt(0)
	v_mfma_f32_32x32x16_bf16 v[34:49], v[82:85], v[114:117], v[34:49]
	v_mfma_f32_32x32x16_bf16 v[50:65], v[82:85], v[240:243], v[50:65]
	v_exp_f32_e32 v98, v98
	v_exp_f32_e32 v99, v99
	v_exp_f32_e32 v100, v100
	v_add_f32_e32 v27, v27, v98
	v_exp_f32_e32 v101, v101
	v_add_f32_e32 v27, v27, v99
	v_exp_f32_e32 v102, v102
	v_add_f32_e32 v27, v27, v100
	v_exp_f32_e32 v103, v103
	v_add_f32_e32 v27, v27, v101
	v_exp_f32_e32 v104, v104
	v_add_f32_e32 v27, v27, v102
	v_exp_f32_e32 v105, v105
	v_add_f32_e32 v27, v27, v103
	v_add_f32_e32 v27, v27, v104
	v_add_f32_e32 v27, v27, v105
	v_cvt_pk_bf16_f32 v98, v98, v99
	v_cvt_pk_bf16_f32 v99, v100, v101
	v_cvt_pk_bf16_f32 v100, v102, v103
	v_cvt_pk_bf16_f32 v101, v104, v105
	v_mfma_f32_32x32x16_bf16 v[34:49], v[90:93], v[118:121], v[34:49]
	v_mfma_f32_32x32x16_bf16 v[50:65], v[90:93], v[244:247], v[50:65]
	v_exp_f32_e32 v106, v106
	v_exp_f32_e32 v107, v107
	v_exp_f32_e32 v108, v108
	v_add_f32_e32 v27, v27, v106
	v_exp_f32_e32 v109, v109
	v_add_f32_e32 v27, v27, v107
	v_exp_f32_e32 v110, v110
	v_add_f32_e32 v27, v27, v108
	v_exp_f32_e32 v111, v111
	v_add_f32_e32 v27, v27, v109
	v_exp_f32_e32 v112, v112
	v_add_f32_e32 v27, v27, v110
	v_exp_f32_e32 v113, v113
	v_add_f32_e32 v27, v27, v111
	v_add_f32_e32 v27, v27, v112
	v_add_f32_e32 v27, v27, v113
	v_cvt_pk_bf16_f32 v106, v106, v107
	v_cvt_pk_bf16_f32 v107, v108, v109
	v_cvt_pk_bf16_f32 v108, v110, v111
	v_cvt_pk_bf16_f32 v109, v112, v113
	v_add_f32_e32 v236, v236, v27
	s_nop 1
	v_mfma_f32_32x32x16_bf16 v[34:49], v[98:101], v[122:125], v[34:49]
	v_mfma_f32_32x32x16_bf16 v[50:65], v[98:101], v[248:251], v[50:65]
	v_mfma_f32_32x32x16_bf16 v[34:49], v[106:109], v[126:129], v[34:49]
	v_mfma_f32_32x32x16_bf16 v[50:65], v[106:109], v[20:23], v[50:65]
	s_branch .Lmy_te_29
.Lmy_tf_27:
	s_waitcnt lgkmcnt(0)
	v_mov_b32_e32 v2, v237
	v_mfma_f32_32x32x16_bf16 v[142:157], v[218:221], v[4:7], v[66:81]
	v_exp_f32_e32 v82, v82
	v_exp_f32_e32 v83, v83
	v_exp_f32_e32 v84, v84
	v_add_f32_e32 v27, v82, v83
	v_exp_f32_e32 v85, v85
	ds_read_b64_tr_b16 v[114:115], v2 offset:49152
	ds_read_b64_tr_b16 v[116:117], v2 offset:49664
	ds_read_b64_tr_b16 v[118:119], v2 offset:50176
	ds_read_b64_tr_b16 v[120:121], v2 offset:50688
	v_mfma_f32_32x32x16_bf16 v[158:173], v[214:217], v[4:7], v[66:81]
	v_exp_f32_e32 v86, v86
	v_add_f32_e32 v27, v27, v84
	v_exp_f32_e32 v87, v87
	v_add_f32_e32 v27, v27, v85
	v_exp_f32_e32 v88, v88
	ds_read_b64_tr_b16 v[122:123], v2 offset:51200
	ds_read_b64_tr_b16 v[124:125], v2 offset:51712
	ds_read_b64_tr_b16 v[126:127], v2 offset:52224
	ds_read_b64_tr_b16 v[128:129], v2 offset:52736
	v_mfma_f32_32x32x16_bf16 v[142:157], v[210:213], v[8:11], v[142:157]
	v_add_f32_e32 v27, v27, v86
	v_exp_f32_e32 v89, v89
	v_add_f32_e32 v27, v27, v87
	v_add_f32_e32 v27, v27, v88
	v_add_f32_e32 v27, v27, v89
	ds_read_b64_tr_b16 v[240:241], v2 offset:53248
	ds_read_b64_tr_b16 v[242:243], v2 offset:53760
	ds_read_b64_tr_b16 v[244:245], v2 offset:54272
	ds_read_b64_tr_b16 v[246:247], v2 offset:54784
	v_mfma_f32_32x32x16_bf16 v[158:173], v[206:209], v[8:11], v[158:173]
	v_cvt_pk_bf16_f32 v82, v82, v83
	v_cvt_pk_bf16_f32 v83, v84, v85
	v_cvt_pk_bf16_f32 v84, v86, v87
	v_cvt_pk_bf16_f32 v85, v88, v89
	ds_read_b64_tr_b16 v[248:249], v2 offset:55296
	ds_read_b64_tr_b16 v[250:251], v2 offset:55808
	ds_read_b64_tr_b16 v[20:21], v2 offset:56320
	ds_read_b64_tr_b16 v[22:23], v2 offset:56832
	v_mfma_f32_32x32x16_bf16 v[142:157], v[202:205], v[12:15], v[142:157]
	v_exp_f32_e32 v90, v90
	v_exp_f32_e32 v91, v91
	v_exp_f32_e32 v92, v92
	v_add_f32_e32 v27, v27, v90
	v_exp_f32_e32 v93, v93
	v_mfma_f32_32x32x16_bf16 v[158:173], v[198:201], v[12:15], v[158:173]
	v_add_f32_e32 v27, v27, v91
	v_exp_f32_e32 v94, v94
	v_add_f32_e32 v27, v27, v92
	v_exp_f32_e32 v95, v95
	v_add_f32_e32 v27, v27, v93
	s_waitcnt vmcnt(2)
	s_barrier
	v_mfma_f32_32x32x16_bf16 v[142:157], v[194:197], v[130:133], v[142:157]
	s_add_u32 m0, s57, 0x6000
	v_exp_f32_e32 v96, v96
	v_add_f32_e32 v27, v27, v94
	global_load_lds_dwordx4 v[28:29], off
	v_lshl_add_u64 v[28:29], v[28:29], 0, s[30:31]
	v_exp_f32_e32 v97, v97
	v_add_f32_e32 v27, v27, v95
	v_add_f32_e32 v27, v27, v96
	v_mfma_f32_32x32x16_bf16 v[158:173], v[190:193], v[130:133], v[158:173]
	v_add_f32_e32 v27, v27, v97
	v_cvt_pk_bf16_f32 v90, v90, v91
	v_cvt_pk_bf16_f32 v91, v92, v93
	v_cvt_pk_bf16_f32 v92, v94, v95
	v_cvt_pk_bf16_f32 v93, v96, v97
	v_mfma_f32_32x32x16_bf16 v[142:157], v[186:189], v[134:137], v[142:157]
	v_exp_f32_e32 v98, v98
	v_exp_f32_e32 v99, v99
	v_exp_f32_e32 v100, v100
	v_add_f32_e32 v27, v27, v98
	v_exp_f32_e32 v101, v101
	v_mfma_f32_32x32x16_bf16 v[158:173], v[182:185], v[134:137], v[158:173]
	v_add_f32_e32 v27, v27, v99
	v_exp_f32_e32 v102, v102
	v_add_f32_e32 v27, v27, v100
	v_exp_f32_e32 v103, v103
	v_add_f32_e32 v27, v27, v101
	v_mfma_f32_32x32x16_bf16 v[142:157], v[178:181], v[138:141], v[142:157]
	v_exp_f32_e32 v104, v104
	v_add_f32_e32 v27, v27, v102
	v_exp_f32_e32 v105, v105
	v_add_f32_e32 v27, v27, v103
	v_add_f32_e32 v27, v27, v104
	v_mfma_f32_32x32x16_bf16 v[158:173], v[174:177], v[138:141], v[158:173]
	v_add_f32_e32 v27, v27, v105
	v_cvt_pk_bf16_f32 v98, v98, v99
	v_cvt_pk_bf16_f32 v99, v100, v101
	v_cvt_pk_bf16_f32 v100, v102, v103
	v_cvt_pk_bf16_f32 v101, v104, v105
	s_waitcnt lgkmcnt(0)
	v_add_u32_e32 v2, 0x6000, v238
	v_mfma_f32_32x32x16_bf16 v[34:49], v[82:85], v[114:117], v[34:49]
	v_exp_f32_e32 v106, v106
	v_exp_f32_e32 v107, v107
	v_exp_f32_e32 v108, v108
	v_add_f32_e32 v27, v27, v106
	v_exp_f32_e32 v109, v109
	v_add_f32_e32 v27, v27, v107
	v_exp_f32_e32 v110, v110
	v_add_f32_e32 v27, v27, v108
	v_exp_f32_e32 v111, v111
	v_add_f32_e32 v27, v27, v109
	s_cmp_gt_u32 s71, 1
	s_cbranch_scc0 .Lmy_nok_30
	ds_read_b128 v[218:221], v2
	ds_read_b128 v[214:217], v2 offset:512
	ds_read_b128 v[210:213], v2 offset:2048
	ds_read_b128 v[206:209], v2 offset:2560
	ds_read_b128 v[202:205], v2 offset:4096
	ds_read_b128 v[198:201], v2 offset:4608
	ds_read_b128 v[194:197], v2 offset:6144
	ds_read_b128 v[190:193], v2 offset:6656
	ds_read_b128 v[186:189], v2 offset:8192
	ds_read_b128 v[182:185], v2 offset:8704
	ds_read_b128 v[178:181], v2 offset:10240
	ds_read_b128 v[174:177], v2 offset:10752
